# early barrier k=8 tail prio 2 + int8 nop trims
# baseline (speedup 1.0000x reference)
.LBB0_308:
	ds_read_b128 v[142:145], v191
	ds_read_b128 v[138:141], v191 offset:1024
	ds_read_b128 v[134:137], v191 offset:2048
	ds_read_b128 v[130:133], v191 offset:3072
	s_add_u32 s46, s44, 0xfff80080
	s_addc_u32 s47, s45, -1
	s_cmp_eq_u32 s37, 28
	s_cselect_b32 s49, s0, s47
	s_cselect_b32 s48, s1, s46
	s_cselect_b32 s47, s7, s31
	s_cselect_b32 s46, s14, s15
	v_lshl_add_u64 v[166:167], s[44:45], 0, v[162:163]
	s_add_i32 m0, s9, 0xc000
	ds_read_b128 v[170:173], v192
	ds_read_b128 v[174:177], v192 offset:1024
	s_waitcnt lgkmcnt(0)
	ds_read_b128 v[178:181], v192 offset:2048
	ds_read_b128 v[182:185], v192 offset:3072
	ds_read_b128 v[204:207], v192 offset:4096
	ds_read_b128 v[208:211], v192 offset:5120
	ds_read_b128 v[212:215], v192 offset:6144
	ds_read_b128 v[216:219], v192 offset:7168
	global_load_lds_dwordx4 v[166:167], off
	v_lshl_add_u64 v[166:167], s[44:45], 0, v[164:165]
	s_add_i32 m0, s9, 0xe000
	s_nop 0
	global_load_lds_dwordx4 v[166:167], off
	s_waitcnt lgkmcnt(8)
	s_barrier
	s_waitcnt lgkmcnt(0)
	s_setprio 1
	s_waitcnt lgkmcnt(0)
	v_mfma_i32_16x16x64_i8 v[126:129], v[142:145], v[170:173], v[126:129]
	v_mfma_i32_16x16x64_i8 v[126:129], v[138:141], v[174:177], v[126:129]
	v_mfma_i32_16x16x64_i8 v[122:125], v[134:137], v[170:173], v[122:125]
	v_mfma_i32_16x16x64_i8 v[122:125], v[130:133], v[174:177], v[122:125]
	v_mfma_i32_16x16x64_i8 v[110:113], v[142:145], v[178:181], v[110:113]
	v_mfma_i32_16x16x64_i8 v[110:113], v[138:141], v[182:185], v[110:113]
	v_mfma_i32_16x16x64_i8 v[106:109], v[134:137], v[178:181], v[106:109]
	v_mfma_i32_16x16x64_i8 v[106:109], v[130:133], v[182:185], v[106:109]
	s_barrier
	s_setprio 2
	v_mfma_i32_16x16x64_i8 v[94:97], v[142:145], v[204:207], v[94:97]
	v_mfma_i32_16x16x64_i8 v[94:97], v[138:141], v[208:211], v[94:97]
	v_mfma_i32_16x16x64_i8 v[90:93], v[134:137], v[204:207], v[90:93]
	v_mfma_i32_16x16x64_i8 v[90:93], v[130:133], v[208:211], v[90:93]
	v_mfma_i32_16x16x64_i8 v[78:81], v[142:145], v[212:215], v[78:81]
	v_mfma_i32_16x16x64_i8 v[78:81], v[138:141], v[216:219], v[78:81]
	v_mfma_i32_16x16x64_i8 v[74:77], v[134:137], v[212:215], v[74:77]
	v_mfma_i32_16x16x64_i8 v[74:77], v[130:133], v[216:219], v[74:77]
	s_setprio 0
	s_add_i32 s50, s55, s8
	v_lshl_add_u64 v[166:167], s[46:47], 0, v[148:149]
	s_mov_b32 m0, s50
	ds_read_b128 v[220:223], v193
	ds_read_b128 v[224:227], v193 offset:1024
	ds_read_b128 v[234:237], v193 offset:2048
	ds_read_b128 v[238:241], v193 offset:3072
	global_load_lds_dwordx4 v[166:167], off
	v_lshl_add_u64 v[168:169], s[46:47], 0, v[152:153]
	s_add_i32 m0, s50, 0x2000
	s_nop 0
	global_load_lds_dwordx4 v[168:169], off
	s_barrier
	s_waitcnt lgkmcnt(0)
	s_setprio 1
	s_waitcnt lgkmcnt(0)
	v_mfma_i32_16x16x64_i8 v[118:121], v[220:223], v[170:173], v[118:121]
	v_mfma_i32_16x16x64_i8 v[118:121], v[224:227], v[174:177], v[118:121]
	v_mfma_i32_16x16x64_i8 v[114:117], v[234:237], v[170:173], v[114:117]
	v_mfma_i32_16x16x64_i8 v[114:117], v[238:241], v[174:177], v[114:117]
	v_mfma_i32_16x16x64_i8 v[102:105], v[220:223], v[178:181], v[102:105]
	v_mfma_i32_16x16x64_i8 v[102:105], v[224:227], v[182:185], v[102:105]
	v_mfma_i32_16x16x64_i8 v[98:101], v[234:237], v[178:181], v[98:101]
	v_mfma_i32_16x16x64_i8 v[98:101], v[238:241], v[182:185], v[98:101]
	s_barrier
	s_setprio 2
	v_mfma_i32_16x16x64_i8 v[86:89], v[220:223], v[204:207], v[86:89]
	v_mfma_i32_16x16x64_i8 v[86:89], v[224:227], v[208:211], v[86:89]
	v_mfma_i32_16x16x64_i8 v[82:85], v[234:237], v[204:207], v[82:85]
	v_mfma_i32_16x16x64_i8 v[82:85], v[238:241], v[208:211], v[82:85]
	v_mfma_i32_16x16x64_i8 v[70:73], v[220:223], v[212:215], v[70:73]
	v_mfma_i32_16x16x64_i8 v[70:73], v[224:227], v[216:219], v[70:73]
	v_mfma_i32_16x16x64_i8 v[66:69], v[234:237], v[212:215], v[66:69]
	v_mfma_i32_16x16x64_i8 v[66:69], v[238:241], v[216:219], v[66:69]
	s_setprio 0
	s_mov_b32 m0, s9
	v_lshl_add_u64 v[170:171], s[48:49], 0, v[146:147]
	ds_read_b128 v[174:177], v192 offset:16384
	ds_read_b128 v[178:181], v192 offset:17408
	ds_read_b128 v[182:185], v192 offset:18432
	ds_read_b128 v[204:207], v192 offset:19456
	ds_read_b128 v[208:211], v192 offset:20480
	ds_read_b128 v[212:215], v192 offset:21504
	ds_read_b128 v[216:219], v192 offset:22528
	ds_read_b128 v[242:245], v192 offset:23552
	global_load_lds_dwordx4 v[170:171], off
	v_lshl_add_u64 v[172:173], s[48:49], 0, v[150:151]
	s_mov_b32 m0, s13
	s_nop 0
	global_load_lds_dwordx4 v[172:173], off
	s_barrier
	s_waitcnt lgkmcnt(0)
	s_setprio 1
	s_waitcnt lgkmcnt(0)
	v_mfma_i32_16x16x64_i8 v[62:65], v[142:145], v[174:177], v[62:65]
	v_mfma_i32_16x16x64_i8 v[62:65], v[138:141], v[178:181], v[62:65]
	v_mfma_i32_16x16x64_i8 v[58:61], v[134:137], v[174:177], v[58:61]
	v_mfma_i32_16x16x64_i8 v[58:61], v[130:133], v[178:181], v[58:61]
	v_mfma_i32_16x16x64_i8 v[46:49], v[142:145], v[182:185], v[46:49]
	v_mfma_i32_16x16x64_i8 v[46:49], v[138:141], v[204:207], v[46:49]
	v_mfma_i32_16x16x64_i8 v[42:45], v[134:137], v[182:185], v[42:45]
	v_mfma_i32_16x16x64_i8 v[42:45], v[130:133], v[204:207], v[42:45]
	s_barrier
	s_setprio 2
	v_mfma_i32_16x16x64_i8 v[30:33], v[142:145], v[208:211], v[30:33]
	v_mfma_i32_16x16x64_i8 v[30:33], v[138:141], v[212:215], v[30:33]
	v_mfma_i32_16x16x64_i8 v[26:29], v[134:137], v[208:211], v[26:29]
	v_mfma_i32_16x16x64_i8 v[26:29], v[130:133], v[212:215], v[26:29]
	v_mfma_i32_16x16x64_i8 v[14:17], v[142:145], v[216:219], v[14:17]
	v_mfma_i32_16x16x64_i8 v[14:17], v[138:141], v[242:245], v[14:17]
	v_mfma_i32_16x16x64_i8 v[10:13], v[134:137], v[216:219], v[10:13]
	v_mfma_i32_16x16x64_i8 v[10:13], v[130:133], v[242:245], v[10:13]
	s_setprio 0
	s_add_u32 s50, s46, 0x80000
	s_addc_u32 s51, s47, 0
	s_add_i32 s59, s56, s8
	v_lshl_add_u64 v[130:131], s[50:51], 0, v[148:149]
	s_mov_b32 m0, s59
	s_nop 0
	global_load_lds_dwordx4 v[130:131], off
	v_lshl_add_u64 v[130:131], s[50:51], 0, v[152:153]
	s_add_i32 m0, s59, 0x2000
	s_nop 0
	global_load_lds_dwordx4 v[130:131], off
	s_waitcnt vmcnt(6)
	s_barrier
	s_setprio 1
	v_mfma_i32_16x16x64_i8 v[54:57], v[220:223], v[174:177], v[54:57]
	v_mfma_i32_16x16x64_i8 v[54:57], v[224:227], v[178:181], v[54:57]
	v_mfma_i32_16x16x64_i8 v[50:53], v[234:237], v[174:177], v[50:53]
	v_mfma_i32_16x16x64_i8 v[50:53], v[238:241], v[178:181], v[50:53]
	v_mfma_i32_16x16x64_i8 v[38:41], v[220:223], v[182:185], v[38:41]
	v_mfma_i32_16x16x64_i8 v[38:41], v[224:227], v[204:207], v[38:41]
	v_mfma_i32_16x16x64_i8 v[34:37], v[234:237], v[182:185], v[34:37]
	v_mfma_i32_16x16x64_i8 v[34:37], v[238:241], v[204:207], v[34:37]
	s_barrier
	s_setprio 2
	v_mfma_i32_16x16x64_i8 v[22:25], v[220:223], v[208:211], v[22:25]
	v_mfma_i32_16x16x64_i8 v[22:25], v[224:227], v[212:215], v[22:25]
	v_mfma_i32_16x16x64_i8 v[18:21], v[234:237], v[208:211], v[18:21]
	v_mfma_i32_16x16x64_i8 v[18:21], v[238:241], v[212:215], v[18:21]
	v_mfma_i32_16x16x64_i8 v[6:9], v[220:223], v[216:219], v[6:9]
	v_mfma_i32_16x16x64_i8 v[6:9], v[224:227], v[242:245], v[6:9]
	v_mfma_i32_16x16x64_i8 v[2:5], v[234:237], v[216:219], v[2:5]
	v_mfma_i32_16x16x64_i8 v[2:5], v[238:241], v[242:245], v[2:5]
	s_setprio 0
	s_add_i32 s50, 0, 0x18000
	v_add_u32_e32 v142, s50, v188
	ds_read_b128 v[130:133], v142
	ds_read_b128 v[134:137], v142 offset:1024
	ds_read_b128 v[138:141], v142 offset:2048
	ds_read_b128 v[142:145], v142 offset:3072
	s_add_u32 s48, s48, 0x80000
	s_addc_u32 s49, s49, 0
	s_mov_b32 m0, s29
	v_lshl_add_u64 v[186:187], s[48:49], 0, v[146:147]
	ds_read_b128 v[174:177], v192 offset:32768
	ds_read_b128 v[178:181], v192 offset:33792
	ds_read_b128 v[182:185], v192 offset:34816
	ds_read_b128 v[204:207], v192 offset:35840
	ds_read_b128 v[208:211], v192 offset:36864
	ds_read_b128 v[212:215], v192 offset:37888
	ds_read_b128 v[216:219], v192 offset:38912
	ds_read_b128 v[220:223], v192 offset:39936
	global_load_lds_dwordx4 v[186:187], off
	v_lshl_add_u64 v[186:187], s[48:49], 0, v[150:151]
	s_mov_b32 m0, s33
	s_nop 0
	global_load_lds_dwordx4 v[186:187], off
	s_waitcnt lgkmcnt(8)
	s_barrier
	s_waitcnt lgkmcnt(0)
	s_setprio 1
	s_waitcnt lgkmcnt(0)
	v_mfma_i32_16x16x64_i8 v[126:129], v[130:133], v[174:177], v[126:129]
	v_mfma_i32_16x16x64_i8 v[126:129], v[134:137], v[178:181], v[126:129]
	v_mfma_i32_16x16x64_i8 v[122:125], v[138:141], v[174:177], v[122:125]
	v_mfma_i32_16x16x64_i8 v[122:125], v[142:145], v[178:181], v[122:125]
	v_mfma_i32_16x16x64_i8 v[110:113], v[130:133], v[182:185], v[110:113]
	v_mfma_i32_16x16x64_i8 v[110:113], v[134:137], v[204:207], v[110:113]
	v_mfma_i32_16x16x64_i8 v[106:109], v[138:141], v[182:185], v[106:109]
	v_mfma_i32_16x16x64_i8 v[106:109], v[142:145], v[204:207], v[106:109]
	s_barrier
	s_setprio 2
	v_mfma_i32_16x16x64_i8 v[94:97], v[130:133], v[208:211], v[94:97]
	v_mfma_i32_16x16x64_i8 v[94:97], v[134:137], v[212:215], v[94:97]
	v_mfma_i32_16x16x64_i8 v[90:93], v[138:141], v[208:211], v[90:93]
	v_mfma_i32_16x16x64_i8 v[90:93], v[142:145], v[212:215], v[90:93]
	v_mfma_i32_16x16x64_i8 v[78:81], v[130:133], v[216:219], v[78:81]
	v_mfma_i32_16x16x64_i8 v[78:81], v[134:137], v[220:223], v[78:81]
	v_mfma_i32_16x16x64_i8 v[74:77], v[138:141], v[216:219], v[74:77]
	v_mfma_i32_16x16x64_i8 v[74:77], v[142:145], v[220:223], v[74:77]
	s_setprio 0
	s_add_i32 s48, 0, 0x1c000
	s_add_i32 s49, s50, s8
	v_add_u32_e32 v156, s48, v188
	v_lshl_add_u64 v[166:167], v[166:167], 0, s[22:23]
	s_mov_b32 m0, s49
	ds_read_b128 v[224:227], v156
	ds_read_b128 v[234:237], v156 offset:1024
	ds_read_b128 v[238:241], v156 offset:2048
	ds_read_b128 v[242:245], v156 offset:3072
	global_load_lds_dwordx4 v[166:167], off
	v_lshl_add_u64 v[166:167], v[168:169], 0, s[22:23]
	s_add_i32 m0, s49, 0x2000
	s_nop 0
	global_load_lds_dwordx4 v[166:167], off
	s_barrier
	s_waitcnt lgkmcnt(0)
	s_setprio 1
	s_waitcnt lgkmcnt(0)
	v_mfma_i32_16x16x64_i8 v[118:121], v[224:227], v[174:177], v[118:121]
	v_mfma_i32_16x16x64_i8 v[118:121], v[234:237], v[178:181], v[118:121]
	v_mfma_i32_16x16x64_i8 v[114:117], v[238:241], v[174:177], v[114:117]
	v_mfma_i32_16x16x64_i8 v[114:117], v[242:245], v[178:181], v[114:117]
	v_mfma_i32_16x16x64_i8 v[102:105], v[224:227], v[182:185], v[102:105]
	v_mfma_i32_16x16x64_i8 v[102:105], v[234:237], v[204:207], v[102:105]
	v_mfma_i32_16x16x64_i8 v[98:101], v[238:241], v[182:185], v[98:101]
	v_mfma_i32_16x16x64_i8 v[98:101], v[242:245], v[204:207], v[98:101]
	s_barrier
	s_setprio 2
	v_mfma_i32_16x16x64_i8 v[86:89], v[224:227], v[208:211], v[86:89]
	v_mfma_i32_16x16x64_i8 v[86:89], v[234:237], v[212:215], v[86:89]
	v_mfma_i32_16x16x64_i8 v[82:85], v[238:241], v[208:211], v[82:85]
	v_mfma_i32_16x16x64_i8 v[82:85], v[242:245], v[212:215], v[82:85]
	v_mfma_i32_16x16x64_i8 v[70:73], v[224:227], v[216:219], v[70:73]
	v_mfma_i32_16x16x64_i8 v[70:73], v[234:237], v[220:223], v[70:73]
	v_mfma_i32_16x16x64_i8 v[66:69], v[238:241], v[216:219], v[66:69]
	v_mfma_i32_16x16x64_i8 v[66:69], v[242:245], v[220:223], v[66:69]
	s_setprio 0
	s_mov_b32 m0, s53
	v_lshl_add_u64 v[170:171], v[170:171], 0, s[22:23]
	ds_read_b128 v[166:169], v192 offset:49152
	ds_read_b128 v[174:177], v192 offset:50176
	ds_read_b128 v[178:181], v192 offset:51200
	ds_read_b128 v[182:185], v192 offset:52224
	ds_read_b128 v[204:207], v192 offset:53248
	ds_read_b128 v[208:211], v192 offset:54272
	ds_read_b128 v[212:215], v192 offset:55296
	ds_read_b128 v[216:219], v192 offset:56320
	global_load_lds_dwordx4 v[170:171], off
	v_lshl_add_u64 v[170:171], v[172:173], 0, s[22:23]
	s_mov_b32 m0, s54
	s_nop 0
	global_load_lds_dwordx4 v[170:171], off
	s_barrier
	s_waitcnt lgkmcnt(0)
	s_setprio 1
	s_waitcnt lgkmcnt(0)
	v_mfma_i32_16x16x64_i8 v[62:65], v[130:133], v[166:169], v[62:65]
	v_mfma_i32_16x16x64_i8 v[62:65], v[134:137], v[174:177], v[62:65]
	v_mfma_i32_16x16x64_i8 v[58:61], v[138:141], v[166:169], v[58:61]
	v_mfma_i32_16x16x64_i8 v[58:61], v[142:145], v[174:177], v[58:61]
	v_mfma_i32_16x16x64_i8 v[46:49], v[130:133], v[178:181], v[46:49]
	v_mfma_i32_16x16x64_i8 v[46:49], v[134:137], v[182:185], v[46:49]
	v_mfma_i32_16x16x64_i8 v[42:45], v[138:141], v[178:181], v[42:45]
	v_mfma_i32_16x16x64_i8 v[42:45], v[142:145], v[182:185], v[42:45]
	s_barrier
	s_setprio 2
	v_mfma_i32_16x16x64_i8 v[30:33], v[130:133], v[204:207], v[30:33]
	v_mfma_i32_16x16x64_i8 v[30:33], v[134:137], v[208:211], v[30:33]
	v_mfma_i32_16x16x64_i8 v[26:29], v[138:141], v[204:207], v[26:29]
	v_mfma_i32_16x16x64_i8 v[26:29], v[142:145], v[208:211], v[26:29]
	v_mfma_i32_16x16x64_i8 v[14:17], v[130:133], v[212:215], v[14:17]
	v_mfma_i32_16x16x64_i8 v[14:17], v[134:137], v[216:219], v[14:17]
	v_mfma_i32_16x16x64_i8 v[10:13], v[138:141], v[212:215], v[10:13]
	v_mfma_i32_16x16x64_i8 v[10:13], v[142:145], v[216:219], v[10:13]
	s_setprio 0
	s_add_u32 s46, s46, 0x80080
	s_addc_u32 s47, s47, 0
	s_add_i32 s48, s48, s8
	v_lshl_add_u64 v[130:131], s[46:47], 0, v[148:149]
	s_mov_b32 m0, s48
	s_nop 0
	global_load_lds_dwordx4 v[130:131], off
	v_lshl_add_u64 v[130:131], s[46:47], 0, v[152:153]
	s_add_i32 m0, s48, 0x2000
	s_nop 0
	global_load_lds_dwordx4 v[130:131], off
	s_waitcnt vmcnt(6)
	s_barrier
	s_setprio 1
	v_mfma_i32_16x16x64_i8 v[54:57], v[224:227], v[166:169], v[54:57]
	v_mfma_i32_16x16x64_i8 v[54:57], v[234:237], v[174:177], v[54:57]
	v_mfma_i32_16x16x64_i8 v[50:53], v[238:241], v[166:169], v[50:53]
	v_mfma_i32_16x16x64_i8 v[50:53], v[242:245], v[174:177], v[50:53]
	v_mfma_i32_16x16x64_i8 v[38:41], v[224:227], v[178:181], v[38:41]
	v_mfma_i32_16x16x64_i8 v[38:41], v[234:237], v[182:185], v[38:41]
	v_mfma_i32_16x16x64_i8 v[34:37], v[238:241], v[178:181], v[34:37]
	v_mfma_i32_16x16x64_i8 v[34:37], v[242:245], v[182:185], v[34:37]
	s_barrier
	s_setprio 2
	v_mfma_i32_16x16x64_i8 v[22:25], v[224:227], v[204:207], v[22:25]
	v_mfma_i32_16x16x64_i8 v[22:25], v[234:237], v[208:211], v[22:25]
	v_mfma_i32_16x16x64_i8 v[18:21], v[238:241], v[204:207], v[18:21]
	v_mfma_i32_16x16x64_i8 v[18:21], v[242:245], v[208:211], v[18:21]
	v_mfma_i32_16x16x64_i8 v[6:9], v[224:227], v[212:215], v[6:9]
	v_mfma_i32_16x16x64_i8 v[6:9], v[234:237], v[216:219], v[6:9]
	v_mfma_i32_16x16x64_i8 v[2:5], v[238:241], v[212:215], v[2:5]
	v_mfma_i32_16x16x64_i8 v[2:5], v[242:245], v[216:219], v[2:5]
	s_setprio 0
	s_add_i32 s37, s37, 2
	s_add_u32 s44, s44, 0x100
	s_addc_u32 s45, s45, 0
	s_add_u32 s15, s15, 0x100
	s_addc_u32 s31, s31, 0
	s_cmp_gt_u32 s37, 29
	s_cbranch_scc0 .LBB0_308
	s_nop 15
	s_nop 15
	s_and_b64 vcc, exec, s[24:25]
	s_cbranch_vccz .LBB0_311
	s_barrier

.LBB0_412:
	ds_read_b128 v[130:133], v191
	ds_read_b128 v[134:137], v191 offset:1024
	ds_read_b128 v[138:141], v191 offset:2048
	ds_read_b128 v[142:145], v191 offset:3072
	ds_read_b128 v[146:149], v192
	ds_read_b128 v[150:153], v192 offset:1024
	ds_read_b128 v[174:177], v192 offset:2048
	s_waitcnt lgkmcnt(0)
	ds_read_b128 v[178:181], v192 offset:3072
	s_add_u32 s42, s40, 0xfff00080
	s_addc_u32 s43, s41, -1
	s_cmp_eq_u32 s29, 60
	s_cselect_b32 s45, s0, s43
	s_cselect_b32 s44, s1, s42
	s_cselect_b32 s43, s7, s27
	s_cselect_b32 s42, s14, s15
	v_lshl_add_u64 v[186:187], s[40:41], 0, v[170:171]
	s_add_i32 m0, s9, 0xc000
	ds_read_b128 v[182:185], v193
	ds_read_b128 v[204:207], v193 offset:1024
	ds_read_b128 v[208:211], v193 offset:2048
	ds_read_b128 v[212:215], v193 offset:3072
	ds_read_b128 v[216:219], v193 offset:4096
	ds_read_b128 v[220:223], v193 offset:5120
	ds_read_b128 v[224:227], v193 offset:6144
	ds_read_b128 v[234:237], v193 offset:7168
	global_load_lds_dwordx4 v[186:187], off
	v_lshl_add_u64 v[186:187], s[40:41], 0, v[172:173]
	s_add_i32 m0, s9, 0xe000
	s_nop 0
	global_load_lds_dwordx4 v[186:187], off
	s_waitcnt vmcnt(8)
	s_waitcnt lgkmcnt(0)
	s_barrier
	s_setprio 1
	s_waitcnt lgkmcnt(0)
	v_mfma_f32_16x16x32_bf16 v[126:129], v[130:133], v[182:185], v[126:129]
	v_mfma_f32_16x16x32_bf16 v[122:125], v[138:141], v[182:185], v[122:125]
	v_mfma_f32_16x16x32_bf16 v[118:121], v[130:133], v[208:211], v[118:121]
	v_mfma_f32_16x16x32_bf16 v[110:113], v[138:141], v[208:211], v[110:113]
	v_mfma_f32_16x16x32_bf16 v[102:105], v[130:133], v[216:219], v[102:105]
	v_mfma_f32_16x16x32_bf16 v[94:97], v[138:141], v[216:219], v[94:97]
	v_mfma_f32_16x16x32_bf16 v[86:89], v[130:133], v[224:227], v[86:89]
	v_mfma_f32_16x16x32_bf16 v[78:81], v[138:141], v[224:227], v[78:81]
	v_mfma_f32_16x16x32_bf16 v[126:129], v[134:137], v[204:207], v[126:129]
	v_mfma_f32_16x16x32_bf16 v[122:125], v[142:145], v[204:207], v[122:125]
	v_mfma_f32_16x16x32_bf16 v[118:121], v[134:137], v[212:215], v[118:121]
	v_mfma_f32_16x16x32_bf16 v[110:113], v[142:145], v[212:215], v[110:113]
	v_mfma_f32_16x16x32_bf16 v[102:105], v[134:137], v[220:223], v[102:105]
	v_mfma_f32_16x16x32_bf16 v[94:97], v[142:145], v[220:223], v[94:97]
	v_mfma_f32_16x16x32_bf16 v[86:89], v[134:137], v[234:237], v[86:89]
	v_mfma_f32_16x16x32_bf16 v[78:81], v[142:145], v[234:237], v[78:81]
	v_mfma_f32_16x16x32_bf16 v[114:117], v[146:149], v[182:185], v[114:117]
	v_mfma_f32_16x16x32_bf16 v[106:109], v[174:177], v[182:185], v[106:109]
	v_mfma_f32_16x16x32_bf16 v[98:101], v[146:149], v[208:211], v[98:101]
	v_mfma_f32_16x16x32_bf16 v[90:93], v[174:177], v[208:211], v[90:93]
	v_mfma_f32_16x16x32_bf16 v[82:85], v[146:149], v[216:219], v[82:85]
	v_mfma_f32_16x16x32_bf16 v[74:77], v[174:177], v[216:219], v[74:77]
	v_mfma_f32_16x16x32_bf16 v[70:73], v[146:149], v[224:227], v[70:73]
	v_mfma_f32_16x16x32_bf16 v[66:69], v[174:177], v[224:227], v[66:69]
	s_barrier
	s_setprio 2
	v_mfma_f32_16x16x32_bf16 v[114:117], v[150:153], v[204:207], v[114:117]
	v_mfma_f32_16x16x32_bf16 v[106:109], v[178:181], v[204:207], v[106:109]
	v_mfma_f32_16x16x32_bf16 v[98:101], v[150:153], v[212:215], v[98:101]
	v_mfma_f32_16x16x32_bf16 v[90:93], v[178:181], v[212:215], v[90:93]
	v_mfma_f32_16x16x32_bf16 v[82:85], v[150:153], v[220:223], v[82:85]
	v_mfma_f32_16x16x32_bf16 v[74:77], v[178:181], v[220:223], v[74:77]
	v_mfma_f32_16x16x32_bf16 v[70:73], v[150:153], v[234:237], v[70:73]
	v_mfma_f32_16x16x32_bf16 v[66:69], v[178:181], v[234:237], v[66:69]
	s_setprio 0
	s_add_i32 s46, s52, s8
	v_lshl_add_u64 v[186:187], s[42:43], 0, v[158:159]
	s_mov_b32 m0, s46
	ds_read_b128 v[182:185], v193 offset:16384
	ds_read_b128 v[204:207], v193 offset:17408
	ds_read_b128 v[208:211], v193 offset:18432
	ds_read_b128 v[212:215], v193 offset:19456
	ds_read_b128 v[216:219], v193 offset:20480
	ds_read_b128 v[220:223], v193 offset:21504
	ds_read_b128 v[224:227], v193 offset:22528
	ds_read_b128 v[234:237], v193 offset:23552
	global_load_lds_dwordx4 v[186:187], off
	s_add_i32 m0, s46, 0x2000
	s_add_u32 s46, s42, 0x100000
	v_lshl_add_u64 v[194:195], s[42:43], 0, v[162:163]
	s_addc_u32 s47, s43, 0
	s_add_i32 s56, s53, s8
	global_load_lds_dwordx4 v[194:195], off
	v_lshl_add_u64 v[200:201], s[46:47], 0, v[158:159]
	s_mov_b32 m0, s56
	v_lshl_add_u64 v[238:239], s[44:45], 0, v[160:161]
	global_load_lds_dwordx4 v[200:201], off
	v_lshl_add_u64 v[200:201], s[46:47], 0, v[162:163]
	s_add_i32 m0, s56, 0x2000
	s_nop 0
	global_load_lds_dwordx4 v[200:201], off
	v_lshl_add_u64 v[200:201], s[44:45], 0, v[156:157]
	s_mov_b32 m0, s9
	s_nop 0
	global_load_lds_dwordx4 v[200:201], off
	s_mov_b32 m0, s13
	s_nop 0
	global_load_lds_dwordx4 v[238:239], off
	s_waitcnt vmcnt(8)
	s_waitcnt lgkmcnt(0)
	s_barrier
	s_setprio 1
	s_waitcnt lgkmcnt(0)
	v_mfma_f32_16x16x32_bf16 v[62:65], v[130:133], v[182:185], v[62:65]
	v_mfma_f32_16x16x32_bf16 v[58:61], v[138:141], v[182:185], v[58:61]
	v_mfma_f32_16x16x32_bf16 v[54:57], v[130:133], v[208:211], v[54:57]
	v_mfma_f32_16x16x32_bf16 v[46:49], v[138:141], v[208:211], v[46:49]
	v_mfma_f32_16x16x32_bf16 v[38:41], v[130:133], v[216:219], v[38:41]
	v_mfma_f32_16x16x32_bf16 v[30:33], v[138:141], v[216:219], v[30:33]
	v_mfma_f32_16x16x32_bf16 v[22:25], v[130:133], v[224:227], v[22:25]
	v_mfma_f32_16x16x32_bf16 v[14:17], v[138:141], v[224:227], v[14:17]
	v_mfma_f32_16x16x32_bf16 v[62:65], v[134:137], v[204:207], v[62:65]
	v_mfma_f32_16x16x32_bf16 v[58:61], v[142:145], v[204:207], v[58:61]
	v_mfma_f32_16x16x32_bf16 v[54:57], v[134:137], v[212:215], v[54:57]
	v_mfma_f32_16x16x32_bf16 v[46:49], v[142:145], v[212:215], v[46:49]
	v_mfma_f32_16x16x32_bf16 v[38:41], v[134:137], v[220:223], v[38:41]
	v_mfma_f32_16x16x32_bf16 v[30:33], v[142:145], v[220:223], v[30:33]
	v_mfma_f32_16x16x32_bf16 v[22:25], v[134:137], v[234:237], v[22:25]
	v_mfma_f32_16x16x32_bf16 v[14:17], v[142:145], v[234:237], v[14:17]
	v_mfma_f32_16x16x32_bf16 v[50:53], v[146:149], v[182:185], v[50:53]
	v_mfma_f32_16x16x32_bf16 v[42:45], v[174:177], v[182:185], v[42:45]
	v_mfma_f32_16x16x32_bf16 v[34:37], v[146:149], v[208:211], v[34:37]
	v_mfma_f32_16x16x32_bf16 v[26:29], v[174:177], v[208:211], v[26:29]
	v_mfma_f32_16x16x32_bf16 v[18:21], v[146:149], v[216:219], v[18:21]
	v_mfma_f32_16x16x32_bf16 v[10:13], v[174:177], v[216:219], v[10:13]
	v_mfma_f32_16x16x32_bf16 v[6:9], v[146:149], v[224:227], v[6:9]
	v_mfma_f32_16x16x32_bf16 v[2:5], v[174:177], v[224:227], v[2:5]
	s_barrier
	s_setprio 2
	v_mfma_f32_16x16x32_bf16 v[50:53], v[150:153], v[204:207], v[50:53]
	v_mfma_f32_16x16x32_bf16 v[42:45], v[178:181], v[204:207], v[42:45]
	v_mfma_f32_16x16x32_bf16 v[34:37], v[150:153], v[212:215], v[34:37]
	v_mfma_f32_16x16x32_bf16 v[26:29], v[178:181], v[212:215], v[26:29]
	v_mfma_f32_16x16x32_bf16 v[18:21], v[150:153], v[220:223], v[18:21]
	v_mfma_f32_16x16x32_bf16 v[10:13], v[178:181], v[220:223], v[10:13]
	v_mfma_f32_16x16x32_bf16 v[6:9], v[150:153], v[234:237], v[6:9]
	v_mfma_f32_16x16x32_bf16 v[2:5], v[178:181], v[234:237], v[2:5]
	s_setprio 0
	s_add_i32 s46, 0, 0x18000
	s_add_i32 s47, 0, 0x1c000
	v_add_u32_e32 v142, s46, v188
	v_add_u32_e32 v164, s47, v188
	ds_read_b128 v[130:133], v142
	ds_read_b128 v[134:137], v142 offset:1024
	ds_read_b128 v[138:141], v142 offset:2048
	ds_read_b128 v[142:145], v142 offset:3072
	ds_read_b128 v[146:149], v164
	ds_read_b128 v[150:153], v164 offset:1024
	ds_read_b128 v[174:177], v164 offset:2048
	ds_read_b128 v[178:181], v164 offset:3072
	s_add_u32 s44, s44, 0x100000
	s_addc_u32 s45, s45, 0
	s_mov_b32 m0, s33
	v_lshl_add_u64 v[240:241], s[44:45], 0, v[156:157]
	ds_read_b128 v[182:185], v193 offset:32768
	ds_read_b128 v[204:207], v193 offset:33792
	ds_read_b128 v[208:211], v193 offset:34816
	ds_read_b128 v[212:215], v193 offset:35840
	ds_read_b128 v[216:219], v193 offset:36864
	ds_read_b128 v[220:223], v193 offset:37888
	ds_read_b128 v[224:227], v193 offset:38912
	ds_read_b128 v[234:237], v193 offset:39936
	global_load_lds_dwordx4 v[240:241], off
	v_lshl_add_u64 v[240:241], s[44:45], 0, v[160:161]
	s_mov_b32 m0, s39
	s_nop 0
	global_load_lds_dwordx4 v[240:241], off
	s_waitcnt vmcnt(8)
	s_waitcnt lgkmcnt(0)
	s_barrier
	s_setprio 1
	s_waitcnt lgkmcnt(0)
	v_mfma_f32_16x16x32_bf16 v[126:129], v[130:133], v[182:185], v[126:129]
	v_mfma_f32_16x16x32_bf16 v[122:125], v[138:141], v[182:185], v[122:125]
	v_mfma_f32_16x16x32_bf16 v[118:121], v[130:133], v[208:211], v[118:121]
	v_mfma_f32_16x16x32_bf16 v[110:113], v[138:141], v[208:211], v[110:113]
	v_mfma_f32_16x16x32_bf16 v[102:105], v[130:133], v[216:219], v[102:105]
	v_mfma_f32_16x16x32_bf16 v[94:97], v[138:141], v[216:219], v[94:97]
	v_mfma_f32_16x16x32_bf16 v[86:89], v[130:133], v[224:227], v[86:89]
	v_mfma_f32_16x16x32_bf16 v[78:81], v[138:141], v[224:227], v[78:81]
	v_mfma_f32_16x16x32_bf16 v[126:129], v[134:137], v[204:207], v[126:129]
	v_mfma_f32_16x16x32_bf16 v[122:125], v[142:145], v[204:207], v[122:125]
	v_mfma_f32_16x16x32_bf16 v[118:121], v[134:137], v[212:215], v[118:121]
	v_mfma_f32_16x16x32_bf16 v[110:113], v[142:145], v[212:215], v[110:113]
	v_mfma_f32_16x16x32_bf16 v[102:105], v[134:137], v[220:223], v[102:105]
	v_mfma_f32_16x16x32_bf16 v[94:97], v[142:145], v[220:223], v[94:97]
	v_mfma_f32_16x16x32_bf16 v[86:89], v[134:137], v[234:237], v[86:89]
	v_mfma_f32_16x16x32_bf16 v[78:81], v[142:145], v[234:237], v[78:81]
	v_mfma_f32_16x16x32_bf16 v[114:117], v[146:149], v[182:185], v[114:117]
	v_mfma_f32_16x16x32_bf16 v[106:109], v[174:177], v[182:185], v[106:109]
	v_mfma_f32_16x16x32_bf16 v[98:101], v[146:149], v[208:211], v[98:101]
	v_mfma_f32_16x16x32_bf16 v[90:93], v[174:177], v[208:211], v[90:93]
	v_mfma_f32_16x16x32_bf16 v[82:85], v[146:149], v[216:219], v[82:85]
	v_mfma_f32_16x16x32_bf16 v[74:77], v[174:177], v[216:219], v[74:77]
	v_mfma_f32_16x16x32_bf16 v[70:73], v[146:149], v[224:227], v[70:73]
	v_mfma_f32_16x16x32_bf16 v[66:69], v[174:177], v[224:227], v[66:69]
	s_barrier
	s_setprio 2
	v_mfma_f32_16x16x32_bf16 v[114:117], v[150:153], v[204:207], v[114:117]
	v_mfma_f32_16x16x32_bf16 v[106:109], v[178:181], v[204:207], v[106:109]
	v_mfma_f32_16x16x32_bf16 v[98:101], v[150:153], v[212:215], v[98:101]
	v_mfma_f32_16x16x32_bf16 v[90:93], v[178:181], v[212:215], v[90:93]
	v_mfma_f32_16x16x32_bf16 v[82:85], v[150:153], v[220:223], v[82:85]
	v_mfma_f32_16x16x32_bf16 v[74:77], v[178:181], v[220:223], v[74:77]
	v_mfma_f32_16x16x32_bf16 v[70:73], v[150:153], v[234:237], v[70:73]
	v_mfma_f32_16x16x32_bf16 v[66:69], v[178:181], v[234:237], v[66:69]
	s_setprio 0
	s_add_i32 s44, s46, s8
	v_lshl_add_u64 v[186:187], v[186:187], 0, s[20:21]
	s_mov_b32 m0, s44
	ds_read_b128 v[182:185], v193 offset:49152
	ds_read_b128 v[204:207], v193 offset:50176
	ds_read_b128 v[208:211], v193 offset:51200
	ds_read_b128 v[212:215], v193 offset:52224
	ds_read_b128 v[216:219], v193 offset:53248
	ds_read_b128 v[220:223], v193 offset:54272
	ds_read_b128 v[224:227], v193 offset:55296
	ds_read_b128 v[234:237], v193 offset:56320
	global_load_lds_dwordx4 v[186:187], off
	s_add_i32 m0, s44, 0x2000
	s_add_u32 s42, s42, 0x100080
	v_lshl_add_u64 v[186:187], v[194:195], 0, s[20:21]
	s_addc_u32 s43, s43, 0
	s_add_i32 s44, s47, s8
	global_load_lds_dwordx4 v[186:187], off
	v_lshl_add_u64 v[186:187], s[42:43], 0, v[158:159]
	s_mov_b32 m0, s44
	s_nop 0
	global_load_lds_dwordx4 v[186:187], off
	v_lshl_add_u64 v[186:187], s[42:43], 0, v[162:163]
	s_add_i32 m0, s44, 0x2000
	s_nop 0
	global_load_lds_dwordx4 v[186:187], off
	v_lshl_add_u64 v[186:187], v[200:201], 0, s[20:21]
	s_mov_b32 m0, s50
	s_nop 0
	global_load_lds_dwordx4 v[186:187], off
	v_lshl_add_u64 v[186:187], v[238:239], 0, s[20:21]
	s_mov_b32 m0, s51
	s_nop 0
	global_load_lds_dwordx4 v[186:187], off
	s_waitcnt vmcnt(8)
	s_waitcnt lgkmcnt(0)
	s_barrier
	s_setprio 1
	s_waitcnt lgkmcnt(0)
	v_mfma_f32_16x16x32_bf16 v[62:65], v[130:133], v[182:185], v[62:65]
	v_mfma_f32_16x16x32_bf16 v[58:61], v[138:141], v[182:185], v[58:61]
	v_mfma_f32_16x16x32_bf16 v[54:57], v[130:133], v[208:211], v[54:57]
	v_mfma_f32_16x16x32_bf16 v[46:49], v[138:141], v[208:211], v[46:49]
	v_mfma_f32_16x16x32_bf16 v[38:41], v[130:133], v[216:219], v[38:41]
	v_mfma_f32_16x16x32_bf16 v[30:33], v[138:141], v[216:219], v[30:33]
	v_mfma_f32_16x16x32_bf16 v[22:25], v[130:133], v[224:227], v[22:25]
	v_mfma_f32_16x16x32_bf16 v[14:17], v[138:141], v[224:227], v[14:17]
	v_mfma_f32_16x16x32_bf16 v[62:65], v[134:137], v[204:207], v[62:65]
	v_mfma_f32_16x16x32_bf16 v[58:61], v[142:145], v[204:207], v[58:61]
	v_mfma_f32_16x16x32_bf16 v[54:57], v[134:137], v[212:215], v[54:57]
	v_mfma_f32_16x16x32_bf16 v[46:49], v[142:145], v[212:215], v[46:49]
	v_mfma_f32_16x16x32_bf16 v[38:41], v[134:137], v[220:223], v[38:41]
	v_mfma_f32_16x16x32_bf16 v[30:33], v[142:145], v[220:223], v[30:33]
	v_mfma_f32_16x16x32_bf16 v[22:25], v[134:137], v[234:237], v[22:25]
	v_mfma_f32_16x16x32_bf16 v[14:17], v[142:145], v[234:237], v[14:17]
	v_mfma_f32_16x16x32_bf16 v[50:53], v[146:149], v[182:185], v[50:53]
	v_mfma_f32_16x16x32_bf16 v[42:45], v[174:177], v[182:185], v[42:45]
	v_mfma_f32_16x16x32_bf16 v[34:37], v[146:149], v[208:211], v[34:37]
	v_mfma_f32_16x16x32_bf16 v[26:29], v[174:177], v[208:211], v[26:29]
	v_mfma_f32_16x16x32_bf16 v[18:21], v[146:149], v[216:219], v[18:21]
	v_mfma_f32_16x16x32_bf16 v[10:13], v[174:177], v[216:219], v[10:13]
	v_mfma_f32_16x16x32_bf16 v[6:9], v[146:149], v[224:227], v[6:9]
	v_mfma_f32_16x16x32_bf16 v[2:5], v[174:177], v[224:227], v[2:5]
	s_barrier
	s_setprio 2
	v_mfma_f32_16x16x32_bf16 v[50:53], v[150:153], v[204:207], v[50:53]
	v_mfma_f32_16x16x32_bf16 v[42:45], v[178:181], v[204:207], v[42:45]
	v_mfma_f32_16x16x32_bf16 v[34:37], v[150:153], v[212:215], v[34:37]
	v_mfma_f32_16x16x32_bf16 v[26:29], v[178:181], v[212:215], v[26:29]
	v_mfma_f32_16x16x32_bf16 v[18:21], v[150:153], v[220:223], v[18:21]
	v_mfma_f32_16x16x32_bf16 v[10:13], v[178:181], v[220:223], v[10:13]
	v_mfma_f32_16x16x32_bf16 v[6:9], v[150:153], v[234:237], v[6:9]
	v_mfma_f32_16x16x32_bf16 v[2:5], v[178:181], v[234:237], v[2:5]
	s_setprio 0
	s_add_i32 s29, s29, 2
	s_add_u32 s40, s40, 0x100
	s_addc_u32 s41, s41, 0
	s_add_u32 s15, s15, 0x100
	s_addc_u32 s27, s27, 0
	s_cmp_gt_u32 s29, 61
	s_cbranch_scc0 .LBB0_412
	s_and_b64 vcc, exec, s[22:23]
	s_cbranch_vccz .LBB0_415
	s_barrier

.LBB0_514:
	ds_read_b128 v[156:159], v146
	ds_read_b128 v[160:163], v146 offset:1024
	ds_read_b128 v[164:167], v146 offset:2048
	ds_read_b128 v[168:171], v146 offset:3072
	ds_read_b128 v[172:175], v147
	s_waitcnt lgkmcnt(0)
	ds_read_b128 v[176:179], v147 offset:1024
	ds_read_b128 v[180:183], v147 offset:2048
	ds_read_b128 v[184:187], v147 offset:3072
	s_add_u32 s28, s26, 0xfff00080
	s_addc_u32 s29, s27, -1
	s_cmp_eq_u32 s50, 4
	s_cselect_b32 s31, s19, s29
	s_cselect_b32 s30, s18, s28
	s_cselect_b32 s29, s21, s49
	s_cselect_b32 s28, s20, s23
	s_mov_b32 m0, s36
	v_lshl_add_u64 v[142:143], s[26:27], 0, v[138:139]
	ds_read_b128 v[190:193], v148
	ds_read_b128 v[204:207], v148 offset:1024
	ds_read_b128 v[208:211], v148 offset:2048
	ds_read_b128 v[212:215], v148 offset:3072
	ds_read_b128 v[216:219], v148 offset:4096
	ds_read_b128 v[220:223], v148 offset:5120
	ds_read_b128 v[224:227], v148 offset:6144
	ds_read_b128 v[234:237], v148 offset:7168
	global_load_lds_dwordx4 v[142:143], off
	v_lshl_add_u64 v[142:143], s[26:27], 0, v[140:141]
	s_mov_b32 m0, s37
	s_nop 0
	global_load_lds_dwordx4 v[142:143], off
	s_waitcnt vmcnt(8)
	s_waitcnt lgkmcnt(0)
	s_barrier
	s_setprio 1
	s_waitcnt lgkmcnt(0)
	v_mfma_f32_16x16x32_bf16 v[126:129], v[156:159], v[190:193], v[126:129]
	v_mfma_f32_16x16x32_bf16 v[122:125], v[164:167], v[190:193], v[122:125]
	v_mfma_f32_16x16x32_bf16 v[118:121], v[156:159], v[208:211], v[118:121]
	v_mfma_f32_16x16x32_bf16 v[110:113], v[164:167], v[208:211], v[110:113]
	v_mfma_f32_16x16x32_bf16 v[102:105], v[156:159], v[216:219], v[102:105]
	v_mfma_f32_16x16x32_bf16 v[94:97], v[164:167], v[216:219], v[94:97]
	v_mfma_f32_16x16x32_bf16 v[82:85], v[156:159], v[224:227], v[82:85]
	v_mfma_f32_16x16x32_bf16 v[74:77], v[164:167], v[224:227], v[74:77]
	v_mfma_f32_16x16x32_bf16 v[126:129], v[160:163], v[204:207], v[126:129]
	v_mfma_f32_16x16x32_bf16 v[122:125], v[168:171], v[204:207], v[122:125]
	v_mfma_f32_16x16x32_bf16 v[118:121], v[160:163], v[212:215], v[118:121]
	v_mfma_f32_16x16x32_bf16 v[110:113], v[168:171], v[212:215], v[110:113]
	v_mfma_f32_16x16x32_bf16 v[102:105], v[160:163], v[220:223], v[102:105]
	v_mfma_f32_16x16x32_bf16 v[94:97], v[168:171], v[220:223], v[94:97]
	v_mfma_f32_16x16x32_bf16 v[82:85], v[160:163], v[234:237], v[82:85]
	v_mfma_f32_16x16x32_bf16 v[74:77], v[168:171], v[234:237], v[74:77]
	v_mfma_f32_16x16x32_bf16 v[114:117], v[172:175], v[190:193], v[114:117]
	v_mfma_f32_16x16x32_bf16 v[106:109], v[180:183], v[190:193], v[106:109]
	v_mfma_f32_16x16x32_bf16 v[98:101], v[172:175], v[208:211], v[98:101]
	v_mfma_f32_16x16x32_bf16 v[90:93], v[180:183], v[208:211], v[90:93]
	v_mfma_f32_16x16x32_bf16 v[86:89], v[172:175], v[216:219], v[86:89]
	v_mfma_f32_16x16x32_bf16 v[78:81], v[180:183], v[216:219], v[78:81]
	v_mfma_f32_16x16x32_bf16 v[70:73], v[172:175], v[224:227], v[70:73]
	v_mfma_f32_16x16x32_bf16 v[66:69], v[180:183], v[224:227], v[66:69]
	s_barrier
	s_setprio 2
	v_mfma_f32_16x16x32_bf16 v[114:117], v[176:179], v[204:207], v[114:117]
	v_mfma_f32_16x16x32_bf16 v[106:109], v[184:187], v[204:207], v[106:109]
	v_mfma_f32_16x16x32_bf16 v[98:101], v[176:179], v[212:215], v[98:101]
	v_mfma_f32_16x16x32_bf16 v[90:93], v[184:187], v[212:215], v[90:93]
	v_mfma_f32_16x16x32_bf16 v[86:89], v[176:179], v[220:223], v[86:89]
	v_mfma_f32_16x16x32_bf16 v[78:81], v[184:187], v[220:223], v[78:81]
	v_mfma_f32_16x16x32_bf16 v[70:73], v[176:179], v[234:237], v[70:73]
	v_mfma_f32_16x16x32_bf16 v[66:69], v[184:187], v[234:237], v[66:69]
	s_setprio 0
	s_mov_b32 m0, s38
	v_lshl_add_u64 v[142:143], s[28:29], 0, v[134:135]
	s_add_u32 s52, s28, 0x20000
	ds_read_b128 v[190:193], v148 offset:16384
	ds_read_b128 v[204:207], v148 offset:17408
	ds_read_b128 v[208:211], v148 offset:18432
	ds_read_b128 v[212:215], v148 offset:19456
	ds_read_b128 v[216:219], v148 offset:20480
	ds_read_b128 v[220:223], v148 offset:21504
	ds_read_b128 v[224:227], v148 offset:22528
	ds_read_b128 v[234:237], v148 offset:23552
	global_load_lds_dwordx4 v[142:143], off
	v_lshl_add_u64 v[152:153], s[28:29], 0, v[130:131]
	s_mov_b32 m0, s39
	s_addc_u32 s53, s29, 0
	global_load_lds_dwordx4 v[152:153], off
	v_lshl_add_u64 v[194:195], s[52:53], 0, v[134:135]
	s_mov_b32 m0, s40
	v_lshl_add_u64 v[200:201], s[30:31], 0, v[132:133]
	global_load_lds_dwordx4 v[194:195], off
	v_lshl_add_u64 v[194:195], s[52:53], 0, v[130:131]
	s_mov_b32 m0, s41
	s_nop 0
	global_load_lds_dwordx4 v[194:195], off
	v_lshl_add_u64 v[194:195], s[30:31], 0, v[136:137]
	s_mov_b32 m0, s9
	s_nop 0
	global_load_lds_dwordx4 v[194:195], off
	s_mov_b32 m0, s13
	s_nop 0
	global_load_lds_dwordx4 v[200:201], off
	s_waitcnt vmcnt(8)
	s_waitcnt lgkmcnt(0)
	s_barrier
	s_setprio 1
	s_waitcnt lgkmcnt(0)
	v_mfma_f32_16x16x32_bf16 v[62:65], v[156:159], v[190:193], v[62:65]
	v_mfma_f32_16x16x32_bf16 v[58:61], v[164:167], v[190:193], v[58:61]
	v_mfma_f32_16x16x32_bf16 v[54:57], v[156:159], v[208:211], v[54:57]
	v_mfma_f32_16x16x32_bf16 v[46:49], v[164:167], v[208:211], v[46:49]
	v_mfma_f32_16x16x32_bf16 v[38:41], v[156:159], v[216:219], v[38:41]
	v_mfma_f32_16x16x32_bf16 v[30:33], v[164:167], v[216:219], v[30:33]
	v_mfma_f32_16x16x32_bf16 v[22:25], v[156:159], v[224:227], v[22:25]
	v_mfma_f32_16x16x32_bf16 v[14:17], v[164:167], v[224:227], v[14:17]
	v_mfma_f32_16x16x32_bf16 v[62:65], v[160:163], v[204:207], v[62:65]
	v_mfma_f32_16x16x32_bf16 v[58:61], v[168:171], v[204:207], v[58:61]
	v_mfma_f32_16x16x32_bf16 v[54:57], v[160:163], v[212:215], v[54:57]
	v_mfma_f32_16x16x32_bf16 v[46:49], v[168:171], v[212:215], v[46:49]
	v_mfma_f32_16x16x32_bf16 v[38:41], v[160:163], v[220:223], v[38:41]
	v_mfma_f32_16x16x32_bf16 v[30:33], v[168:171], v[220:223], v[30:33]
	v_mfma_f32_16x16x32_bf16 v[22:25], v[160:163], v[234:237], v[22:25]
	v_mfma_f32_16x16x32_bf16 v[14:17], v[168:171], v[234:237], v[14:17]
	v_mfma_f32_16x16x32_bf16 v[50:53], v[172:175], v[190:193], v[50:53]
	v_mfma_f32_16x16x32_bf16 v[42:45], v[180:183], v[190:193], v[42:45]
	v_mfma_f32_16x16x32_bf16 v[34:37], v[172:175], v[208:211], v[34:37]
	v_mfma_f32_16x16x32_bf16 v[26:29], v[180:183], v[208:211], v[26:29]
	v_mfma_f32_16x16x32_bf16 v[18:21], v[172:175], v[216:219], v[18:21]
	v_mfma_f32_16x16x32_bf16 v[10:13], v[180:183], v[216:219], v[10:13]
	v_mfma_f32_16x16x32_bf16 v[6:9], v[172:175], v[224:227], v[6:9]
	v_mfma_f32_16x16x32_bf16 v[2:5], v[180:183], v[224:227], v[2:5]
	s_barrier
	s_setprio 2
	v_mfma_f32_16x16x32_bf16 v[50:53], v[176:179], v[204:207], v[50:53]
	v_mfma_f32_16x16x32_bf16 v[42:45], v[184:187], v[204:207], v[42:45]
	v_mfma_f32_16x16x32_bf16 v[34:37], v[176:179], v[212:215], v[34:37]
	v_mfma_f32_16x16x32_bf16 v[26:29], v[184:187], v[212:215], v[26:29]
	v_mfma_f32_16x16x32_bf16 v[18:21], v[176:179], v[220:223], v[18:21]
	v_mfma_f32_16x16x32_bf16 v[10:13], v[184:187], v[220:223], v[10:13]
	v_mfma_f32_16x16x32_bf16 v[6:9], v[176:179], v[234:237], v[6:9]
	v_mfma_f32_16x16x32_bf16 v[2:5], v[184:187], v[234:237], v[2:5]
	s_setprio 0
	ds_read_b128 v[156:159], v149
	ds_read_b128 v[160:163], v149 offset:1024
	ds_read_b128 v[164:167], v149 offset:2048
	ds_read_b128 v[168:171], v149 offset:3072
	ds_read_b128 v[172:175], v150
	ds_read_b128 v[176:179], v150 offset:1024
	ds_read_b128 v[180:183], v150 offset:2048
	ds_read_b128 v[184:187], v150 offset:3072
	s_add_u32 s30, s30, 0x100000
	s_addc_u32 s31, s31, 0
	s_mov_b32 m0, s14
	v_lshl_add_u64 v[238:239], s[30:31], 0, v[136:137]
	ds_read_b128 v[190:193], v148 offset:32768
	ds_read_b128 v[204:207], v148 offset:33792
	ds_read_b128 v[208:211], v148 offset:34816
	ds_read_b128 v[212:215], v148 offset:35840
	ds_read_b128 v[216:219], v148 offset:36864
	ds_read_b128 v[220:223], v148 offset:37888
	ds_read_b128 v[224:227], v148 offset:38912
	ds_read_b128 v[234:237], v148 offset:39936
	global_load_lds_dwordx4 v[238:239], off
	v_lshl_add_u64 v[238:239], s[30:31], 0, v[132:133]
	s_mov_b32 m0, s15
	s_nop 0
	global_load_lds_dwordx4 v[238:239], off
	s_waitcnt vmcnt(8)
	s_waitcnt lgkmcnt(0)
	s_barrier
	s_setprio 1
	s_waitcnt lgkmcnt(0)
	v_mfma_f32_16x16x32_bf16 v[126:129], v[156:159], v[190:193], v[126:129]
	v_mfma_f32_16x16x32_bf16 v[122:125], v[164:167], v[190:193], v[122:125]
	v_mfma_f32_16x16x32_bf16 v[118:121], v[156:159], v[208:211], v[118:121]
	v_mfma_f32_16x16x32_bf16 v[110:113], v[164:167], v[208:211], v[110:113]
	v_mfma_f32_16x16x32_bf16 v[102:105], v[156:159], v[216:219], v[102:105]
	v_mfma_f32_16x16x32_bf16 v[94:97], v[164:167], v[216:219], v[94:97]
	v_mfma_f32_16x16x32_bf16 v[82:85], v[156:159], v[224:227], v[82:85]
	v_mfma_f32_16x16x32_bf16 v[74:77], v[164:167], v[224:227], v[74:77]
	v_mfma_f32_16x16x32_bf16 v[126:129], v[160:163], v[204:207], v[126:129]
	v_mfma_f32_16x16x32_bf16 v[122:125], v[168:171], v[204:207], v[122:125]
	v_mfma_f32_16x16x32_bf16 v[118:121], v[160:163], v[212:215], v[118:121]
	v_mfma_f32_16x16x32_bf16 v[110:113], v[168:171], v[212:215], v[110:113]
	v_mfma_f32_16x16x32_bf16 v[102:105], v[160:163], v[220:223], v[102:105]
	v_mfma_f32_16x16x32_bf16 v[94:97], v[168:171], v[220:223], v[94:97]
	v_mfma_f32_16x16x32_bf16 v[82:85], v[160:163], v[234:237], v[82:85]
	v_mfma_f32_16x16x32_bf16 v[74:77], v[168:171], v[234:237], v[74:77]
	v_mfma_f32_16x16x32_bf16 v[114:117], v[172:175], v[190:193], v[114:117]
	v_mfma_f32_16x16x32_bf16 v[106:109], v[180:183], v[190:193], v[106:109]
	v_mfma_f32_16x16x32_bf16 v[98:101], v[172:175], v[208:211], v[98:101]
	v_mfma_f32_16x16x32_bf16 v[90:93], v[180:183], v[208:211], v[90:93]
	v_mfma_f32_16x16x32_bf16 v[86:89], v[172:175], v[216:219], v[86:89]
	v_mfma_f32_16x16x32_bf16 v[78:81], v[180:183], v[216:219], v[78:81]
	v_mfma_f32_16x16x32_bf16 v[70:73], v[172:175], v[224:227], v[70:73]
	v_mfma_f32_16x16x32_bf16 v[66:69], v[180:183], v[224:227], v[66:69]
	s_barrier
	s_setprio 2
	v_mfma_f32_16x16x32_bf16 v[114:117], v[176:179], v[204:207], v[114:117]
	v_mfma_f32_16x16x32_bf16 v[106:109], v[184:187], v[204:207], v[106:109]
	v_mfma_f32_16x16x32_bf16 v[98:101], v[176:179], v[212:215], v[98:101]
	v_mfma_f32_16x16x32_bf16 v[90:93], v[184:187], v[212:215], v[90:93]
	v_mfma_f32_16x16x32_bf16 v[86:89], v[176:179], v[220:223], v[86:89]
	v_mfma_f32_16x16x32_bf16 v[78:81], v[184:187], v[220:223], v[78:81]
	v_mfma_f32_16x16x32_bf16 v[70:73], v[176:179], v[234:237], v[70:73]
	v_mfma_f32_16x16x32_bf16 v[66:69], v[184:187], v[234:237], v[66:69]
	s_setprio 0
	s_mov_b32 m0, s42
	v_lshl_add_u64 v[142:143], v[142:143], 0, s[4:5]
	s_add_u32 s28, s28, 0x20080
	ds_read_b128 v[190:193], v148 offset:49152
	ds_read_b128 v[204:207], v148 offset:50176
	ds_read_b128 v[208:211], v148 offset:51200
	ds_read_b128 v[212:215], v148 offset:52224
	ds_read_b128 v[216:219], v148 offset:53248
	ds_read_b128 v[220:223], v148 offset:54272
	ds_read_b128 v[224:227], v148 offset:55296
	ds_read_b128 v[234:237], v148 offset:56320
	global_load_lds_dwordx4 v[142:143], off
	v_lshl_add_u64 v[142:143], v[152:153], 0, s[4:5]
	s_mov_b32 m0, s43
	s_addc_u32 s29, s29, 0
	global_load_lds_dwordx4 v[142:143], off
	v_lshl_add_u64 v[142:143], s[28:29], 0, v[134:135]
	s_mov_b32 m0, s44
	s_nop 0
	global_load_lds_dwordx4 v[142:143], off
	v_lshl_add_u64 v[142:143], s[28:29], 0, v[130:131]
	s_mov_b32 m0, s45
	s_nop 0
	global_load_lds_dwordx4 v[142:143], off
	v_lshl_add_u64 v[142:143], v[194:195], 0, s[4:5]
	s_mov_b32 m0, s34
	s_nop 0
	global_load_lds_dwordx4 v[142:143], off
	v_lshl_add_u64 v[142:143], v[200:201], 0, s[4:5]
	s_mov_b32 m0, s35
	s_nop 0
	global_load_lds_dwordx4 v[142:143], off
	s_waitcnt vmcnt(8)
	s_waitcnt lgkmcnt(0)
	s_barrier
	s_setprio 1
	s_waitcnt lgkmcnt(0)
	v_mfma_f32_16x16x32_bf16 v[62:65], v[156:159], v[190:193], v[62:65]
	v_mfma_f32_16x16x32_bf16 v[58:61], v[164:167], v[190:193], v[58:61]
	v_mfma_f32_16x16x32_bf16 v[54:57], v[156:159], v[208:211], v[54:57]
	v_mfma_f32_16x16x32_bf16 v[46:49], v[164:167], v[208:211], v[46:49]
	v_mfma_f32_16x16x32_bf16 v[38:41], v[156:159], v[216:219], v[38:41]
	v_mfma_f32_16x16x32_bf16 v[30:33], v[164:167], v[216:219], v[30:33]
	v_mfma_f32_16x16x32_bf16 v[22:25], v[156:159], v[224:227], v[22:25]
	v_mfma_f32_16x16x32_bf16 v[14:17], v[164:167], v[224:227], v[14:17]
	v_mfma_f32_16x16x32_bf16 v[62:65], v[160:163], v[204:207], v[62:65]
	v_mfma_f32_16x16x32_bf16 v[58:61], v[168:171], v[204:207], v[58:61]
	v_mfma_f32_16x16x32_bf16 v[54:57], v[160:163], v[212:215], v[54:57]
	v_mfma_f32_16x16x32_bf16 v[46:49], v[168:171], v[212:215], v[46:49]
	v_mfma_f32_16x16x32_bf16 v[38:41], v[160:163], v[220:223], v[38:41]
	v_mfma_f32_16x16x32_bf16 v[30:33], v[168:171], v[220:223], v[30:33]
	v_mfma_f32_16x16x32_bf16 v[22:25], v[160:163], v[234:237], v[22:25]
	v_mfma_f32_16x16x32_bf16 v[14:17], v[168:171], v[234:237], v[14:17]
	v_mfma_f32_16x16x32_bf16 v[50:53], v[172:175], v[190:193], v[50:53]
	v_mfma_f32_16x16x32_bf16 v[42:45], v[180:183], v[190:193], v[42:45]
	v_mfma_f32_16x16x32_bf16 v[34:37], v[172:175], v[208:211], v[34:37]
	v_mfma_f32_16x16x32_bf16 v[26:29], v[180:183], v[208:211], v[26:29]
	v_mfma_f32_16x16x32_bf16 v[18:21], v[172:175], v[216:219], v[18:21]
	v_mfma_f32_16x16x32_bf16 v[10:13], v[180:183], v[216:219], v[10:13]
	v_mfma_f32_16x16x32_bf16 v[6:9], v[172:175], v[224:227], v[6:9]
	v_mfma_f32_16x16x32_bf16 v[2:5], v[180:183], v[224:227], v[2:5]
	s_barrier
	s_setprio 2
	v_mfma_f32_16x16x32_bf16 v[50:53], v[176:179], v[204:207], v[50:53]
	v_mfma_f32_16x16x32_bf16 v[42:45], v[184:187], v[204:207], v[42:45]
	v_mfma_f32_16x16x32_bf16 v[34:37], v[176:179], v[212:215], v[34:37]
	v_mfma_f32_16x16x32_bf16 v[26:29], v[184:187], v[212:215], v[26:29]
	v_mfma_f32_16x16x32_bf16 v[18:21], v[176:179], v[220:223], v[18:21]
	v_mfma_f32_16x16x32_bf16 v[10:13], v[184:187], v[220:223], v[10:13]
	v_mfma_f32_16x16x32_bf16 v[6:9], v[176:179], v[234:237], v[6:9]
	v_mfma_f32_16x16x32_bf16 v[2:5], v[184:187], v[234:237], v[2:5]
	s_setprio 0
	s_add_i32 s50, s50, 2
	s_add_u32 s26, s26, 0x100
	s_addc_u32 s27, s27, 0
	s_add_u32 s23, s23, 0x100
	s_addc_u32 s49, s49, 0
	s_cmp_gt_u32 s50, 5
	s_cbranch_scc0 .LBB0_514
	s_and_b64 vcc, exec, s[6:7]
	s_cbranch_vccz .LBB0_517
	s_barrier

.LBB0_734:
	ds_read_b128 v[158:161], v227
	ds_read_b128 v[154:157], v227 offset:1024
	ds_read_b128 v[150:153], v227 offset:2048
	ds_read_b128 v[146:149], v227 offset:3072
	ds_read_b128 v[62:65], v233
	ds_read_b128 v[58:61], v233 offset:1024
	ds_read_b128 v[54:57], v233 offset:2048
	ds_read_b128 v[50:53], v233 offset:3072
	s_add_u32 s14, s30, s34
	s_addc_u32 s15, s31, s35
	s_add_u32 s14, s14, 0x100
	s_addc_u32 s15, s15, 0
	s_add_u32 s25, s77, s34
	s_addc_u32 s29, s78, s35
	s_cmpk_eq_i32 s34, 0xf00
	s_cselect_b32 s41, s31, s15
	s_cselect_b32 s40, s30, s14
	s_cselect_b32 s39, s1, s29
	s_cselect_b32 s38, s0, s25
	s_add_i32 s66, s23, 0xc000
	v_lshl_add_u64 v[240:241], v[162:163], 0, s[34:35]
	s_mov_b32 m0, s66
	s_add_i32 s67, s23, 0xe000
	ds_read_b128 v[166:169], v226
	ds_read_b128 v[170:173], v226 offset:1024
	ds_read_b128 v[174:177], v226 offset:2048
	ds_read_b128 v[178:181], v226 offset:3072
	ds_read_b128 v[182:185], v226 offset:4096
	ds_read_b128 v[186:189], v226 offset:5120
	ds_read_b128 v[190:193], v226 offset:6144
	ds_read_b128 v[236:239], v226 offset:7168
	global_load_lds_dwordx4 v[240:241], off
	v_lshl_add_u64 v[240:241], v[164:165], 0, s[34:35]
	s_mov_b32 m0, s67
	s_nop 0
	global_load_lds_dwordx4 v[240:241], off
	s_waitcnt vmcnt(8)
	s_waitcnt lgkmcnt(0)
	s_barrier
	s_setprio 1
	s_waitcnt lgkmcnt(0)
	v_mfma_i32_16x16x64_i8 v[142:145], v[158:161], v[166:169], v[142:145]
	v_mfma_i32_16x16x64_i8 v[142:145], v[154:157], v[170:173], v[142:145]
	v_mfma_i32_16x16x64_i8 v[138:141], v[150:153], v[166:169], v[138:141]
	v_mfma_i32_16x16x64_i8 v[138:141], v[146:149], v[170:173], v[138:141]
	v_mfma_i32_16x16x64_i8 v[126:129], v[158:161], v[174:177], v[126:129]
	v_mfma_i32_16x16x64_i8 v[126:129], v[154:157], v[178:181], v[126:129]
	v_mfma_i32_16x16x64_i8 v[122:125], v[150:153], v[174:177], v[122:125]
	v_mfma_i32_16x16x64_i8 v[122:125], v[146:149], v[178:181], v[122:125]
	v_mfma_i32_16x16x64_i8 v[110:113], v[158:161], v[182:185], v[110:113]
	v_mfma_i32_16x16x64_i8 v[110:113], v[154:157], v[186:189], v[110:113]
	v_mfma_i32_16x16x64_i8 v[106:109], v[150:153], v[182:185], v[106:109]
	v_mfma_i32_16x16x64_i8 v[106:109], v[146:149], v[186:189], v[106:109]
	v_mfma_i32_16x16x64_i8 v[94:97], v[158:161], v[190:193], v[94:97]
	v_mfma_i32_16x16x64_i8 v[94:97], v[154:157], v[236:239], v[94:97]
	v_mfma_i32_16x16x64_i8 v[90:93], v[150:153], v[190:193], v[90:93]
	v_mfma_i32_16x16x64_i8 v[90:93], v[146:149], v[236:239], v[90:93]
	v_mfma_i32_16x16x64_i8 v[134:137], v[62:65], v[166:169], v[134:137]
	v_mfma_i32_16x16x64_i8 v[134:137], v[58:61], v[170:173], v[134:137]
	v_mfma_i32_16x16x64_i8 v[130:133], v[54:57], v[166:169], v[130:133]
	v_mfma_i32_16x16x64_i8 v[130:133], v[50:53], v[170:173], v[130:133]
	v_mfma_i32_16x16x64_i8 v[118:121], v[62:65], v[174:177], v[118:121]
	v_mfma_i32_16x16x64_i8 v[118:121], v[58:61], v[178:181], v[118:121]
	v_mfma_i32_16x16x64_i8 v[114:117], v[54:57], v[174:177], v[114:117]
	v_mfma_i32_16x16x64_i8 v[114:117], v[50:53], v[178:181], v[114:117]
	s_barrier
	s_setprio 2
	v_mfma_i32_16x16x64_i8 v[102:105], v[62:65], v[182:185], v[102:105]
	v_mfma_i32_16x16x64_i8 v[102:105], v[58:61], v[186:189], v[102:105]
	v_mfma_i32_16x16x64_i8 v[98:101], v[54:57], v[182:185], v[98:101]
	v_mfma_i32_16x16x64_i8 v[98:101], v[50:53], v[186:189], v[98:101]
	v_mfma_i32_16x16x64_i8 v[86:89], v[62:65], v[190:193], v[86:89]
	v_mfma_i32_16x16x64_i8 v[86:89], v[58:61], v[236:239], v[86:89]
	v_mfma_i32_16x16x64_i8 v[82:85], v[54:57], v[190:193], v[82:85]
	v_mfma_i32_16x16x64_i8 v[82:85], v[50:53], v[236:239], v[82:85]
	s_setprio 0
	s_add_i32 s68, s60, s21
	s_add_i32 s69, s68, 0x2000
	v_lshl_add_u64 v[166:167], s[38:39], 0, v[202:203]
	s_mov_b32 m0, s68
	s_add_u32 s14, s38, 0x80000
	ds_read_b128 v[174:177], v226 offset:16384
	ds_read_b128 v[178:181], v226 offset:17408
	ds_read_b128 v[182:185], v226 offset:18432
	ds_read_b128 v[186:189], v226 offset:19456
	ds_read_b128 v[190:193], v226 offset:20480
	ds_read_b128 v[236:239], v226 offset:21504
	ds_read_b128 v[240:243], v226 offset:22528
	ds_read_b128 v[244:247], v226 offset:23552
	global_load_lds_dwordx4 v[166:167], off
	v_lshl_add_u64 v[168:169], s[38:39], 0, v[206:207]
	s_mov_b32 m0, s69
	s_addc_u32 s15, s39, 0
	s_add_i32 s70, s61, s21
	global_load_lds_dwordx4 v[168:169], off
	v_lshl_add_u64 v[170:171], s[14:15], 0, v[202:203]
	s_mov_b32 m0, s70
	s_add_i32 s71, s70, 0x2000
	global_load_lds_dwordx4 v[170:171], off
	v_lshl_add_u64 v[170:171], s[14:15], 0, v[206:207]
	s_mov_b32 m0, s71
	v_lshl_add_u64 v[172:173], s[40:41], 0, v[204:205]
	global_load_lds_dwordx4 v[170:171], off
	v_lshl_add_u64 v[170:171], s[40:41], 0, v[194:195]
	s_mov_b32 m0, s23
	s_nop 0
	global_load_lds_dwordx4 v[170:171], off
	s_mov_b32 m0, s42
	s_nop 0
	global_load_lds_dwordx4 v[172:173], off
	s_waitcnt vmcnt(8)
	s_waitcnt lgkmcnt(0)
	s_barrier
	s_setprio 1
	s_waitcnt lgkmcnt(0)
	v_mfma_i32_16x16x64_i8 v[78:81], v[158:161], v[174:177], v[78:81]
	v_mfma_i32_16x16x64_i8 v[78:81], v[154:157], v[178:181], v[78:81]
	v_mfma_i32_16x16x64_i8 v[74:77], v[150:153], v[174:177], v[74:77]
	v_mfma_i32_16x16x64_i8 v[74:77], v[146:149], v[178:181], v[74:77]
	v_mfma_i32_16x16x64_i8 v[46:49], v[158:161], v[182:185], v[46:49]
	v_mfma_i32_16x16x64_i8 v[46:49], v[154:157], v[186:189], v[46:49]
	v_mfma_i32_16x16x64_i8 v[42:45], v[150:153], v[182:185], v[42:45]
	v_mfma_i32_16x16x64_i8 v[42:45], v[146:149], v[186:189], v[42:45]
	v_mfma_i32_16x16x64_i8 v[30:33], v[158:161], v[190:193], v[30:33]
	v_mfma_i32_16x16x64_i8 v[30:33], v[154:157], v[236:239], v[30:33]
	v_mfma_i32_16x16x64_i8 v[26:29], v[150:153], v[190:193], v[26:29]
	v_mfma_i32_16x16x64_i8 v[26:29], v[146:149], v[236:239], v[26:29]
	v_mfma_i32_16x16x64_i8 v[14:17], v[158:161], v[240:243], v[14:17]
	v_mfma_i32_16x16x64_i8 v[14:17], v[154:157], v[244:247], v[14:17]
	v_mfma_i32_16x16x64_i8 v[10:13], v[150:153], v[240:243], v[10:13]
	v_mfma_i32_16x16x64_i8 v[10:13], v[146:149], v[244:247], v[10:13]
	v_mfma_i32_16x16x64_i8 v[70:73], v[62:65], v[174:177], v[70:73]
	v_mfma_i32_16x16x64_i8 v[70:73], v[58:61], v[178:181], v[70:73]
	v_mfma_i32_16x16x64_i8 v[66:69], v[54:57], v[174:177], v[66:69]
	v_mfma_i32_16x16x64_i8 v[66:69], v[50:53], v[178:181], v[66:69]
	v_mfma_i32_16x16x64_i8 v[38:41], v[62:65], v[182:185], v[38:41]
	v_mfma_i32_16x16x64_i8 v[38:41], v[58:61], v[186:189], v[38:41]
	v_mfma_i32_16x16x64_i8 v[34:37], v[54:57], v[182:185], v[34:37]
	v_mfma_i32_16x16x64_i8 v[34:37], v[50:53], v[186:189], v[34:37]
	s_barrier
	s_setprio 2
	v_mfma_i32_16x16x64_i8 v[22:25], v[62:65], v[190:193], v[22:25]
	v_mfma_i32_16x16x64_i8 v[22:25], v[58:61], v[236:239], v[22:25]
	v_mfma_i32_16x16x64_i8 v[18:21], v[54:57], v[190:193], v[18:21]
	v_mfma_i32_16x16x64_i8 v[18:21], v[50:53], v[236:239], v[18:21]
	v_mfma_i32_16x16x64_i8 v[6:9], v[62:65], v[240:243], v[6:9]
	v_mfma_i32_16x16x64_i8 v[6:9], v[58:61], v[244:247], v[6:9]
	v_mfma_i32_16x16x64_i8 v[2:5], v[54:57], v[240:243], v[2:5]
	v_mfma_i32_16x16x64_i8 v[2:5], v[50:53], v[244:247], v[2:5]
	s_setprio 0
	s_add_i32 s72, 0, 0x18000
	v_add_u32_e32 v235, s72, v225
	s_add_i32 s74, 0, 0x1c000
	v_add_u32_e32 v236, s74, v225
	ds_read_b128 v[50:53], v235
	ds_read_b128 v[54:57], v235 offset:1024
	ds_read_b128 v[58:61], v235 offset:2048
	ds_read_b128 v[62:65], v235 offset:3072
	ds_read_b128 v[146:149], v236
	ds_read_b128 v[150:153], v236 offset:1024
	ds_read_b128 v[154:157], v236 offset:2048
	ds_read_b128 v[158:161], v236 offset:3072
	s_add_u32 s14, s40, 0x80000
	s_addc_u32 s15, s41, 0
	s_mov_b32 m0, s43
	v_lshl_add_u64 v[250:251], s[14:15], 0, v[194:195]
	ds_read_b128 v[174:177], v226 offset:32768
	ds_read_b128 v[178:181], v226 offset:33792
	ds_read_b128 v[182:185], v226 offset:34816
	ds_read_b128 v[186:189], v226 offset:35840
	ds_read_b128 v[190:193], v226 offset:36864
	ds_read_b128 v[238:241], v226 offset:37888
	ds_read_b128 v[242:245], v226 offset:38912
	ds_read_b128 v[246:249], v226 offset:39936
	global_load_lds_dwordx4 v[250:251], off
	v_lshl_add_u64 v[250:251], s[14:15], 0, v[204:205]
	s_mov_b32 m0, s44
	s_nop 0
	global_load_lds_dwordx4 v[250:251], off
	s_waitcnt vmcnt(8)
	s_waitcnt lgkmcnt(0)
	s_barrier
	s_setprio 1
	s_waitcnt lgkmcnt(0)
	v_mfma_i32_16x16x64_i8 v[142:145], v[50:53], v[174:177], v[142:145]
	v_mfma_i32_16x16x64_i8 v[142:145], v[54:57], v[178:181], v[142:145]
	v_mfma_i32_16x16x64_i8 v[138:141], v[58:61], v[174:177], v[138:141]
	v_mfma_i32_16x16x64_i8 v[138:141], v[62:65], v[178:181], v[138:141]
	v_mfma_i32_16x16x64_i8 v[126:129], v[50:53], v[182:185], v[126:129]
	v_mfma_i32_16x16x64_i8 v[126:129], v[54:57], v[186:189], v[126:129]
	v_mfma_i32_16x16x64_i8 v[122:125], v[58:61], v[182:185], v[122:125]
	v_mfma_i32_16x16x64_i8 v[122:125], v[62:65], v[186:189], v[122:125]
	v_mfma_i32_16x16x64_i8 v[110:113], v[50:53], v[190:193], v[110:113]
	v_mfma_i32_16x16x64_i8 v[110:113], v[54:57], v[238:241], v[110:113]
	v_mfma_i32_16x16x64_i8 v[106:109], v[58:61], v[190:193], v[106:109]
	v_mfma_i32_16x16x64_i8 v[106:109], v[62:65], v[238:241], v[106:109]
	v_mfma_i32_16x16x64_i8 v[94:97], v[50:53], v[242:245], v[94:97]
	v_mfma_i32_16x16x64_i8 v[94:97], v[54:57], v[246:249], v[94:97]
	v_mfma_i32_16x16x64_i8 v[90:93], v[58:61], v[242:245], v[90:93]
	v_mfma_i32_16x16x64_i8 v[90:93], v[62:65], v[246:249], v[90:93]
	v_mfma_i32_16x16x64_i8 v[134:137], v[146:149], v[174:177], v[134:137]
	v_mfma_i32_16x16x64_i8 v[134:137], v[150:153], v[178:181], v[134:137]
	v_mfma_i32_16x16x64_i8 v[130:133], v[154:157], v[174:177], v[130:133]
	v_mfma_i32_16x16x64_i8 v[130:133], v[158:161], v[178:181], v[130:133]
	v_mfma_i32_16x16x64_i8 v[118:121], v[146:149], v[182:185], v[118:121]
	v_mfma_i32_16x16x64_i8 v[118:121], v[150:153], v[186:189], v[118:121]
	v_mfma_i32_16x16x64_i8 v[114:117], v[154:157], v[182:185], v[114:117]
	v_mfma_i32_16x16x64_i8 v[114:117], v[158:161], v[186:189], v[114:117]
	s_barrier
	s_setprio 2
	v_mfma_i32_16x16x64_i8 v[102:105], v[146:149], v[190:193], v[102:105]
	v_mfma_i32_16x16x64_i8 v[102:105], v[150:153], v[238:241], v[102:105]
	v_mfma_i32_16x16x64_i8 v[98:101], v[154:157], v[190:193], v[98:101]
	v_mfma_i32_16x16x64_i8 v[98:101], v[158:161], v[238:241], v[98:101]
	v_mfma_i32_16x16x64_i8 v[86:89], v[146:149], v[242:245], v[86:89]
	v_mfma_i32_16x16x64_i8 v[86:89], v[150:153], v[246:249], v[86:89]
	v_mfma_i32_16x16x64_i8 v[82:85], v[154:157], v[242:245], v[82:85]
	v_mfma_i32_16x16x64_i8 v[82:85], v[158:161], v[246:249], v[82:85]
	s_setprio 0
	s_add_i32 s72, s72, s21
	s_add_i32 s73, s72, 0x2000
	v_lshl_add_u64 v[166:167], v[166:167], 0, s[6:7]
	s_mov_b32 m0, s72
	s_add_u32 s14, s38, 0x80080
	ds_read_b128 v[174:177], v226 offset:49152
	ds_read_b128 v[178:181], v226 offset:50176
	ds_read_b128 v[182:185], v226 offset:51200
	ds_read_b128 v[186:189], v226 offset:52224
	ds_read_b128 v[190:193], v226 offset:53248
	ds_read_b128 v[238:241], v226 offset:54272
	ds_read_b128 v[242:245], v226 offset:55296
	ds_read_b128 v[246:249], v226 offset:56320
	global_load_lds_dwordx4 v[166:167], off
	v_lshl_add_u64 v[166:167], v[168:169], 0, s[6:7]
	s_mov_b32 m0, s73
	s_addc_u32 s15, s39, 0
	s_add_i32 s74, s74, s21
	global_load_lds_dwordx4 v[166:167], off
	v_lshl_add_u64 v[166:167], s[14:15], 0, v[202:203]
	s_mov_b32 m0, s74
	s_add_i32 s75, s74, 0x2000
	global_load_lds_dwordx4 v[166:167], off
	v_lshl_add_u64 v[166:167], s[14:15], 0, v[206:207]
	s_mov_b32 m0, s75
	s_nop 0
	global_load_lds_dwordx4 v[166:167], off
	v_lshl_add_u64 v[166:167], v[170:171], 0, s[6:7]
	s_mov_b32 m0, s51
	s_nop 0
	global_load_lds_dwordx4 v[166:167], off
	v_lshl_add_u64 v[166:167], v[172:173], 0, s[6:7]
	s_mov_b32 m0, s53
	s_nop 0
	global_load_lds_dwordx4 v[166:167], off
	s_waitcnt vmcnt(8)
	s_waitcnt lgkmcnt(0)
	s_barrier
	s_setprio 1
	s_waitcnt lgkmcnt(0)
	v_mfma_i32_16x16x64_i8 v[78:81], v[50:53], v[174:177], v[78:81]
	v_mfma_i32_16x16x64_i8 v[78:81], v[54:57], v[178:181], v[78:81]
	v_mfma_i32_16x16x64_i8 v[74:77], v[58:61], v[174:177], v[74:77]
	v_mfma_i32_16x16x64_i8 v[74:77], v[62:65], v[178:181], v[74:77]
	v_mfma_i32_16x16x64_i8 v[46:49], v[50:53], v[182:185], v[46:49]
	v_mfma_i32_16x16x64_i8 v[46:49], v[54:57], v[186:189], v[46:49]
	v_mfma_i32_16x16x64_i8 v[42:45], v[58:61], v[182:185], v[42:45]
	v_mfma_i32_16x16x64_i8 v[42:45], v[62:65], v[186:189], v[42:45]
	v_mfma_i32_16x16x64_i8 v[30:33], v[50:53], v[190:193], v[30:33]
	v_mfma_i32_16x16x64_i8 v[30:33], v[54:57], v[238:241], v[30:33]
	v_mfma_i32_16x16x64_i8 v[26:29], v[58:61], v[190:193], v[26:29]
	v_mfma_i32_16x16x64_i8 v[26:29], v[62:65], v[238:241], v[26:29]
	v_mfma_i32_16x16x64_i8 v[14:17], v[50:53], v[242:245], v[14:17]
	v_mfma_i32_16x16x64_i8 v[14:17], v[54:57], v[246:249], v[14:17]
	v_mfma_i32_16x16x64_i8 v[10:13], v[58:61], v[242:245], v[10:13]
	v_mfma_i32_16x16x64_i8 v[10:13], v[62:65], v[246:249], v[10:13]
	v_mfma_i32_16x16x64_i8 v[70:73], v[146:149], v[174:177], v[70:73]
	v_mfma_i32_16x16x64_i8 v[70:73], v[150:153], v[178:181], v[70:73]
	v_mfma_i32_16x16x64_i8 v[66:69], v[154:157], v[174:177], v[66:69]
	v_mfma_i32_16x16x64_i8 v[66:69], v[158:161], v[178:181], v[66:69]
	v_mfma_i32_16x16x64_i8 v[38:41], v[146:149], v[182:185], v[38:41]
	v_mfma_i32_16x16x64_i8 v[38:41], v[150:153], v[186:189], v[38:41]
	v_mfma_i32_16x16x64_i8 v[34:37], v[154:157], v[182:185], v[34:37]
	v_mfma_i32_16x16x64_i8 v[34:37], v[158:161], v[186:189], v[34:37]
	s_barrier
	s_setprio 2
	v_mfma_i32_16x16x64_i8 v[22:25], v[146:149], v[190:193], v[22:25]
	v_mfma_i32_16x16x64_i8 v[22:25], v[150:153], v[238:241], v[22:25]
	v_mfma_i32_16x16x64_i8 v[18:21], v[154:157], v[190:193], v[18:21]
	v_mfma_i32_16x16x64_i8 v[18:21], v[158:161], v[238:241], v[18:21]
	v_mfma_i32_16x16x64_i8 v[6:9], v[146:149], v[242:245], v[6:9]
	v_mfma_i32_16x16x64_i8 v[6:9], v[150:153], v[246:249], v[6:9]
	v_mfma_i32_16x16x64_i8 v[2:5], v[154:157], v[242:245], v[2:5]
	v_mfma_i32_16x16x64_i8 v[2:5], v[158:161], v[246:249], v[2:5]
	s_setprio 0
	s_add_i32 s3, s3, 2
	s_add_u32 s34, s34, 0x100
	s_addc_u32 s35, s35, 0
	s_cmp_gt_u32 s3, 29
	s_cbranch_scc0 .LBB0_734
	s_nop 15
	s_nop 15
	s_and_b64 vcc, exec, s[8:9]
	s_cbranch_vccz .LBB0_737
	s_barrier

.LBB0_740:
	ds_read_b128 v[158:161], v227
	ds_read_b128 v[154:157], v227 offset:1024
	ds_read_b128 v[150:153], v227 offset:2048
	ds_read_b128 v[146:149], v227 offset:3072
	ds_read_b128 v[62:65], v233
	ds_read_b128 v[58:61], v233 offset:1024
	ds_read_b128 v[54:57], v233 offset:2048
	ds_read_b128 v[50:53], v233 offset:3072
	s_add_u32 s36, s38, 0xfff80080
	s_addc_u32 s37, s39, -1
	s_cmp_eq_u32 s33, 28
	s_cselect_b32 s41, s1, s37
	s_cselect_b32 s40, s0, s36
	s_cselect_b32 s37, s15, s29
	s_cselect_b32 s36, s14, s25
	s_mov_b32 m0, s66
	v_lshl_add_u64 v[238:239], s[38:39], 0, v[208:209]
	ds_read_b128 v[162:165], v226
	ds_read_b128 v[166:169], v226 offset:1024
	ds_read_b128 v[170:173], v226 offset:2048
	ds_read_b128 v[174:177], v226 offset:3072
	ds_read_b128 v[178:181], v226 offset:4096
	ds_read_b128 v[182:185], v226 offset:5120
	ds_read_b128 v[186:189], v226 offset:6144
	ds_read_b128 v[190:193], v226 offset:7168
	global_load_lds_dwordx4 v[238:239], off
	v_lshl_add_u64 v[238:239], s[38:39], 0, v[212:213]
	s_mov_b32 m0, s67
	s_nop 0
	global_load_lds_dwordx4 v[238:239], off
	s_waitcnt vmcnt(8)
	s_waitcnt lgkmcnt(0)
	s_barrier
	s_setprio 1
	s_waitcnt lgkmcnt(0)
	v_mfma_i32_16x16x64_i8 v[142:145], v[158:161], v[162:165], v[142:145]
	v_mfma_i32_16x16x64_i8 v[142:145], v[154:157], v[166:169], v[142:145]
	v_mfma_i32_16x16x64_i8 v[138:141], v[150:153], v[162:165], v[138:141]
	v_mfma_i32_16x16x64_i8 v[138:141], v[146:149], v[166:169], v[138:141]
	v_mfma_i32_16x16x64_i8 v[126:129], v[158:161], v[170:173], v[126:129]
	v_mfma_i32_16x16x64_i8 v[126:129], v[154:157], v[174:177], v[126:129]
	v_mfma_i32_16x16x64_i8 v[122:125], v[150:153], v[170:173], v[122:125]
	v_mfma_i32_16x16x64_i8 v[122:125], v[146:149], v[174:177], v[122:125]
	v_mfma_i32_16x16x64_i8 v[110:113], v[158:161], v[178:181], v[110:113]
	v_mfma_i32_16x16x64_i8 v[110:113], v[154:157], v[182:185], v[110:113]
	v_mfma_i32_16x16x64_i8 v[106:109], v[150:153], v[178:181], v[106:109]
	v_mfma_i32_16x16x64_i8 v[106:109], v[146:149], v[182:185], v[106:109]
	v_mfma_i32_16x16x64_i8 v[94:97], v[158:161], v[186:189], v[94:97]
	v_mfma_i32_16x16x64_i8 v[94:97], v[154:157], v[190:193], v[94:97]
	v_mfma_i32_16x16x64_i8 v[90:93], v[150:153], v[186:189], v[90:93]
	v_mfma_i32_16x16x64_i8 v[90:93], v[146:149], v[190:193], v[90:93]
	v_mfma_i32_16x16x64_i8 v[134:137], v[62:65], v[162:165], v[134:137]
	v_mfma_i32_16x16x64_i8 v[134:137], v[58:61], v[166:169], v[134:137]
	v_mfma_i32_16x16x64_i8 v[130:133], v[54:57], v[162:165], v[130:133]
	v_mfma_i32_16x16x64_i8 v[130:133], v[50:53], v[166:169], v[130:133]
	v_mfma_i32_16x16x64_i8 v[118:121], v[62:65], v[170:173], v[118:121]
	v_mfma_i32_16x16x64_i8 v[118:121], v[58:61], v[174:177], v[118:121]
	v_mfma_i32_16x16x64_i8 v[114:117], v[54:57], v[170:173], v[114:117]
	v_mfma_i32_16x16x64_i8 v[114:117], v[50:53], v[174:177], v[114:117]
	s_barrier
	s_setprio 2
	v_mfma_i32_16x16x64_i8 v[102:105], v[62:65], v[178:181], v[102:105]
	v_mfma_i32_16x16x64_i8 v[102:105], v[58:61], v[182:185], v[102:105]
	v_mfma_i32_16x16x64_i8 v[98:101], v[54:57], v[178:181], v[98:101]
	v_mfma_i32_16x16x64_i8 v[98:101], v[50:53], v[182:185], v[98:101]
	v_mfma_i32_16x16x64_i8 v[86:89], v[62:65], v[186:189], v[86:89]
	v_mfma_i32_16x16x64_i8 v[86:89], v[58:61], v[190:193], v[86:89]
	v_mfma_i32_16x16x64_i8 v[82:85], v[54:57], v[186:189], v[82:85]
	v_mfma_i32_16x16x64_i8 v[82:85], v[50:53], v[190:193], v[82:85]
	s_setprio 0
	s_mov_b32 m0, s68
	v_lshl_add_u64 v[162:163], s[36:37], 0, v[202:203]
	s_add_u32 s80, s36, 0x80000
	ds_read_b128 v[170:173], v226 offset:16384
	ds_read_b128 v[174:177], v226 offset:17408
	ds_read_b128 v[178:181], v226 offset:18432
	ds_read_b128 v[182:185], v226 offset:19456
	ds_read_b128 v[186:189], v226 offset:20480
	ds_read_b128 v[190:193], v226 offset:21504
	ds_read_b128 v[238:241], v226 offset:22528
	ds_read_b128 v[242:245], v226 offset:23552
	global_load_lds_dwordx4 v[162:163], off
	v_lshl_add_u64 v[164:165], s[36:37], 0, v[206:207]
	s_mov_b32 m0, s69
	s_addc_u32 s81, s37, 0
	global_load_lds_dwordx4 v[164:165], off
	v_lshl_add_u64 v[166:167], s[80:81], 0, v[202:203]
	s_mov_b32 m0, s70
	v_lshl_add_u64 v[168:169], s[40:41], 0, v[204:205]
	global_load_lds_dwordx4 v[166:167], off
	v_lshl_add_u64 v[166:167], s[80:81], 0, v[206:207]
	s_mov_b32 m0, s71
	s_nop 0
	global_load_lds_dwordx4 v[166:167], off
	v_lshl_add_u64 v[166:167], s[40:41], 0, v[194:195]
	s_mov_b32 m0, s23
	s_nop 0
	global_load_lds_dwordx4 v[166:167], off
	s_mov_b32 m0, s42
	s_nop 0
	global_load_lds_dwordx4 v[168:169], off
	s_waitcnt vmcnt(8)
	s_waitcnt lgkmcnt(0)
	s_barrier
	s_setprio 1
	s_waitcnt lgkmcnt(0)
	v_mfma_i32_16x16x64_i8 v[78:81], v[158:161], v[170:173], v[78:81]
	v_mfma_i32_16x16x64_i8 v[78:81], v[154:157], v[174:177], v[78:81]
	v_mfma_i32_16x16x64_i8 v[74:77], v[150:153], v[170:173], v[74:77]
	v_mfma_i32_16x16x64_i8 v[74:77], v[146:149], v[174:177], v[74:77]
	v_mfma_i32_16x16x64_i8 v[46:49], v[158:161], v[178:181], v[46:49]
	v_mfma_i32_16x16x64_i8 v[46:49], v[154:157], v[182:185], v[46:49]
	v_mfma_i32_16x16x64_i8 v[42:45], v[150:153], v[178:181], v[42:45]
	v_mfma_i32_16x16x64_i8 v[42:45], v[146:149], v[182:185], v[42:45]
	v_mfma_i32_16x16x64_i8 v[30:33], v[158:161], v[186:189], v[30:33]
	v_mfma_i32_16x16x64_i8 v[30:33], v[154:157], v[190:193], v[30:33]
	v_mfma_i32_16x16x64_i8 v[26:29], v[150:153], v[186:189], v[26:29]
	v_mfma_i32_16x16x64_i8 v[26:29], v[146:149], v[190:193], v[26:29]
	v_mfma_i32_16x16x64_i8 v[14:17], v[158:161], v[238:241], v[14:17]
	v_mfma_i32_16x16x64_i8 v[14:17], v[154:157], v[242:245], v[14:17]
	v_mfma_i32_16x16x64_i8 v[10:13], v[150:153], v[238:241], v[10:13]
	v_mfma_i32_16x16x64_i8 v[10:13], v[146:149], v[242:245], v[10:13]
	v_mfma_i32_16x16x64_i8 v[70:73], v[62:65], v[170:173], v[70:73]
	v_mfma_i32_16x16x64_i8 v[70:73], v[58:61], v[174:177], v[70:73]
	v_mfma_i32_16x16x64_i8 v[66:69], v[54:57], v[170:173], v[66:69]
	v_mfma_i32_16x16x64_i8 v[66:69], v[50:53], v[174:177], v[66:69]
	v_mfma_i32_16x16x64_i8 v[38:41], v[62:65], v[178:181], v[38:41]
	v_mfma_i32_16x16x64_i8 v[38:41], v[58:61], v[182:185], v[38:41]
	v_mfma_i32_16x16x64_i8 v[34:37], v[54:57], v[178:181], v[34:37]
	v_mfma_i32_16x16x64_i8 v[34:37], v[50:53], v[182:185], v[34:37]
	s_barrier
	s_setprio 2
	v_mfma_i32_16x16x64_i8 v[22:25], v[62:65], v[186:189], v[22:25]
	v_mfma_i32_16x16x64_i8 v[22:25], v[58:61], v[190:193], v[22:25]
	v_mfma_i32_16x16x64_i8 v[18:21], v[54:57], v[186:189], v[18:21]
	v_mfma_i32_16x16x64_i8 v[18:21], v[50:53], v[190:193], v[18:21]
	v_mfma_i32_16x16x64_i8 v[6:9], v[62:65], v[238:241], v[6:9]
	v_mfma_i32_16x16x64_i8 v[6:9], v[58:61], v[242:245], v[6:9]
	v_mfma_i32_16x16x64_i8 v[2:5], v[54:57], v[238:241], v[2:5]
	v_mfma_i32_16x16x64_i8 v[2:5], v[50:53], v[242:245], v[2:5]
	s_setprio 0
	ds_read_b128 v[50:53], v235
	ds_read_b128 v[54:57], v235 offset:1024
	ds_read_b128 v[58:61], v235 offset:2048
	ds_read_b128 v[62:65], v235 offset:3072
	ds_read_b128 v[146:149], v236
	ds_read_b128 v[150:153], v236 offset:1024
	ds_read_b128 v[154:157], v236 offset:2048
	ds_read_b128 v[158:161], v236 offset:3072
	s_add_u32 s40, s40, 0x80000
	s_addc_u32 s41, s41, 0
	s_mov_b32 m0, s43
	v_lshl_add_u64 v[246:247], s[40:41], 0, v[194:195]
	ds_read_b128 v[170:173], v226 offset:32768
	ds_read_b128 v[174:177], v226 offset:33792
	ds_read_b128 v[178:181], v226 offset:34816
	ds_read_b128 v[182:185], v226 offset:35840
	ds_read_b128 v[186:189], v226 offset:36864
	ds_read_b128 v[190:193], v226 offset:37888
	ds_read_b128 v[238:241], v226 offset:38912
	ds_read_b128 v[242:245], v226 offset:39936
	global_load_lds_dwordx4 v[246:247], off
	v_lshl_add_u64 v[246:247], s[40:41], 0, v[204:205]
	s_mov_b32 m0, s44
	s_nop 0
	global_load_lds_dwordx4 v[246:247], off
	s_waitcnt vmcnt(8)
	s_waitcnt lgkmcnt(0)
	s_barrier
	s_setprio 1
	s_waitcnt lgkmcnt(0)
	v_mfma_i32_16x16x64_i8 v[142:145], v[50:53], v[170:173], v[142:145]
	v_mfma_i32_16x16x64_i8 v[142:145], v[54:57], v[174:177], v[142:145]
	v_mfma_i32_16x16x64_i8 v[138:141], v[58:61], v[170:173], v[138:141]
	v_mfma_i32_16x16x64_i8 v[138:141], v[62:65], v[174:177], v[138:141]
	v_mfma_i32_16x16x64_i8 v[126:129], v[50:53], v[178:181], v[126:129]
	v_mfma_i32_16x16x64_i8 v[126:129], v[54:57], v[182:185], v[126:129]
	v_mfma_i32_16x16x64_i8 v[122:125], v[58:61], v[178:181], v[122:125]
	v_mfma_i32_16x16x64_i8 v[122:125], v[62:65], v[182:185], v[122:125]
	v_mfma_i32_16x16x64_i8 v[110:113], v[50:53], v[186:189], v[110:113]
	v_mfma_i32_16x16x64_i8 v[110:113], v[54:57], v[190:193], v[110:113]
	v_mfma_i32_16x16x64_i8 v[106:109], v[58:61], v[186:189], v[106:109]
	v_mfma_i32_16x16x64_i8 v[106:109], v[62:65], v[190:193], v[106:109]
	v_mfma_i32_16x16x64_i8 v[94:97], v[50:53], v[238:241], v[94:97]
	v_mfma_i32_16x16x64_i8 v[94:97], v[54:57], v[242:245], v[94:97]
	v_mfma_i32_16x16x64_i8 v[90:93], v[58:61], v[238:241], v[90:93]
	v_mfma_i32_16x16x64_i8 v[90:93], v[62:65], v[242:245], v[90:93]
	v_mfma_i32_16x16x64_i8 v[134:137], v[146:149], v[170:173], v[134:137]
	v_mfma_i32_16x16x64_i8 v[134:137], v[150:153], v[174:177], v[134:137]
	v_mfma_i32_16x16x64_i8 v[130:133], v[154:157], v[170:173], v[130:133]
	v_mfma_i32_16x16x64_i8 v[130:133], v[158:161], v[174:177], v[130:133]
	v_mfma_i32_16x16x64_i8 v[118:121], v[146:149], v[178:181], v[118:121]
	v_mfma_i32_16x16x64_i8 v[118:121], v[150:153], v[182:185], v[118:121]
	v_mfma_i32_16x16x64_i8 v[114:117], v[154:157], v[178:181], v[114:117]
	v_mfma_i32_16x16x64_i8 v[114:117], v[158:161], v[182:185], v[114:117]
	s_barrier
	s_setprio 2
	v_mfma_i32_16x16x64_i8 v[102:105], v[146:149], v[186:189], v[102:105]
	v_mfma_i32_16x16x64_i8 v[102:105], v[150:153], v[190:193], v[102:105]
	v_mfma_i32_16x16x64_i8 v[98:101], v[154:157], v[186:189], v[98:101]
	v_mfma_i32_16x16x64_i8 v[98:101], v[158:161], v[190:193], v[98:101]
	v_mfma_i32_16x16x64_i8 v[86:89], v[146:149], v[238:241], v[86:89]
	v_mfma_i32_16x16x64_i8 v[86:89], v[150:153], v[242:245], v[86:89]
	v_mfma_i32_16x16x64_i8 v[82:85], v[154:157], v[238:241], v[82:85]
	v_mfma_i32_16x16x64_i8 v[82:85], v[158:161], v[242:245], v[82:85]
	s_setprio 0
	s_mov_b32 m0, s72
	v_lshl_add_u64 v[162:163], v[162:163], 0, s[6:7]
	s_add_u32 s36, s36, 0x80080
	ds_read_b128 v[170:173], v226 offset:49152
	ds_read_b128 v[174:177], v226 offset:50176
	ds_read_b128 v[178:181], v226 offset:51200
	ds_read_b128 v[182:185], v226 offset:52224
	ds_read_b128 v[186:189], v226 offset:53248
	ds_read_b128 v[190:193], v226 offset:54272
	ds_read_b128 v[238:241], v226 offset:55296
	ds_read_b128 v[242:245], v226 offset:56320
	global_load_lds_dwordx4 v[162:163], off
	v_lshl_add_u64 v[162:163], v[164:165], 0, s[6:7]
	s_mov_b32 m0, s73
	s_addc_u32 s37, s37, 0
	global_load_lds_dwordx4 v[162:163], off
	v_lshl_add_u64 v[162:163], s[36:37], 0, v[202:203]
	s_mov_b32 m0, s74
	s_nop 0
	global_load_lds_dwordx4 v[162:163], off
	v_lshl_add_u64 v[162:163], s[36:37], 0, v[206:207]
	s_mov_b32 m0, s75
	s_nop 0
	global_load_lds_dwordx4 v[162:163], off
	v_lshl_add_u64 v[162:163], v[166:167], 0, s[6:7]
	s_mov_b32 m0, s51
	s_nop 0
	global_load_lds_dwordx4 v[162:163], off
	v_lshl_add_u64 v[162:163], v[168:169], 0, s[6:7]
	s_mov_b32 m0, s53
	s_nop 0
	global_load_lds_dwordx4 v[162:163], off
	s_waitcnt vmcnt(8)
	s_waitcnt lgkmcnt(0)
	s_barrier
	s_setprio 1
	s_waitcnt lgkmcnt(0)
	v_mfma_i32_16x16x64_i8 v[78:81], v[50:53], v[170:173], v[78:81]
	v_mfma_i32_16x16x64_i8 v[78:81], v[54:57], v[174:177], v[78:81]
	v_mfma_i32_16x16x64_i8 v[74:77], v[58:61], v[170:173], v[74:77]
	v_mfma_i32_16x16x64_i8 v[74:77], v[62:65], v[174:177], v[74:77]
	v_mfma_i32_16x16x64_i8 v[46:49], v[50:53], v[178:181], v[46:49]
	v_mfma_i32_16x16x64_i8 v[46:49], v[54:57], v[182:185], v[46:49]
	v_mfma_i32_16x16x64_i8 v[42:45], v[58:61], v[178:181], v[42:45]
	v_mfma_i32_16x16x64_i8 v[42:45], v[62:65], v[182:185], v[42:45]
	v_mfma_i32_16x16x64_i8 v[30:33], v[50:53], v[186:189], v[30:33]
	v_mfma_i32_16x16x64_i8 v[30:33], v[54:57], v[190:193], v[30:33]
	v_mfma_i32_16x16x64_i8 v[26:29], v[58:61], v[186:189], v[26:29]
	v_mfma_i32_16x16x64_i8 v[26:29], v[62:65], v[190:193], v[26:29]
	v_mfma_i32_16x16x64_i8 v[14:17], v[50:53], v[238:241], v[14:17]
	v_mfma_i32_16x16x64_i8 v[14:17], v[54:57], v[242:245], v[14:17]
	v_mfma_i32_16x16x64_i8 v[10:13], v[58:61], v[238:241], v[10:13]
	v_mfma_i32_16x16x64_i8 v[10:13], v[62:65], v[242:245], v[10:13]
	v_mfma_i32_16x16x64_i8 v[70:73], v[146:149], v[170:173], v[70:73]
	v_mfma_i32_16x16x64_i8 v[70:73], v[150:153], v[174:177], v[70:73]
	v_mfma_i32_16x16x64_i8 v[66:69], v[154:157], v[170:173], v[66:69]
	v_mfma_i32_16x16x64_i8 v[66:69], v[158:161], v[174:177], v[66:69]
	v_mfma_i32_16x16x64_i8 v[38:41], v[146:149], v[178:181], v[38:41]
	v_mfma_i32_16x16x64_i8 v[38:41], v[150:153], v[182:185], v[38:41]
	v_mfma_i32_16x16x64_i8 v[34:37], v[154:157], v[178:181], v[34:37]
	v_mfma_i32_16x16x64_i8 v[34:37], v[158:161], v[182:185], v[34:37]
	s_barrier
	s_setprio 2
	v_mfma_i32_16x16x64_i8 v[22:25], v[146:149], v[186:189], v[22:25]
	v_mfma_i32_16x16x64_i8 v[22:25], v[150:153], v[190:193], v[22:25]
	v_mfma_i32_16x16x64_i8 v[18:21], v[154:157], v[186:189], v[18:21]
	v_mfma_i32_16x16x64_i8 v[18:21], v[158:161], v[190:193], v[18:21]
	v_mfma_i32_16x16x64_i8 v[6:9], v[146:149], v[238:241], v[6:9]
	v_mfma_i32_16x16x64_i8 v[6:9], v[150:153], v[242:245], v[6:9]
	v_mfma_i32_16x16x64_i8 v[2:5], v[154:157], v[238:241], v[2:5]
	v_mfma_i32_16x16x64_i8 v[2:5], v[158:161], v[242:245], v[2:5]
	s_setprio 0
	s_add_i32 s33, s33, 2
	s_add_u32 s38, s38, 0x100
	s_addc_u32 s39, s39, 0
	s_add_u32 s25, s25, 0x100
	s_addc_u32 s29, s29, 0
	s_cmp_gt_u32 s33, 29
	s_cbranch_scc0 .LBB0_740
	s_nop 15
	s_nop 15
	s_and_b64 vcc, exec, s[8:9]
	s_cbranch_vccz .LBB0_743
	s_barrier

.LBB0_746:
	ds_read_b128 v[158:161], v227
	ds_read_b128 v[154:157], v227 offset:1024
	ds_read_b128 v[150:153], v227 offset:2048
	ds_read_b128 v[146:149], v227 offset:3072
	ds_read_b128 v[142:145], v233
	ds_read_b128 v[138:141], v233 offset:1024
	ds_read_b128 v[134:137], v233 offset:2048
	ds_read_b128 v[130:133], v233 offset:3072
	s_add_u32 s38, s29, s36
	s_addc_u32 s39, s33, s37
	s_add_u32 s38, s38, 0x3d000100
	s_addc_u32 s39, s39, 0
	s_add_u32 s81, s25, s36
	s_addc_u32 s82, s79, s37
	s_cmpk_eq_i32 s36, 0x700
	s_cselect_b32 s41, s1, s39
	s_cselect_b32 s40, s0, s38
	s_cselect_b32 s39, s15, s82
	s_cselect_b32 s38, s14, s81
	s_mov_b32 m0, s66
	v_lshl_add_u64 v[242:243], v[162:163], 0, s[36:37]
	ds_read_b128 v[166:169], v226
	ds_read_b128 v[170:173], v226 offset:1024
	ds_read_b128 v[174:177], v226 offset:2048
	ds_read_b128 v[178:181], v226 offset:3072
	ds_read_b128 v[182:185], v226 offset:4096
	ds_read_b128 v[186:189], v226 offset:5120
	ds_read_b128 v[190:193], v226 offset:6144
	ds_read_b128 v[238:241], v226 offset:7168
	global_load_lds_dwordx4 v[242:243], off
	v_lshl_add_u64 v[242:243], v[164:165], 0, s[36:37]
	s_mov_b32 m0, s67
	s_nop 0
	global_load_lds_dwordx4 v[242:243], off
	s_waitcnt vmcnt(8)
	s_waitcnt lgkmcnt(0)
	s_barrier
	s_setprio 1
	s_waitcnt lgkmcnt(0)
	v_mfma_i32_16x16x64_i8 v[30:33], v[158:161], v[166:169], v[30:33]
	v_mfma_i32_16x16x64_i8 v[30:33], v[154:157], v[170:173], v[30:33]
	v_mfma_i32_16x16x64_i8 v[26:29], v[150:153], v[166:169], v[26:29]
	v_mfma_i32_16x16x64_i8 v[26:29], v[146:149], v[170:173], v[26:29]
	v_mfma_i32_16x16x64_i8 v[46:49], v[158:161], v[174:177], v[46:49]
	v_mfma_i32_16x16x64_i8 v[46:49], v[154:157], v[178:181], v[46:49]
	v_mfma_i32_16x16x64_i8 v[42:45], v[150:153], v[174:177], v[42:45]
	v_mfma_i32_16x16x64_i8 v[42:45], v[146:149], v[178:181], v[42:45]
	v_mfma_i32_16x16x64_i8 v[74:77], v[158:161], v[182:185], v[74:77]
	v_mfma_i32_16x16x64_i8 v[74:77], v[154:157], v[186:189], v[74:77]
	v_mfma_i32_16x16x64_i8 v[70:73], v[150:153], v[182:185], v[70:73]
	v_mfma_i32_16x16x64_i8 v[70:73], v[146:149], v[186:189], v[70:73]
	v_mfma_i32_16x16x64_i8 v[94:97], v[158:161], v[190:193], v[94:97]
	v_mfma_i32_16x16x64_i8 v[94:97], v[154:157], v[238:241], v[94:97]
	v_mfma_i32_16x16x64_i8 v[90:93], v[150:153], v[190:193], v[90:93]
	v_mfma_i32_16x16x64_i8 v[90:93], v[146:149], v[238:241], v[90:93]
	v_mfma_i32_16x16x64_i8 v[38:41], v[142:145], v[166:169], v[38:41]
	v_mfma_i32_16x16x64_i8 v[38:41], v[138:141], v[170:173], v[38:41]
	v_mfma_i32_16x16x64_i8 v[34:37], v[134:137], v[166:169], v[34:37]
	v_mfma_i32_16x16x64_i8 v[34:37], v[130:133], v[170:173], v[34:37]
	v_mfma_i32_16x16x64_i8 v[58:61], v[142:145], v[174:177], v[58:61]
	v_mfma_i32_16x16x64_i8 v[58:61], v[138:141], v[178:181], v[58:61]
	v_mfma_i32_16x16x64_i8 v[54:57], v[134:137], v[174:177], v[54:57]
	v_mfma_i32_16x16x64_i8 v[54:57], v[130:133], v[178:181], v[54:57]
	s_barrier
	s_setprio 2
	v_mfma_i32_16x16x64_i8 v[86:89], v[142:145], v[182:185], v[86:89]
	v_mfma_i32_16x16x64_i8 v[86:89], v[138:141], v[186:189], v[86:89]
	v_mfma_i32_16x16x64_i8 v[82:85], v[134:137], v[182:185], v[82:85]
	v_mfma_i32_16x16x64_i8 v[82:85], v[130:133], v[186:189], v[82:85]
	v_mfma_i32_16x16x64_i8 v[102:105], v[142:145], v[190:193], v[102:105]
	v_mfma_i32_16x16x64_i8 v[102:105], v[138:141], v[238:241], v[102:105]
	v_mfma_i32_16x16x64_i8 v[98:101], v[134:137], v[190:193], v[98:101]
	v_mfma_i32_16x16x64_i8 v[98:101], v[130:133], v[238:241], v[98:101]
	s_setprio 0
	s_mov_b32 m0, s68
	v_lshl_add_u64 v[166:167], s[38:39], 0, v[202:203]
	s_add_u32 s82, s38, 0x80000
	ds_read_b128 v[174:177], v226 offset:16384
	ds_read_b128 v[178:181], v226 offset:17408
	ds_read_b128 v[182:185], v226 offset:18432
	ds_read_b128 v[186:189], v226 offset:19456
	ds_read_b128 v[190:193], v226 offset:20480
	ds_read_b128 v[238:241], v226 offset:21504
	ds_read_b128 v[242:245], v226 offset:22528
	ds_read_b128 v[246:249], v226 offset:23552
	global_load_lds_dwordx4 v[166:167], off
	v_lshl_add_u64 v[168:169], s[38:39], 0, v[206:207]
	s_mov_b32 m0, s69
	s_addc_u32 s83, s39, 0
	global_load_lds_dwordx4 v[168:169], off
	v_lshl_add_u64 v[170:171], s[82:83], 0, v[202:203]
	s_mov_b32 m0, s70
	v_lshl_add_u64 v[172:173], s[40:41], 0, v[204:205]
	global_load_lds_dwordx4 v[170:171], off
	v_lshl_add_u64 v[170:171], s[82:83], 0, v[206:207]
	s_mov_b32 m0, s71
	s_nop 0
	global_load_lds_dwordx4 v[170:171], off
	v_lshl_add_u64 v[170:171], s[40:41], 0, v[194:195]
	s_mov_b32 m0, s23
	s_nop 0
	global_load_lds_dwordx4 v[170:171], off
	s_mov_b32 m0, s42
	s_nop 0
	global_load_lds_dwordx4 v[172:173], off
	s_waitcnt vmcnt(8)
	s_waitcnt lgkmcnt(0)
	s_barrier
	s_setprio 1
	s_waitcnt lgkmcnt(0)
	v_mfma_i32_16x16x64_i8 v[110:113], v[158:161], v[174:177], v[110:113]
	v_mfma_i32_16x16x64_i8 v[110:113], v[154:157], v[178:181], v[110:113]
	v_mfma_i32_16x16x64_i8 v[106:109], v[150:153], v[174:177], v[106:109]
	v_mfma_i32_16x16x64_i8 v[106:109], v[146:149], v[178:181], v[106:109]
	v_mfma_i32_16x16x64_i8 v[126:129], v[158:161], v[182:185], v[126:129]
	v_mfma_i32_16x16x64_i8 v[126:129], v[154:157], v[186:189], v[126:129]
	v_mfma_i32_16x16x64_i8 v[118:121], v[150:153], v[182:185], v[118:121]
	v_mfma_i32_16x16x64_i8 v[118:121], v[146:149], v[186:189], v[118:121]
	v_mfma_i32_16x16x64_i8 v[62:65], v[158:161], v[190:193], v[62:65]
	v_mfma_i32_16x16x64_i8 v[62:65], v[154:157], v[238:241], v[62:65]
	v_mfma_i32_16x16x64_i8 v[50:53], v[150:153], v[190:193], v[50:53]
	v_mfma_i32_16x16x64_i8 v[50:53], v[146:149], v[238:241], v[50:53]
	v_mfma_i32_16x16x64_i8 v[14:17], v[158:161], v[242:245], v[14:17]
	v_mfma_i32_16x16x64_i8 v[14:17], v[154:157], v[246:249], v[14:17]
	v_mfma_i32_16x16x64_i8 v[10:13], v[150:153], v[242:245], v[10:13]
	v_mfma_i32_16x16x64_i8 v[10:13], v[146:149], v[246:249], v[10:13]
	v_mfma_i32_16x16x64_i8 v[122:125], v[142:145], v[174:177], v[122:125]
	v_mfma_i32_16x16x64_i8 v[122:125], v[138:141], v[178:181], v[122:125]
	v_mfma_i32_16x16x64_i8 v[114:117], v[134:137], v[174:177], v[114:117]
	v_mfma_i32_16x16x64_i8 v[114:117], v[130:133], v[178:181], v[114:117]
	v_mfma_i32_16x16x64_i8 v[78:81], v[142:145], v[182:185], v[78:81]
	v_mfma_i32_16x16x64_i8 v[78:81], v[138:141], v[186:189], v[78:81]
	v_mfma_i32_16x16x64_i8 v[66:69], v[134:137], v[182:185], v[66:69]
	v_mfma_i32_16x16x64_i8 v[66:69], v[130:133], v[186:189], v[66:69]
	s_barrier
	s_setprio 2
	v_mfma_i32_16x16x64_i8 v[22:25], v[142:145], v[190:193], v[22:25]
	v_mfma_i32_16x16x64_i8 v[22:25], v[138:141], v[238:241], v[22:25]
	v_mfma_i32_16x16x64_i8 v[18:21], v[134:137], v[190:193], v[18:21]
	v_mfma_i32_16x16x64_i8 v[18:21], v[130:133], v[238:241], v[18:21]
	v_mfma_i32_16x16x64_i8 v[6:9], v[142:145], v[242:245], v[6:9]
	v_mfma_i32_16x16x64_i8 v[6:9], v[138:141], v[246:249], v[6:9]
	v_mfma_i32_16x16x64_i8 v[2:5], v[134:137], v[242:245], v[2:5]
	v_mfma_i32_16x16x64_i8 v[2:5], v[130:133], v[246:249], v[2:5]
	s_setprio 0
	ds_read_b128 v[130:133], v235
	ds_read_b128 v[134:137], v235 offset:1024
	ds_read_b128 v[138:141], v235 offset:2048
	ds_read_b128 v[142:145], v235 offset:3072
	ds_read_b128 v[146:149], v236
	ds_read_b128 v[150:153], v236 offset:1024
	ds_read_b128 v[154:157], v236 offset:2048
	ds_read_b128 v[158:161], v236 offset:3072
	s_add_u32 s40, s40, 0x80000
	s_addc_u32 s41, s41, 0
	s_mov_b32 m0, s43
	v_lshl_add_u64 v[250:251], s[40:41], 0, v[194:195]
	ds_read_b128 v[174:177], v226 offset:32768
	ds_read_b128 v[178:181], v226 offset:33792
	ds_read_b128 v[182:185], v226 offset:34816
	ds_read_b128 v[186:189], v226 offset:35840
	ds_read_b128 v[190:193], v226 offset:36864
	ds_read_b128 v[238:241], v226 offset:37888
	ds_read_b128 v[242:245], v226 offset:38912
	ds_read_b128 v[246:249], v226 offset:39936
	global_load_lds_dwordx4 v[250:251], off
	v_lshl_add_u64 v[250:251], s[40:41], 0, v[204:205]
	s_mov_b32 m0, s44
	s_nop 0
	global_load_lds_dwordx4 v[250:251], off
	s_waitcnt vmcnt(8)
	s_waitcnt lgkmcnt(0)
	s_barrier
	s_setprio 1
	s_waitcnt lgkmcnt(0)
	v_mfma_i32_16x16x64_i8 v[30:33], v[130:133], v[174:177], v[30:33]
	v_mfma_i32_16x16x64_i8 v[30:33], v[134:137], v[178:181], v[30:33]
	v_mfma_i32_16x16x64_i8 v[26:29], v[138:141], v[174:177], v[26:29]
	v_mfma_i32_16x16x64_i8 v[26:29], v[142:145], v[178:181], v[26:29]
	v_mfma_i32_16x16x64_i8 v[46:49], v[130:133], v[182:185], v[46:49]
	v_mfma_i32_16x16x64_i8 v[46:49], v[134:137], v[186:189], v[46:49]
	v_mfma_i32_16x16x64_i8 v[42:45], v[138:141], v[182:185], v[42:45]
	v_mfma_i32_16x16x64_i8 v[42:45], v[142:145], v[186:189], v[42:45]
	v_mfma_i32_16x16x64_i8 v[74:77], v[130:133], v[190:193], v[74:77]
	v_mfma_i32_16x16x64_i8 v[74:77], v[134:137], v[238:241], v[74:77]
	v_mfma_i32_16x16x64_i8 v[70:73], v[138:141], v[190:193], v[70:73]
	v_mfma_i32_16x16x64_i8 v[70:73], v[142:145], v[238:241], v[70:73]
	v_mfma_i32_16x16x64_i8 v[94:97], v[130:133], v[242:245], v[94:97]
	v_mfma_i32_16x16x64_i8 v[94:97], v[134:137], v[246:249], v[94:97]
	v_mfma_i32_16x16x64_i8 v[90:93], v[138:141], v[242:245], v[90:93]
	v_mfma_i32_16x16x64_i8 v[90:93], v[142:145], v[246:249], v[90:93]
	v_mfma_i32_16x16x64_i8 v[38:41], v[146:149], v[174:177], v[38:41]
	v_mfma_i32_16x16x64_i8 v[38:41], v[150:153], v[178:181], v[38:41]
	v_mfma_i32_16x16x64_i8 v[34:37], v[154:157], v[174:177], v[34:37]
	v_mfma_i32_16x16x64_i8 v[34:37], v[158:161], v[178:181], v[34:37]
	v_mfma_i32_16x16x64_i8 v[58:61], v[146:149], v[182:185], v[58:61]
	v_mfma_i32_16x16x64_i8 v[58:61], v[150:153], v[186:189], v[58:61]
	v_mfma_i32_16x16x64_i8 v[54:57], v[154:157], v[182:185], v[54:57]
	v_mfma_i32_16x16x64_i8 v[54:57], v[158:161], v[186:189], v[54:57]
	s_barrier
	s_setprio 2
	v_mfma_i32_16x16x64_i8 v[86:89], v[146:149], v[190:193], v[86:89]
	v_mfma_i32_16x16x64_i8 v[86:89], v[150:153], v[238:241], v[86:89]
	v_mfma_i32_16x16x64_i8 v[82:85], v[154:157], v[190:193], v[82:85]
	v_mfma_i32_16x16x64_i8 v[82:85], v[158:161], v[238:241], v[82:85]
	v_mfma_i32_16x16x64_i8 v[102:105], v[146:149], v[242:245], v[102:105]
	v_mfma_i32_16x16x64_i8 v[102:105], v[150:153], v[246:249], v[102:105]
	v_mfma_i32_16x16x64_i8 v[98:101], v[154:157], v[242:245], v[98:101]
	v_mfma_i32_16x16x64_i8 v[98:101], v[158:161], v[246:249], v[98:101]
	s_setprio 0
	s_mov_b32 m0, s72
	v_lshl_add_u64 v[166:167], v[166:167], 0, s[6:7]
	s_add_u32 s38, s38, 0x80080
	ds_read_b128 v[174:177], v226 offset:49152
	ds_read_b128 v[178:181], v226 offset:50176
	ds_read_b128 v[182:185], v226 offset:51200
	ds_read_b128 v[186:189], v226 offset:52224
	ds_read_b128 v[190:193], v226 offset:53248
	ds_read_b128 v[238:241], v226 offset:54272
	ds_read_b128 v[242:245], v226 offset:55296
	ds_read_b128 v[246:249], v226 offset:56320
	global_load_lds_dwordx4 v[166:167], off
	v_lshl_add_u64 v[166:167], v[168:169], 0, s[6:7]
	s_mov_b32 m0, s73
	s_addc_u32 s39, s39, 0
	global_load_lds_dwordx4 v[166:167], off
	v_lshl_add_u64 v[166:167], s[38:39], 0, v[202:203]
	s_mov_b32 m0, s74
	s_nop 0
	global_load_lds_dwordx4 v[166:167], off
	v_lshl_add_u64 v[166:167], s[38:39], 0, v[206:207]
	s_mov_b32 m0, s75
	s_nop 0
	global_load_lds_dwordx4 v[166:167], off
	v_lshl_add_u64 v[166:167], v[170:171], 0, s[6:7]
	s_mov_b32 m0, s51
	s_nop 0
	global_load_lds_dwordx4 v[166:167], off
	v_lshl_add_u64 v[166:167], v[172:173], 0, s[6:7]
	s_mov_b32 m0, s53
	s_nop 0
	global_load_lds_dwordx4 v[166:167], off
	s_waitcnt vmcnt(8)
	s_waitcnt lgkmcnt(0)
	s_barrier
	s_setprio 1
	s_waitcnt lgkmcnt(0)
	v_mfma_i32_16x16x64_i8 v[110:113], v[130:133], v[174:177], v[110:113]
	v_mfma_i32_16x16x64_i8 v[110:113], v[134:137], v[178:181], v[110:113]
	v_mfma_i32_16x16x64_i8 v[106:109], v[138:141], v[174:177], v[106:109]
	v_mfma_i32_16x16x64_i8 v[106:109], v[142:145], v[178:181], v[106:109]
	v_mfma_i32_16x16x64_i8 v[126:129], v[130:133], v[182:185], v[126:129]
	v_mfma_i32_16x16x64_i8 v[126:129], v[134:137], v[186:189], v[126:129]
	v_mfma_i32_16x16x64_i8 v[118:121], v[138:141], v[182:185], v[118:121]
	v_mfma_i32_16x16x64_i8 v[118:121], v[142:145], v[186:189], v[118:121]
	v_mfma_i32_16x16x64_i8 v[62:65], v[130:133], v[190:193], v[62:65]
	v_mfma_i32_16x16x64_i8 v[62:65], v[134:137], v[238:241], v[62:65]
	v_mfma_i32_16x16x64_i8 v[50:53], v[138:141], v[190:193], v[50:53]
	v_mfma_i32_16x16x64_i8 v[50:53], v[142:145], v[238:241], v[50:53]
	v_mfma_i32_16x16x64_i8 v[14:17], v[130:133], v[242:245], v[14:17]
	v_mfma_i32_16x16x64_i8 v[14:17], v[134:137], v[246:249], v[14:17]
	v_mfma_i32_16x16x64_i8 v[10:13], v[138:141], v[242:245], v[10:13]
	v_mfma_i32_16x16x64_i8 v[10:13], v[142:145], v[246:249], v[10:13]
	v_mfma_i32_16x16x64_i8 v[122:125], v[146:149], v[174:177], v[122:125]
	v_mfma_i32_16x16x64_i8 v[122:125], v[150:153], v[178:181], v[122:125]
	v_mfma_i32_16x16x64_i8 v[114:117], v[154:157], v[174:177], v[114:117]
	v_mfma_i32_16x16x64_i8 v[114:117], v[158:161], v[178:181], v[114:117]
	v_mfma_i32_16x16x64_i8 v[78:81], v[146:149], v[182:185], v[78:81]
	v_mfma_i32_16x16x64_i8 v[78:81], v[150:153], v[186:189], v[78:81]
	v_mfma_i32_16x16x64_i8 v[66:69], v[154:157], v[182:185], v[66:69]
	v_mfma_i32_16x16x64_i8 v[66:69], v[158:161], v[186:189], v[66:69]
	s_barrier
	s_setprio 2
	v_mfma_i32_16x16x64_i8 v[22:25], v[146:149], v[190:193], v[22:25]
	v_mfma_i32_16x16x64_i8 v[22:25], v[150:153], v[238:241], v[22:25]
	v_mfma_i32_16x16x64_i8 v[18:21], v[154:157], v[190:193], v[18:21]
	v_mfma_i32_16x16x64_i8 v[18:21], v[158:161], v[238:241], v[18:21]
	v_mfma_i32_16x16x64_i8 v[6:9], v[146:149], v[242:245], v[6:9]
	v_mfma_i32_16x16x64_i8 v[6:9], v[150:153], v[246:249], v[6:9]
	v_mfma_i32_16x16x64_i8 v[2:5], v[154:157], v[242:245], v[2:5]
	v_mfma_i32_16x16x64_i8 v[2:5], v[158:161], v[246:249], v[2:5]
	s_setprio 0
	s_add_i32 s80, s80, 2
	s_add_u32 s36, s36, 0x100
	s_addc_u32 s37, s37, 0
	s_cmp_gt_u32 s80, 13
	s_cbranch_scc0 .LBB0_746
	s_nop 15
	s_nop 15
	s_and_b64 vcc, exec, s[8:9]
	s_cbranch_vccz .LBB0_749
	s_barrier

.LBB0_752:
	ds_read_b128 v[134:137], v227
	ds_read_b128 v[138:141], v227 offset:1024
	ds_read_b128 v[142:145], v227 offset:2048
	ds_read_b128 v[146:149], v227 offset:3072
	ds_read_b128 v[150:153], v233
	ds_read_b128 v[154:157], v233 offset:1024
	ds_read_b128 v[158:161], v233 offset:2048
	ds_read_b128 v[162:165], v233 offset:3072
	s_add_u32 s30, s29, s2
	s_addc_u32 s31, s33, s3
	s_add_u32 s30, s30, 0x200100
	s_addc_u32 s31, s31, 0
	s_add_u32 s77, s25, s2
	s_addc_u32 s78, s40, s3
	s_cmpk_eq_i32 s2, 0xf00
	s_cselect_b32 s35, s0, s31
	s_cselect_b32 s34, s1, s30
	s_cselect_b32 s31, s14, s78
	s_cselect_b32 s30, s15, s77
	s_mov_b32 m0, s66
	v_lshl_add_u64 v[242:243], v[130:131], 0, s[2:3]
	ds_read_b128 v[166:169], v226
	ds_read_b128 v[170:173], v226 offset:1024
	ds_read_b128 v[174:177], v226 offset:2048
	ds_read_b128 v[178:181], v226 offset:3072
	ds_read_b128 v[182:185], v226 offset:4096
	ds_read_b128 v[186:189], v226 offset:5120
	ds_read_b128 v[190:193], v226 offset:6144
	ds_read_b128 v[238:241], v226 offset:7168
	global_load_lds_dwordx4 v[242:243], off
	v_lshl_add_u64 v[242:243], v[132:133], 0, s[2:3]
	s_mov_b32 m0, s67
	s_nop 0
	global_load_lds_dwordx4 v[242:243], off
	s_waitcnt vmcnt(8)
	s_waitcnt lgkmcnt(0)
	s_barrier
	s_setprio 1
	s_waitcnt lgkmcnt(0)
	v_mfma_f32_16x16x32_bf16 v[26:29], v[134:137], v[166:169], v[26:29]
	v_mfma_f32_16x16x32_bf16 v[30:33], v[142:145], v[166:169], v[30:33]
	v_mfma_f32_16x16x32_bf16 v[42:45], v[134:137], v[174:177], v[42:45]
	v_mfma_f32_16x16x32_bf16 v[46:49], v[142:145], v[174:177], v[46:49]
	v_mfma_f32_16x16x32_bf16 v[70:73], v[134:137], v[182:185], v[70:73]
	v_mfma_f32_16x16x32_bf16 v[74:77], v[142:145], v[182:185], v[74:77]
	v_mfma_f32_16x16x32_bf16 v[90:93], v[134:137], v[190:193], v[90:93]
	v_mfma_f32_16x16x32_bf16 v[94:97], v[142:145], v[190:193], v[94:97]
	v_mfma_f32_16x16x32_bf16 v[26:29], v[138:141], v[170:173], v[26:29]
	v_mfma_f32_16x16x32_bf16 v[30:33], v[146:149], v[170:173], v[30:33]
	v_mfma_f32_16x16x32_bf16 v[42:45], v[138:141], v[178:181], v[42:45]
	v_mfma_f32_16x16x32_bf16 v[46:49], v[146:149], v[178:181], v[46:49]
	v_mfma_f32_16x16x32_bf16 v[70:73], v[138:141], v[186:189], v[70:73]
	v_mfma_f32_16x16x32_bf16 v[74:77], v[146:149], v[186:189], v[74:77]
	v_mfma_f32_16x16x32_bf16 v[90:93], v[138:141], v[238:241], v[90:93]
	v_mfma_f32_16x16x32_bf16 v[94:97], v[146:149], v[238:241], v[94:97]
	v_mfma_f32_16x16x32_bf16 v[34:37], v[150:153], v[166:169], v[34:37]
	v_mfma_f32_16x16x32_bf16 v[38:41], v[158:161], v[166:169], v[38:41]
	v_mfma_f32_16x16x32_bf16 v[54:57], v[150:153], v[174:177], v[54:57]
	v_mfma_f32_16x16x32_bf16 v[58:61], v[158:161], v[174:177], v[58:61]
	v_mfma_f32_16x16x32_bf16 v[82:85], v[150:153], v[182:185], v[82:85]
	v_mfma_f32_16x16x32_bf16 v[86:89], v[158:161], v[182:185], v[86:89]
	v_mfma_f32_16x16x32_bf16 v[98:101], v[150:153], v[190:193], v[98:101]
	v_mfma_f32_16x16x32_bf16 v[102:105], v[158:161], v[190:193], v[102:105]
	s_barrier
	s_setprio 2
	v_mfma_f32_16x16x32_bf16 v[34:37], v[154:157], v[170:173], v[34:37]
	v_mfma_f32_16x16x32_bf16 v[38:41], v[162:165], v[170:173], v[38:41]
	v_mfma_f32_16x16x32_bf16 v[54:57], v[154:157], v[178:181], v[54:57]
	v_mfma_f32_16x16x32_bf16 v[58:61], v[162:165], v[178:181], v[58:61]
	v_mfma_f32_16x16x32_bf16 v[82:85], v[154:157], v[186:189], v[82:85]
	v_mfma_f32_16x16x32_bf16 v[86:89], v[162:165], v[186:189], v[86:89]
	v_mfma_f32_16x16x32_bf16 v[98:101], v[154:157], v[238:241], v[98:101]
	v_mfma_f32_16x16x32_bf16 v[102:105], v[162:165], v[238:241], v[102:105]
	s_setprio 0
	s_mov_b32 m0, s68
	v_lshl_add_u64 v[242:243], s[30:31], 0, v[202:203]
	s_add_u32 s78, s30, 0x80000
	ds_read_b128 v[166:169], v226 offset:16384
	ds_read_b128 v[170:173], v226 offset:17408
	ds_read_b128 v[174:177], v226 offset:18432
	ds_read_b128 v[178:181], v226 offset:19456
	ds_read_b128 v[182:185], v226 offset:20480
	ds_read_b128 v[186:189], v226 offset:21504
	ds_read_b128 v[190:193], v226 offset:22528
	ds_read_b128 v[238:241], v226 offset:23552
	global_load_lds_dwordx4 v[242:243], off
	v_lshl_add_u64 v[244:245], s[30:31], 0, v[206:207]
	s_mov_b32 m0, s69
	s_addc_u32 s79, s31, 0
	global_load_lds_dwordx4 v[244:245], off
	v_lshl_add_u64 v[246:247], s[78:79], 0, v[202:203]
	s_mov_b32 m0, s70
	v_lshl_add_u64 v[248:249], s[34:35], 0, v[204:205]
	global_load_lds_dwordx4 v[246:247], off
	v_lshl_add_u64 v[246:247], s[78:79], 0, v[206:207]
	s_mov_b32 m0, s71
	s_nop 0
	global_load_lds_dwordx4 v[246:247], off
	v_lshl_add_u64 v[246:247], s[34:35], 0, v[194:195]
	s_mov_b32 m0, s23
	s_nop 0
	global_load_lds_dwordx4 v[246:247], off
	s_mov_b32 m0, s42
	s_nop 0
	global_load_lds_dwordx4 v[248:249], off
	s_waitcnt vmcnt(8)
	s_waitcnt lgkmcnt(0)
	s_barrier
	s_setprio 1
	s_waitcnt lgkmcnt(0)
	v_mfma_f32_16x16x32_bf16 v[106:109], v[134:137], v[166:169], v[106:109]
	v_mfma_f32_16x16x32_bf16 v[110:113], v[142:145], v[166:169], v[110:113]
	v_mfma_f32_16x16x32_bf16 v[118:121], v[134:137], v[174:177], v[118:121]
	v_mfma_f32_16x16x32_bf16 v[126:129], v[142:145], v[174:177], v[126:129]
	v_mfma_f32_16x16x32_bf16 v[50:53], v[134:137], v[182:185], v[50:53]
	v_mfma_f32_16x16x32_bf16 v[62:65], v[142:145], v[182:185], v[62:65]
	v_mfma_f32_16x16x32_bf16 v[10:13], v[134:137], v[190:193], v[10:13]
	v_mfma_f32_16x16x32_bf16 v[14:17], v[142:145], v[190:193], v[14:17]
	v_mfma_f32_16x16x32_bf16 v[106:109], v[138:141], v[170:173], v[106:109]
	v_mfma_f32_16x16x32_bf16 v[110:113], v[146:149], v[170:173], v[110:113]
	v_mfma_f32_16x16x32_bf16 v[118:121], v[138:141], v[178:181], v[118:121]
	v_mfma_f32_16x16x32_bf16 v[126:129], v[146:149], v[178:181], v[126:129]
	v_mfma_f32_16x16x32_bf16 v[50:53], v[138:141], v[186:189], v[50:53]
	v_mfma_f32_16x16x32_bf16 v[62:65], v[146:149], v[186:189], v[62:65]
	v_mfma_f32_16x16x32_bf16 v[10:13], v[138:141], v[238:241], v[10:13]
	v_mfma_f32_16x16x32_bf16 v[14:17], v[146:149], v[238:241], v[14:17]
	v_mfma_f32_16x16x32_bf16 v[114:117], v[150:153], v[166:169], v[114:117]
	v_mfma_f32_16x16x32_bf16 v[122:125], v[158:161], v[166:169], v[122:125]
	v_mfma_f32_16x16x32_bf16 v[66:69], v[150:153], v[174:177], v[66:69]
	v_mfma_f32_16x16x32_bf16 v[78:81], v[158:161], v[174:177], v[78:81]
	v_mfma_f32_16x16x32_bf16 v[18:21], v[150:153], v[182:185], v[18:21]
	v_mfma_f32_16x16x32_bf16 v[22:25], v[158:161], v[182:185], v[22:25]
	v_mfma_f32_16x16x32_bf16 v[2:5], v[150:153], v[190:193], v[2:5]
	v_mfma_f32_16x16x32_bf16 v[6:9], v[158:161], v[190:193], v[6:9]
	s_barrier
	s_setprio 2
	v_mfma_f32_16x16x32_bf16 v[114:117], v[154:157], v[170:173], v[114:117]
	v_mfma_f32_16x16x32_bf16 v[122:125], v[162:165], v[170:173], v[122:125]
	v_mfma_f32_16x16x32_bf16 v[66:69], v[154:157], v[178:181], v[66:69]
	v_mfma_f32_16x16x32_bf16 v[78:81], v[162:165], v[178:181], v[78:81]
	v_mfma_f32_16x16x32_bf16 v[18:21], v[154:157], v[186:189], v[18:21]
	v_mfma_f32_16x16x32_bf16 v[22:25], v[162:165], v[186:189], v[22:25]
	v_mfma_f32_16x16x32_bf16 v[2:5], v[154:157], v[238:241], v[2:5]
	v_mfma_f32_16x16x32_bf16 v[6:9], v[162:165], v[238:241], v[6:9]
	s_setprio 0
	ds_read_b128 v[134:137], v235
	ds_read_b128 v[138:141], v235 offset:1024
	ds_read_b128 v[142:145], v235 offset:2048
	ds_read_b128 v[146:149], v235 offset:3072
	ds_read_b128 v[150:153], v236
	ds_read_b128 v[154:157], v236 offset:1024
	ds_read_b128 v[158:161], v236 offset:2048
	ds_read_b128 v[162:165], v236 offset:3072
	s_add_u32 s34, s34, 0x80000
	s_addc_u32 s35, s35, 0
	s_mov_b32 m0, s43
	v_lshl_add_u64 v[250:251], s[34:35], 0, v[194:195]
	ds_read_b128 v[166:169], v226 offset:32768
	ds_read_b128 v[170:173], v226 offset:33792
	ds_read_b128 v[174:177], v226 offset:34816
	ds_read_b128 v[178:181], v226 offset:35840
	ds_read_b128 v[182:185], v226 offset:36864
	ds_read_b128 v[186:189], v226 offset:37888
	ds_read_b128 v[190:193], v226 offset:38912
	ds_read_b128 v[238:241], v226 offset:39936
	global_load_lds_dwordx4 v[250:251], off
	v_lshl_add_u64 v[250:251], s[34:35], 0, v[204:205]
	s_mov_b32 m0, s44
	s_nop 0
	global_load_lds_dwordx4 v[250:251], off
	s_waitcnt vmcnt(8)
	s_waitcnt lgkmcnt(0)
	s_barrier
	s_setprio 1
	s_waitcnt lgkmcnt(0)
	v_mfma_f32_16x16x32_bf16 v[26:29], v[134:137], v[166:169], v[26:29]
	v_mfma_f32_16x16x32_bf16 v[30:33], v[142:145], v[166:169], v[30:33]
	v_mfma_f32_16x16x32_bf16 v[42:45], v[134:137], v[174:177], v[42:45]
	v_mfma_f32_16x16x32_bf16 v[46:49], v[142:145], v[174:177], v[46:49]
	v_mfma_f32_16x16x32_bf16 v[70:73], v[134:137], v[182:185], v[70:73]
	v_mfma_f32_16x16x32_bf16 v[74:77], v[142:145], v[182:185], v[74:77]
	v_mfma_f32_16x16x32_bf16 v[90:93], v[134:137], v[190:193], v[90:93]
	v_mfma_f32_16x16x32_bf16 v[94:97], v[142:145], v[190:193], v[94:97]
	v_mfma_f32_16x16x32_bf16 v[26:29], v[138:141], v[170:173], v[26:29]
	v_mfma_f32_16x16x32_bf16 v[30:33], v[146:149], v[170:173], v[30:33]
	v_mfma_f32_16x16x32_bf16 v[42:45], v[138:141], v[178:181], v[42:45]
	v_mfma_f32_16x16x32_bf16 v[46:49], v[146:149], v[178:181], v[46:49]
	v_mfma_f32_16x16x32_bf16 v[70:73], v[138:141], v[186:189], v[70:73]
	v_mfma_f32_16x16x32_bf16 v[74:77], v[146:149], v[186:189], v[74:77]
	v_mfma_f32_16x16x32_bf16 v[90:93], v[138:141], v[238:241], v[90:93]
	v_mfma_f32_16x16x32_bf16 v[94:97], v[146:149], v[238:241], v[94:97]
	v_mfma_f32_16x16x32_bf16 v[34:37], v[150:153], v[166:169], v[34:37]
	v_mfma_f32_16x16x32_bf16 v[38:41], v[158:161], v[166:169], v[38:41]
	v_mfma_f32_16x16x32_bf16 v[54:57], v[150:153], v[174:177], v[54:57]
	v_mfma_f32_16x16x32_bf16 v[58:61], v[158:161], v[174:177], v[58:61]
	v_mfma_f32_16x16x32_bf16 v[82:85], v[150:153], v[182:185], v[82:85]
	v_mfma_f32_16x16x32_bf16 v[86:89], v[158:161], v[182:185], v[86:89]
	v_mfma_f32_16x16x32_bf16 v[98:101], v[150:153], v[190:193], v[98:101]
	v_mfma_f32_16x16x32_bf16 v[102:105], v[158:161], v[190:193], v[102:105]
	s_barrier
	s_setprio 2
	v_mfma_f32_16x16x32_bf16 v[34:37], v[154:157], v[170:173], v[34:37]
	v_mfma_f32_16x16x32_bf16 v[38:41], v[162:165], v[170:173], v[38:41]
	v_mfma_f32_16x16x32_bf16 v[54:57], v[154:157], v[178:181], v[54:57]
	v_mfma_f32_16x16x32_bf16 v[58:61], v[162:165], v[178:181], v[58:61]
	v_mfma_f32_16x16x32_bf16 v[82:85], v[154:157], v[186:189], v[82:85]
	v_mfma_f32_16x16x32_bf16 v[86:89], v[162:165], v[186:189], v[86:89]
	v_mfma_f32_16x16x32_bf16 v[98:101], v[154:157], v[238:241], v[98:101]
	v_mfma_f32_16x16x32_bf16 v[102:105], v[162:165], v[238:241], v[102:105]
	s_setprio 0
	s_mov_b32 m0, s72
	v_lshl_add_u64 v[242:243], v[242:243], 0, s[6:7]
	s_add_u32 s30, s30, 0x80080
	ds_read_b128 v[166:169], v226 offset:49152
	ds_read_b128 v[170:173], v226 offset:50176
	ds_read_b128 v[174:177], v226 offset:51200
	ds_read_b128 v[178:181], v226 offset:52224
	ds_read_b128 v[182:185], v226 offset:53248
	ds_read_b128 v[186:189], v226 offset:54272
	ds_read_b128 v[190:193], v226 offset:55296
	ds_read_b128 v[238:241], v226 offset:56320
	global_load_lds_dwordx4 v[242:243], off
	v_lshl_add_u64 v[242:243], v[244:245], 0, s[6:7]
	s_mov_b32 m0, s73
	s_addc_u32 s31, s31, 0
	global_load_lds_dwordx4 v[242:243], off
	v_lshl_add_u64 v[242:243], s[30:31], 0, v[202:203]
	s_mov_b32 m0, s74
	s_nop 0
	global_load_lds_dwordx4 v[242:243], off
	v_lshl_add_u64 v[242:243], s[30:31], 0, v[206:207]
	s_mov_b32 m0, s75
	s_nop 0
	global_load_lds_dwordx4 v[242:243], off
	v_lshl_add_u64 v[242:243], v[246:247], 0, s[6:7]
	s_mov_b32 m0, s51
	s_nop 0
	global_load_lds_dwordx4 v[242:243], off
	v_lshl_add_u64 v[242:243], v[248:249], 0, s[6:7]
	s_mov_b32 m0, s53
	s_nop 0
	global_load_lds_dwordx4 v[242:243], off
	s_waitcnt vmcnt(8)
	s_waitcnt lgkmcnt(0)
	s_barrier
	s_setprio 1
	s_waitcnt lgkmcnt(0)
	v_mfma_f32_16x16x32_bf16 v[106:109], v[134:137], v[166:169], v[106:109]
	v_mfma_f32_16x16x32_bf16 v[110:113], v[142:145], v[166:169], v[110:113]
	v_mfma_f32_16x16x32_bf16 v[118:121], v[134:137], v[174:177], v[118:121]
	v_mfma_f32_16x16x32_bf16 v[126:129], v[142:145], v[174:177], v[126:129]
	v_mfma_f32_16x16x32_bf16 v[50:53], v[134:137], v[182:185], v[50:53]
	v_mfma_f32_16x16x32_bf16 v[62:65], v[142:145], v[182:185], v[62:65]
	v_mfma_f32_16x16x32_bf16 v[10:13], v[134:137], v[190:193], v[10:13]
	v_mfma_f32_16x16x32_bf16 v[14:17], v[142:145], v[190:193], v[14:17]
	v_mfma_f32_16x16x32_bf16 v[106:109], v[138:141], v[170:173], v[106:109]
	v_mfma_f32_16x16x32_bf16 v[110:113], v[146:149], v[170:173], v[110:113]
	v_mfma_f32_16x16x32_bf16 v[118:121], v[138:141], v[178:181], v[118:121]
	v_mfma_f32_16x16x32_bf16 v[126:129], v[146:149], v[178:181], v[126:129]
	v_mfma_f32_16x16x32_bf16 v[50:53], v[138:141], v[186:189], v[50:53]
	v_mfma_f32_16x16x32_bf16 v[62:65], v[146:149], v[186:189], v[62:65]
	v_mfma_f32_16x16x32_bf16 v[10:13], v[138:141], v[238:241], v[10:13]
	v_mfma_f32_16x16x32_bf16 v[14:17], v[146:149], v[238:241], v[14:17]
	v_mfma_f32_16x16x32_bf16 v[114:117], v[150:153], v[166:169], v[114:117]
	v_mfma_f32_16x16x32_bf16 v[122:125], v[158:161], v[166:169], v[122:125]
	v_mfma_f32_16x16x32_bf16 v[66:69], v[150:153], v[174:177], v[66:69]
	v_mfma_f32_16x16x32_bf16 v[78:81], v[158:161], v[174:177], v[78:81]
	v_mfma_f32_16x16x32_bf16 v[18:21], v[150:153], v[182:185], v[18:21]
	v_mfma_f32_16x16x32_bf16 v[22:25], v[158:161], v[182:185], v[22:25]
	v_mfma_f32_16x16x32_bf16 v[2:5], v[150:153], v[190:193], v[2:5]
	v_mfma_f32_16x16x32_bf16 v[6:9], v[158:161], v[190:193], v[6:9]
	s_barrier
	s_setprio 2
	v_mfma_f32_16x16x32_bf16 v[114:117], v[154:157], v[170:173], v[114:117]
	v_mfma_f32_16x16x32_bf16 v[122:125], v[162:165], v[170:173], v[122:125]
	v_mfma_f32_16x16x32_bf16 v[66:69], v[154:157], v[178:181], v[66:69]
	v_mfma_f32_16x16x32_bf16 v[78:81], v[162:165], v[178:181], v[78:81]
	v_mfma_f32_16x16x32_bf16 v[18:21], v[154:157], v[186:189], v[18:21]
	v_mfma_f32_16x16x32_bf16 v[22:25], v[162:165], v[186:189], v[22:25]
	v_mfma_f32_16x16x32_bf16 v[2:5], v[154:157], v[238:241], v[2:5]
	v_mfma_f32_16x16x32_bf16 v[6:9], v[162:165], v[238:241], v[6:9]
	s_setprio 0
	s_add_i32 s41, s41, 2
	s_add_u32 s2, s2, 0x100
	s_addc_u32 s3, s3, 0
	s_cmp_gt_u32 s41, 29
	s_cbranch_scc0 .LBB0_752
	s_and_b64 vcc, exec, s[8:9]
	s_cbranch_vccz .LBB0_755
	s_barrier

.LBB0_817:
	ds_read_b128 v[130:133], v223
	ds_read_b128 v[134:137], v223 offset:1024
	ds_read_b128 v[138:141], v223 offset:2048
	ds_read_b128 v[142:145], v223 offset:3072
	ds_read_b128 v[146:149], v224
	ds_read_b128 v[150:153], v224 offset:1024
	ds_read_b128 v[154:157], v224 offset:2048
	ds_read_b128 v[158:161], v224 offset:3072
	s_add_u32 s6, s4, 0xfff00080
	s_addc_u32 s7, s5, -1
	s_cmp_eq_u32 s14, 60
	s_cselect_b32 s9, s19, s7
	s_cselect_b32 s8, s18, s6
	s_cselect_b32 s7, s79, s1
	s_cselect_b32 s6, s78, s0
	v_lshl_add_u64 v[194:195], s[4:5], 0, v[170:171]
	s_add_i32 m0, s35, 0xc000
	ds_read_b128 v[174:177], v225
	ds_read_b128 v[178:181], v225 offset:1024
	ds_read_b128 v[182:185], v225 offset:2048
	ds_read_b128 v[186:189], v225 offset:3072
	ds_read_b128 v[190:193], v225 offset:4096
	ds_read_b128 v[202:205], v225 offset:5120
	ds_read_b128 v[206:209], v225 offset:6144
	ds_read_b128 v[210:213], v225 offset:7168
	global_load_lds_dwordx4 v[194:195], off
	v_lshl_add_u64 v[194:195], s[4:5], 0, v[172:173]
	s_add_i32 m0, s35, 0xe000
	s_nop 0
	global_load_lds_dwordx4 v[194:195], off
	s_waitcnt vmcnt(8)
	s_waitcnt lgkmcnt(0)
	s_barrier
	s_setprio 1
	s_waitcnt lgkmcnt(0)
	v_mfma_f32_16x16x32_bf16 v[14:17], v[130:133], v[174:177], v[14:17]
	v_mfma_f32_16x16x32_bf16 v[10:13], v[138:141], v[174:177], v[10:13]
	v_mfma_f32_16x16x32_bf16 v[34:37], v[130:133], v[182:185], v[34:37]
	v_mfma_f32_16x16x32_bf16 v[26:29], v[138:141], v[182:185], v[26:29]
	v_mfma_f32_16x16x32_bf16 v[46:49], v[130:133], v[190:193], v[46:49]
	v_mfma_f32_16x16x32_bf16 v[42:45], v[138:141], v[190:193], v[42:45]
	v_mfma_f32_16x16x32_bf16 v[62:65], v[130:133], v[206:209], v[62:65]
	v_mfma_f32_16x16x32_bf16 v[58:61], v[138:141], v[206:209], v[58:61]
	v_mfma_f32_16x16x32_bf16 v[14:17], v[134:137], v[178:181], v[14:17]
	v_mfma_f32_16x16x32_bf16 v[10:13], v[142:145], v[178:181], v[10:13]
	v_mfma_f32_16x16x32_bf16 v[34:37], v[134:137], v[186:189], v[34:37]
	v_mfma_f32_16x16x32_bf16 v[26:29], v[142:145], v[186:189], v[26:29]
	v_mfma_f32_16x16x32_bf16 v[46:49], v[134:137], v[202:205], v[46:49]
	v_mfma_f32_16x16x32_bf16 v[42:45], v[142:145], v[202:205], v[42:45]
	v_mfma_f32_16x16x32_bf16 v[62:65], v[134:137], v[210:213], v[62:65]
	v_mfma_f32_16x16x32_bf16 v[58:61], v[142:145], v[210:213], v[58:61]
	v_mfma_f32_16x16x32_bf16 v[6:9], v[146:149], v[174:177], v[6:9]
	v_mfma_f32_16x16x32_bf16 v[2:5], v[154:157], v[174:177], v[2:5]
	v_mfma_f32_16x16x32_bf16 v[22:25], v[146:149], v[182:185], v[22:25]
	v_mfma_f32_16x16x32_bf16 v[18:21], v[154:157], v[182:185], v[18:21]
	v_mfma_f32_16x16x32_bf16 v[38:41], v[146:149], v[190:193], v[38:41]
	v_mfma_f32_16x16x32_bf16 v[30:33], v[154:157], v[190:193], v[30:33]
	v_mfma_f32_16x16x32_bf16 v[54:57], v[146:149], v[206:209], v[54:57]
	v_mfma_f32_16x16x32_bf16 v[50:53], v[154:157], v[206:209], v[50:53]
	s_barrier
	s_setprio 2
	v_mfma_f32_16x16x32_bf16 v[6:9], v[150:153], v[178:181], v[6:9]
	v_mfma_f32_16x16x32_bf16 v[2:5], v[158:161], v[178:181], v[2:5]
	v_mfma_f32_16x16x32_bf16 v[22:25], v[150:153], v[186:189], v[22:25]
	v_mfma_f32_16x16x32_bf16 v[18:21], v[158:161], v[186:189], v[18:21]
	v_mfma_f32_16x16x32_bf16 v[38:41], v[150:153], v[202:205], v[38:41]
	v_mfma_f32_16x16x32_bf16 v[30:33], v[158:161], v[202:205], v[30:33]
	v_mfma_f32_16x16x32_bf16 v[54:57], v[150:153], v[210:213], v[54:57]
	v_mfma_f32_16x16x32_bf16 v[50:53], v[158:161], v[210:213], v[50:53]
	s_setprio 0
	s_add_i32 s15, s17, s33
	v_lshl_add_u64 v[194:195], s[6:7], 0, v[164:165]
	s_mov_b32 m0, s15
	ds_read_b128 v[174:177], v225 offset:16384
	ds_read_b128 v[178:181], v225 offset:17408
	ds_read_b128 v[182:185], v225 offset:18432
	ds_read_b128 v[186:189], v225 offset:19456
	ds_read_b128 v[190:193], v225 offset:20480
	ds_read_b128 v[202:205], v225 offset:21504
	ds_read_b128 v[206:209], v225 offset:22528
	ds_read_b128 v[210:213], v225 offset:23552
	global_load_lds_dwordx4 v[194:195], off
	s_add_i32 m0, s15, 0x2000
	s_add_u32 s44, s6, 0x100000
	v_lshl_add_u64 v[214:215], s[6:7], 0, v[168:169]
	s_addc_u32 s45, s7, 0
	s_add_i32 s15, s55, s33
	global_load_lds_dwordx4 v[214:215], off
	v_lshl_add_u64 v[216:217], s[44:45], 0, v[164:165]
	s_mov_b32 m0, s15
	v_lshl_add_u64 v[218:219], s[8:9], 0, v[166:167]
	global_load_lds_dwordx4 v[216:217], off
	v_lshl_add_u64 v[216:217], s[44:45], 0, v[168:169]
	s_add_i32 m0, s15, 0x2000
	s_nop 0
	global_load_lds_dwordx4 v[216:217], off
	v_lshl_add_u64 v[216:217], s[8:9], 0, v[162:163]
	s_mov_b32 m0, s35
	s_nop 0
	global_load_lds_dwordx4 v[216:217], off
	s_mov_b32 m0, s80
	s_nop 0
	global_load_lds_dwordx4 v[218:219], off
	s_waitcnt vmcnt(8)
	s_waitcnt lgkmcnt(0)
	s_barrier
	s_setprio 1
	s_waitcnt lgkmcnt(0)
	v_mfma_f32_16x16x32_bf16 v[78:81], v[130:133], v[174:177], v[78:81]
	v_mfma_f32_16x16x32_bf16 v[74:77], v[138:141], v[174:177], v[74:77]
	v_mfma_f32_16x16x32_bf16 v[94:97], v[130:133], v[182:185], v[94:97]
	v_mfma_f32_16x16x32_bf16 v[90:93], v[138:141], v[182:185], v[90:93]
	v_mfma_f32_16x16x32_bf16 v[110:113], v[130:133], v[190:193], v[110:113]
	v_mfma_f32_16x16x32_bf16 v[106:109], v[138:141], v[190:193], v[106:109]
	v_mfma_f32_16x16x32_bf16 v[118:121], v[130:133], v[206:209], v[118:121]
	v_mfma_f32_16x16x32_bf16 v[114:117], v[138:141], v[206:209], v[114:117]
	v_mfma_f32_16x16x32_bf16 v[78:81], v[134:137], v[178:181], v[78:81]
	v_mfma_f32_16x16x32_bf16 v[74:77], v[142:145], v[178:181], v[74:77]
	v_mfma_f32_16x16x32_bf16 v[94:97], v[134:137], v[186:189], v[94:97]
	v_mfma_f32_16x16x32_bf16 v[90:93], v[142:145], v[186:189], v[90:93]
	v_mfma_f32_16x16x32_bf16 v[110:113], v[134:137], v[202:205], v[110:113]
	v_mfma_f32_16x16x32_bf16 v[106:109], v[142:145], v[202:205], v[106:109]
	v_mfma_f32_16x16x32_bf16 v[118:121], v[134:137], v[210:213], v[118:121]
	v_mfma_f32_16x16x32_bf16 v[114:117], v[142:145], v[210:213], v[114:117]
	v_mfma_f32_16x16x32_bf16 v[70:73], v[146:149], v[174:177], v[70:73]
	v_mfma_f32_16x16x32_bf16 v[66:69], v[154:157], v[174:177], v[66:69]
	v_mfma_f32_16x16x32_bf16 v[86:89], v[146:149], v[182:185], v[86:89]
	v_mfma_f32_16x16x32_bf16 v[82:85], v[154:157], v[182:185], v[82:85]
	v_mfma_f32_16x16x32_bf16 v[102:105], v[146:149], v[190:193], v[102:105]
	v_mfma_f32_16x16x32_bf16 v[98:101], v[154:157], v[190:193], v[98:101]
	v_mfma_f32_16x16x32_bf16 v[122:125], v[146:149], v[206:209], v[122:125]
	v_mfma_f32_16x16x32_bf16 v[126:129], v[154:157], v[206:209], v[126:129]
	s_barrier
	s_setprio 2
	v_mfma_f32_16x16x32_bf16 v[70:73], v[150:153], v[178:181], v[70:73]
	v_mfma_f32_16x16x32_bf16 v[66:69], v[158:161], v[178:181], v[66:69]
	v_mfma_f32_16x16x32_bf16 v[86:89], v[150:153], v[186:189], v[86:89]
	v_mfma_f32_16x16x32_bf16 v[82:85], v[158:161], v[186:189], v[82:85]
	v_mfma_f32_16x16x32_bf16 v[102:105], v[150:153], v[202:205], v[102:105]
	v_mfma_f32_16x16x32_bf16 v[98:101], v[158:161], v[202:205], v[98:101]
	v_mfma_f32_16x16x32_bf16 v[122:125], v[150:153], v[210:213], v[122:125]
	v_mfma_f32_16x16x32_bf16 v[126:129], v[158:161], v[210:213], v[126:129]
	s_setprio 0
	s_add_i32 s56, 0, 0x18000
	s_add_i32 s57, 0, 0x1c000
	v_add_u32_e32 v142, s56, v222
	v_add_u32_e32 v158, s57, v222
	ds_read_b128 v[130:133], v142
	ds_read_b128 v[134:137], v142 offset:1024
	ds_read_b128 v[138:141], v142 offset:2048
	ds_read_b128 v[142:145], v142 offset:3072
	ds_read_b128 v[146:149], v158
	ds_read_b128 v[150:153], v158 offset:1024
	ds_read_b128 v[154:157], v158 offset:2048
	ds_read_b128 v[158:161], v158 offset:3072
	s_add_u32 s8, s8, 0x100000
	s_addc_u32 s9, s9, 0
	s_mov_b32 m0, s59
	v_lshl_add_u64 v[238:239], s[8:9], 0, v[162:163]
	ds_read_b128 v[174:177], v225 offset:32768
	ds_read_b128 v[178:181], v225 offset:33792
	ds_read_b128 v[182:185], v225 offset:34816
	ds_read_b128 v[186:189], v225 offset:35840
	ds_read_b128 v[190:193], v225 offset:36864
	ds_read_b128 v[202:205], v225 offset:37888
	ds_read_b128 v[206:209], v225 offset:38912
	ds_read_b128 v[210:213], v225 offset:39936
	global_load_lds_dwordx4 v[238:239], off
	v_lshl_add_u64 v[238:239], s[8:9], 0, v[166:167]
	s_mov_b32 m0, s60
	s_nop 0
	global_load_lds_dwordx4 v[238:239], off
	s_waitcnt vmcnt(8)
	s_waitcnt lgkmcnt(0)
	s_barrier
	s_setprio 1
	s_waitcnt lgkmcnt(0)
	v_mfma_f32_16x16x32_bf16 v[14:17], v[130:133], v[174:177], v[14:17]
	v_mfma_f32_16x16x32_bf16 v[10:13], v[138:141], v[174:177], v[10:13]
	v_mfma_f32_16x16x32_bf16 v[34:37], v[130:133], v[182:185], v[34:37]
	v_mfma_f32_16x16x32_bf16 v[26:29], v[138:141], v[182:185], v[26:29]
	v_mfma_f32_16x16x32_bf16 v[46:49], v[130:133], v[190:193], v[46:49]
	v_mfma_f32_16x16x32_bf16 v[42:45], v[138:141], v[190:193], v[42:45]
	v_mfma_f32_16x16x32_bf16 v[62:65], v[130:133], v[206:209], v[62:65]
	v_mfma_f32_16x16x32_bf16 v[58:61], v[138:141], v[206:209], v[58:61]
	v_mfma_f32_16x16x32_bf16 v[14:17], v[134:137], v[178:181], v[14:17]
	v_mfma_f32_16x16x32_bf16 v[10:13], v[142:145], v[178:181], v[10:13]
	v_mfma_f32_16x16x32_bf16 v[34:37], v[134:137], v[186:189], v[34:37]
	v_mfma_f32_16x16x32_bf16 v[26:29], v[142:145], v[186:189], v[26:29]
	v_mfma_f32_16x16x32_bf16 v[46:49], v[134:137], v[202:205], v[46:49]
	v_mfma_f32_16x16x32_bf16 v[42:45], v[142:145], v[202:205], v[42:45]
	v_mfma_f32_16x16x32_bf16 v[62:65], v[134:137], v[210:213], v[62:65]
	v_mfma_f32_16x16x32_bf16 v[58:61], v[142:145], v[210:213], v[58:61]
	v_mfma_f32_16x16x32_bf16 v[6:9], v[146:149], v[174:177], v[6:9]
	v_mfma_f32_16x16x32_bf16 v[2:5], v[154:157], v[174:177], v[2:5]
	v_mfma_f32_16x16x32_bf16 v[22:25], v[146:149], v[182:185], v[22:25]
	v_mfma_f32_16x16x32_bf16 v[18:21], v[154:157], v[182:185], v[18:21]
	v_mfma_f32_16x16x32_bf16 v[38:41], v[146:149], v[190:193], v[38:41]
	v_mfma_f32_16x16x32_bf16 v[30:33], v[154:157], v[190:193], v[30:33]
	v_mfma_f32_16x16x32_bf16 v[54:57], v[146:149], v[206:209], v[54:57]
	v_mfma_f32_16x16x32_bf16 v[50:53], v[154:157], v[206:209], v[50:53]
	s_barrier
	s_setprio 2
	v_mfma_f32_16x16x32_bf16 v[6:9], v[150:153], v[178:181], v[6:9]
	v_mfma_f32_16x16x32_bf16 v[2:5], v[158:161], v[178:181], v[2:5]
	v_mfma_f32_16x16x32_bf16 v[22:25], v[150:153], v[186:189], v[22:25]
	v_mfma_f32_16x16x32_bf16 v[18:21], v[158:161], v[186:189], v[18:21]
	v_mfma_f32_16x16x32_bf16 v[38:41], v[150:153], v[202:205], v[38:41]
	v_mfma_f32_16x16x32_bf16 v[30:33], v[158:161], v[202:205], v[30:33]
	v_mfma_f32_16x16x32_bf16 v[54:57], v[150:153], v[210:213], v[54:57]
	v_mfma_f32_16x16x32_bf16 v[50:53], v[158:161], v[210:213], v[50:53]
	s_setprio 0
	s_add_i32 s8, s56, s33
	v_lshl_add_u64 v[194:195], v[194:195], 0, s[26:27]
	s_mov_b32 m0, s8
	ds_read_b128 v[174:177], v225 offset:49152
	ds_read_b128 v[178:181], v225 offset:50176
	ds_read_b128 v[182:185], v225 offset:51200
	ds_read_b128 v[186:189], v225 offset:52224
	ds_read_b128 v[190:193], v225 offset:53248
	ds_read_b128 v[202:205], v225 offset:54272
	ds_read_b128 v[206:209], v225 offset:55296
	ds_read_b128 v[210:213], v225 offset:56320
	global_load_lds_dwordx4 v[194:195], off
	s_add_i32 m0, s8, 0x2000
	s_add_u32 s6, s6, 0x100080
	v_lshl_add_u64 v[194:195], v[214:215], 0, s[26:27]
	s_addc_u32 s7, s7, 0
	s_add_i32 s8, s57, s33
	global_load_lds_dwordx4 v[194:195], off
	v_lshl_add_u64 v[194:195], s[6:7], 0, v[164:165]
	s_mov_b32 m0, s8
	s_nop 0
	global_load_lds_dwordx4 v[194:195], off
	v_lshl_add_u64 v[194:195], s[6:7], 0, v[168:169]
	s_add_i32 m0, s8, 0x2000
	s_nop 0
	global_load_lds_dwordx4 v[194:195], off
	v_lshl_add_u64 v[194:195], v[216:217], 0, s[26:27]
	s_mov_b32 m0, s65
	s_nop 0
	global_load_lds_dwordx4 v[194:195], off
	v_lshl_add_u64 v[194:195], v[218:219], 0, s[26:27]
	s_mov_b32 m0, s66
	s_nop 0
	global_load_lds_dwordx4 v[194:195], off
	s_waitcnt vmcnt(8)
	s_waitcnt lgkmcnt(0)
	s_barrier
	s_setprio 1
	s_waitcnt lgkmcnt(0)
	v_mfma_f32_16x16x32_bf16 v[78:81], v[130:133], v[174:177], v[78:81]
	v_mfma_f32_16x16x32_bf16 v[74:77], v[138:141], v[174:177], v[74:77]
	v_mfma_f32_16x16x32_bf16 v[94:97], v[130:133], v[182:185], v[94:97]
	v_mfma_f32_16x16x32_bf16 v[90:93], v[138:141], v[182:185], v[90:93]
	v_mfma_f32_16x16x32_bf16 v[110:113], v[130:133], v[190:193], v[110:113]
	v_mfma_f32_16x16x32_bf16 v[106:109], v[138:141], v[190:193], v[106:109]
	v_mfma_f32_16x16x32_bf16 v[118:121], v[130:133], v[206:209], v[118:121]
	v_mfma_f32_16x16x32_bf16 v[114:117], v[138:141], v[206:209], v[114:117]
	v_mfma_f32_16x16x32_bf16 v[78:81], v[134:137], v[178:181], v[78:81]
	v_mfma_f32_16x16x32_bf16 v[74:77], v[142:145], v[178:181], v[74:77]
	v_mfma_f32_16x16x32_bf16 v[94:97], v[134:137], v[186:189], v[94:97]
	v_mfma_f32_16x16x32_bf16 v[90:93], v[142:145], v[186:189], v[90:93]
	v_mfma_f32_16x16x32_bf16 v[110:113], v[134:137], v[202:205], v[110:113]
	v_mfma_f32_16x16x32_bf16 v[106:109], v[142:145], v[202:205], v[106:109]
	v_mfma_f32_16x16x32_bf16 v[118:121], v[134:137], v[210:213], v[118:121]
	v_mfma_f32_16x16x32_bf16 v[114:117], v[142:145], v[210:213], v[114:117]
	v_mfma_f32_16x16x32_bf16 v[70:73], v[146:149], v[174:177], v[70:73]
	v_mfma_f32_16x16x32_bf16 v[66:69], v[154:157], v[174:177], v[66:69]
	v_mfma_f32_16x16x32_bf16 v[86:89], v[146:149], v[182:185], v[86:89]
	v_mfma_f32_16x16x32_bf16 v[82:85], v[154:157], v[182:185], v[82:85]
	v_mfma_f32_16x16x32_bf16 v[102:105], v[146:149], v[190:193], v[102:105]
	v_mfma_f32_16x16x32_bf16 v[98:101], v[154:157], v[190:193], v[98:101]
	v_mfma_f32_16x16x32_bf16 v[122:125], v[146:149], v[206:209], v[122:125]
	v_mfma_f32_16x16x32_bf16 v[126:129], v[154:157], v[206:209], v[126:129]
	s_barrier
	s_setprio 2
	v_mfma_f32_16x16x32_bf16 v[70:73], v[150:153], v[178:181], v[70:73]
	v_mfma_f32_16x16x32_bf16 v[66:69], v[158:161], v[178:181], v[66:69]
	v_mfma_f32_16x16x32_bf16 v[86:89], v[150:153], v[186:189], v[86:89]
	v_mfma_f32_16x16x32_bf16 v[82:85], v[158:161], v[186:189], v[82:85]
	v_mfma_f32_16x16x32_bf16 v[102:105], v[150:153], v[202:205], v[102:105]
	v_mfma_f32_16x16x32_bf16 v[98:101], v[158:161], v[202:205], v[98:101]
	v_mfma_f32_16x16x32_bf16 v[122:125], v[150:153], v[210:213], v[122:125]
	v_mfma_f32_16x16x32_bf16 v[126:129], v[158:161], v[210:213], v[126:129]
	s_setprio 0
	s_add_i32 s14, s14, 2
	s_add_u32 s4, s4, 0x100
	s_addc_u32 s5, s5, 0
	s_add_u32 s0, s0, 0x100
	s_addc_u32 s1, s1, 0
	s_cmp_gt_u32 s14, 61
	s_cbranch_scc0 .LBB0_817
	s_and_b64 vcc, exec, s[28:29]
	s_cbranch_vccz .LBB0_820
	s_barrier

.LBB0_961:
	ds_read_b128 v[158:161], v185
	ds_read_b128 v[154:157], v185 offset:1024
	ds_read_b128 v[150:153], v185 offset:2048
	ds_read_b128 v[146:149], v185 offset:3072
	ds_read_b128 v[142:145], v186
	ds_read_b128 v[138:141], v186 offset:1024
	ds_read_b128 v[134:137], v186 offset:2048
	ds_read_b128 v[130:133], v186 offset:3072
	s_add_u32 s30, s28, 0xfff80080
	s_addc_u32 s31, s29, -1
	s_cmp_eq_u32 s45, 28
	s_cselect_b32 s35, s1, s31
	s_cselect_b32 s34, s15, s30
	s_cselect_b32 s31, s19, s44
	s_cselect_b32 s30, s42, s43
	v_lshl_add_u64 v[220:221], s[28:29], 0, v[170:171]
	s_add_i32 m0, s27, 0xc000
	ds_read_b128 v[174:177], v187
	ds_read_b128 v[178:181], v187 offset:1024
	ds_read_b128 v[188:191], v187 offset:2048
	ds_read_b128 v[192:195], v187 offset:3072
	ds_read_b128 v[202:205], v187 offset:4096
	ds_read_b128 v[206:209], v187 offset:5120
	ds_read_b128 v[210:213], v187 offset:6144
	ds_read_b128 v[214:217], v187 offset:7168
	global_load_lds_dwordx4 v[220:221], off
	v_lshl_add_u64 v[220:221], s[28:29], 0, v[172:173]
	s_add_i32 m0, s27, 0xe000
	s_nop 0
	global_load_lds_dwordx4 v[220:221], off
	s_waitcnt vmcnt(8)
	s_waitcnt lgkmcnt(0)
	s_barrier
	s_setprio 1
	s_waitcnt lgkmcnt(0)
	v_mfma_i32_16x16x64_i8 v[126:129], v[158:161], v[174:177], v[126:129]
	v_mfma_i32_16x16x64_i8 v[126:129], v[154:157], v[178:181], v[126:129]
	v_mfma_i32_16x16x64_i8 v[122:125], v[150:153], v[174:177], v[122:125]
	v_mfma_i32_16x16x64_i8 v[122:125], v[146:149], v[178:181], v[122:125]
	v_mfma_i32_16x16x64_i8 v[110:113], v[158:161], v[188:191], v[110:113]
	v_mfma_i32_16x16x64_i8 v[110:113], v[154:157], v[192:195], v[110:113]
	v_mfma_i32_16x16x64_i8 v[106:109], v[150:153], v[188:191], v[106:109]
	v_mfma_i32_16x16x64_i8 v[106:109], v[146:149], v[192:195], v[106:109]
	v_mfma_i32_16x16x64_i8 v[94:97], v[158:161], v[202:205], v[94:97]
	v_mfma_i32_16x16x64_i8 v[94:97], v[154:157], v[206:209], v[94:97]
	v_mfma_i32_16x16x64_i8 v[90:93], v[150:153], v[202:205], v[90:93]
	v_mfma_i32_16x16x64_i8 v[90:93], v[146:149], v[206:209], v[90:93]
	v_mfma_i32_16x16x64_i8 v[78:81], v[158:161], v[210:213], v[78:81]
	v_mfma_i32_16x16x64_i8 v[78:81], v[154:157], v[214:217], v[78:81]
	v_mfma_i32_16x16x64_i8 v[74:77], v[150:153], v[210:213], v[74:77]
	v_mfma_i32_16x16x64_i8 v[74:77], v[146:149], v[214:217], v[74:77]
	v_mfma_i32_16x16x64_i8 v[118:121], v[142:145], v[174:177], v[118:121]
	v_mfma_i32_16x16x64_i8 v[118:121], v[138:141], v[178:181], v[118:121]
	v_mfma_i32_16x16x64_i8 v[114:117], v[134:137], v[174:177], v[114:117]
	v_mfma_i32_16x16x64_i8 v[114:117], v[130:133], v[178:181], v[114:117]
	v_mfma_i32_16x16x64_i8 v[102:105], v[142:145], v[188:191], v[102:105]
	v_mfma_i32_16x16x64_i8 v[102:105], v[138:141], v[192:195], v[102:105]
	v_mfma_i32_16x16x64_i8 v[98:101], v[134:137], v[188:191], v[98:101]
	v_mfma_i32_16x16x64_i8 v[98:101], v[130:133], v[192:195], v[98:101]
	s_barrier
	s_setprio 2
	v_mfma_i32_16x16x64_i8 v[86:89], v[142:145], v[202:205], v[86:89]
	v_mfma_i32_16x16x64_i8 v[86:89], v[138:141], v[206:209], v[86:89]
	v_mfma_i32_16x16x64_i8 v[82:85], v[134:137], v[202:205], v[82:85]
	v_mfma_i32_16x16x64_i8 v[82:85], v[130:133], v[206:209], v[82:85]
	v_mfma_i32_16x16x64_i8 v[70:73], v[142:145], v[210:213], v[70:73]
	v_mfma_i32_16x16x64_i8 v[70:73], v[138:141], v[214:217], v[70:73]
	v_mfma_i32_16x16x64_i8 v[66:69], v[134:137], v[210:213], v[66:69]
	v_mfma_i32_16x16x64_i8 v[66:69], v[130:133], v[214:217], v[66:69]
	s_setprio 0
	s_add_i32 s46, s17, s9
	v_lshl_add_u64 v[174:175], s[30:31], 0, v[166:167]
	s_mov_b32 m0, s46
	ds_read_b128 v[188:191], v187 offset:16384
	ds_read_b128 v[192:195], v187 offset:17408
	ds_read_b128 v[202:205], v187 offset:18432
	ds_read_b128 v[206:209], v187 offset:19456
	ds_read_b128 v[210:213], v187 offset:20480
	ds_read_b128 v[214:217], v187 offset:21504
	ds_read_b128 v[220:223], v187 offset:22528
	ds_read_b128 v[224:227], v187 offset:23552
	global_load_lds_dwordx4 v[174:175], off
	s_add_i32 m0, s46, 0x2000
	s_add_u32 s46, s30, 0x80000
	v_lshl_add_u64 v[176:177], s[30:31], 0, v[162:163]
	s_addc_u32 s47, s31, 0
	s_add_i32 s48, s55, s9
	global_load_lds_dwordx4 v[176:177], off
	v_lshl_add_u64 v[178:179], s[46:47], 0, v[166:167]
	s_mov_b32 m0, s48
	v_lshl_add_u64 v[180:181], s[34:35], 0, v[164:165]
	global_load_lds_dwordx4 v[178:179], off
	v_lshl_add_u64 v[178:179], s[46:47], 0, v[162:163]
	s_add_i32 m0, s48, 0x2000
	s_nop 0
	global_load_lds_dwordx4 v[178:179], off
	v_lshl_add_u64 v[178:179], s[34:35], 0, v[168:169]
	s_mov_b32 m0, s27
	s_nop 0
	global_load_lds_dwordx4 v[178:179], off
	s_mov_b32 m0, s33
	s_nop 0
	global_load_lds_dwordx4 v[180:181], off
	s_waitcnt vmcnt(8)
	s_waitcnt lgkmcnt(0)
	s_barrier
	s_setprio 1
	s_waitcnt lgkmcnt(0)
	v_mfma_i32_16x16x64_i8 v[62:65], v[158:161], v[188:191], v[62:65]
	v_mfma_i32_16x16x64_i8 v[62:65], v[154:157], v[192:195], v[62:65]
	v_mfma_i32_16x16x64_i8 v[58:61], v[150:153], v[188:191], v[58:61]
	v_mfma_i32_16x16x64_i8 v[58:61], v[146:149], v[192:195], v[58:61]
	v_mfma_i32_16x16x64_i8 v[46:49], v[158:161], v[202:205], v[46:49]
	v_mfma_i32_16x16x64_i8 v[46:49], v[154:157], v[206:209], v[46:49]
	v_mfma_i32_16x16x64_i8 v[42:45], v[150:153], v[202:205], v[42:45]
	v_mfma_i32_16x16x64_i8 v[42:45], v[146:149], v[206:209], v[42:45]
	v_mfma_i32_16x16x64_i8 v[30:33], v[158:161], v[210:213], v[30:33]
	v_mfma_i32_16x16x64_i8 v[30:33], v[154:157], v[214:217], v[30:33]
	v_mfma_i32_16x16x64_i8 v[26:29], v[150:153], v[210:213], v[26:29]
	v_mfma_i32_16x16x64_i8 v[26:29], v[146:149], v[214:217], v[26:29]
	v_mfma_i32_16x16x64_i8 v[14:17], v[158:161], v[220:223], v[14:17]
	v_mfma_i32_16x16x64_i8 v[14:17], v[154:157], v[224:227], v[14:17]
	v_mfma_i32_16x16x64_i8 v[10:13], v[150:153], v[220:223], v[10:13]
	v_mfma_i32_16x16x64_i8 v[10:13], v[146:149], v[224:227], v[10:13]
	v_mfma_i32_16x16x64_i8 v[54:57], v[142:145], v[188:191], v[54:57]
	v_mfma_i32_16x16x64_i8 v[54:57], v[138:141], v[192:195], v[54:57]
	v_mfma_i32_16x16x64_i8 v[50:53], v[134:137], v[188:191], v[50:53]
	v_mfma_i32_16x16x64_i8 v[50:53], v[130:133], v[192:195], v[50:53]
	v_mfma_i32_16x16x64_i8 v[38:41], v[142:145], v[202:205], v[38:41]
	v_mfma_i32_16x16x64_i8 v[38:41], v[138:141], v[206:209], v[38:41]
	v_mfma_i32_16x16x64_i8 v[34:37], v[134:137], v[202:205], v[34:37]
	v_mfma_i32_16x16x64_i8 v[34:37], v[130:133], v[206:209], v[34:37]
	s_barrier
	s_setprio 2
	v_mfma_i32_16x16x64_i8 v[22:25], v[142:145], v[210:213], v[22:25]
	v_mfma_i32_16x16x64_i8 v[22:25], v[138:141], v[214:217], v[22:25]
	v_mfma_i32_16x16x64_i8 v[18:21], v[134:137], v[210:213], v[18:21]
	v_mfma_i32_16x16x64_i8 v[18:21], v[130:133], v[214:217], v[18:21]
	v_mfma_i32_16x16x64_i8 v[6:9], v[142:145], v[220:223], v[6:9]
	v_mfma_i32_16x16x64_i8 v[6:9], v[138:141], v[224:227], v[6:9]
	v_mfma_i32_16x16x64_i8 v[2:5], v[134:137], v[220:223], v[2:5]
	v_mfma_i32_16x16x64_i8 v[2:5], v[130:133], v[224:227], v[2:5]
	s_setprio 0
	v_add_u32_e32 v142, s56, v183
	v_add_u32_e32 v158, s57, v183
	ds_read_b128 v[130:133], v142
	ds_read_b128 v[134:137], v142 offset:1024
	ds_read_b128 v[138:141], v142 offset:2048
	ds_read_b128 v[142:145], v142 offset:3072
	ds_read_b128 v[146:149], v158
	ds_read_b128 v[150:153], v158 offset:1024
	ds_read_b128 v[154:157], v158 offset:2048
	ds_read_b128 v[158:161], v158 offset:3072
	s_add_u32 s34, s34, 0x80000
	s_addc_u32 s35, s35, 0
	s_mov_b32 m0, s36
	v_lshl_add_u64 v[232:233], s[34:35], 0, v[168:169]
	ds_read_b128 v[188:191], v187 offset:32768
	ds_read_b128 v[192:195], v187 offset:33792
	ds_read_b128 v[202:205], v187 offset:34816
	ds_read_b128 v[206:209], v187 offset:35840
	ds_read_b128 v[210:213], v187 offset:36864
	ds_read_b128 v[214:217], v187 offset:37888
	ds_read_b128 v[220:223], v187 offset:38912
	ds_read_b128 v[224:227], v187 offset:39936
	global_load_lds_dwordx4 v[232:233], off
	v_lshl_add_u64 v[232:233], s[34:35], 0, v[164:165]
	s_mov_b32 m0, s37
	s_nop 0
	global_load_lds_dwordx4 v[232:233], off
	s_waitcnt vmcnt(8)
	s_waitcnt lgkmcnt(0)
	s_barrier
	s_setprio 1
	s_waitcnt lgkmcnt(0)
	v_mfma_i32_16x16x64_i8 v[126:129], v[130:133], v[188:191], v[126:129]
	v_mfma_i32_16x16x64_i8 v[126:129], v[134:137], v[192:195], v[126:129]
	v_mfma_i32_16x16x64_i8 v[122:125], v[138:141], v[188:191], v[122:125]
	v_mfma_i32_16x16x64_i8 v[122:125], v[142:145], v[192:195], v[122:125]
	v_mfma_i32_16x16x64_i8 v[110:113], v[130:133], v[202:205], v[110:113]
	v_mfma_i32_16x16x64_i8 v[110:113], v[134:137], v[206:209], v[110:113]
	v_mfma_i32_16x16x64_i8 v[106:109], v[138:141], v[202:205], v[106:109]
	v_mfma_i32_16x16x64_i8 v[106:109], v[142:145], v[206:209], v[106:109]
	v_mfma_i32_16x16x64_i8 v[94:97], v[130:133], v[210:213], v[94:97]
	v_mfma_i32_16x16x64_i8 v[94:97], v[134:137], v[214:217], v[94:97]
	v_mfma_i32_16x16x64_i8 v[90:93], v[138:141], v[210:213], v[90:93]
	v_mfma_i32_16x16x64_i8 v[90:93], v[142:145], v[214:217], v[90:93]
	v_mfma_i32_16x16x64_i8 v[78:81], v[130:133], v[220:223], v[78:81]
	v_mfma_i32_16x16x64_i8 v[78:81], v[134:137], v[224:227], v[78:81]
	v_mfma_i32_16x16x64_i8 v[74:77], v[138:141], v[220:223], v[74:77]
	v_mfma_i32_16x16x64_i8 v[74:77], v[142:145], v[224:227], v[74:77]
	v_mfma_i32_16x16x64_i8 v[118:121], v[146:149], v[188:191], v[118:121]
	v_mfma_i32_16x16x64_i8 v[118:121], v[150:153], v[192:195], v[118:121]
	v_mfma_i32_16x16x64_i8 v[114:117], v[154:157], v[188:191], v[114:117]
	v_mfma_i32_16x16x64_i8 v[114:117], v[158:161], v[192:195], v[114:117]
	v_mfma_i32_16x16x64_i8 v[102:105], v[146:149], v[202:205], v[102:105]
	v_mfma_i32_16x16x64_i8 v[102:105], v[150:153], v[206:209], v[102:105]
	v_mfma_i32_16x16x64_i8 v[98:101], v[154:157], v[202:205], v[98:101]
	v_mfma_i32_16x16x64_i8 v[98:101], v[158:161], v[206:209], v[98:101]
	s_barrier
	s_setprio 2
	v_mfma_i32_16x16x64_i8 v[86:89], v[146:149], v[210:213], v[86:89]
	v_mfma_i32_16x16x64_i8 v[86:89], v[150:153], v[214:217], v[86:89]
	v_mfma_i32_16x16x64_i8 v[82:85], v[154:157], v[210:213], v[82:85]
	v_mfma_i32_16x16x64_i8 v[82:85], v[158:161], v[214:217], v[82:85]
	v_mfma_i32_16x16x64_i8 v[70:73], v[146:149], v[220:223], v[70:73]
	v_mfma_i32_16x16x64_i8 v[70:73], v[150:153], v[224:227], v[70:73]
	v_mfma_i32_16x16x64_i8 v[66:69], v[154:157], v[220:223], v[66:69]
	v_mfma_i32_16x16x64_i8 v[66:69], v[158:161], v[224:227], v[66:69]
	s_setprio 0
	s_add_i32 s34, s56, s9
	v_lshl_add_u64 v[174:175], v[174:175], 0, s[4:5]
	s_mov_b32 m0, s34
	ds_read_b128 v[188:191], v187 offset:49152
	ds_read_b128 v[192:195], v187 offset:50176
	ds_read_b128 v[202:205], v187 offset:51200
	ds_read_b128 v[206:209], v187 offset:52224
	ds_read_b128 v[210:213], v187 offset:53248
	ds_read_b128 v[214:217], v187 offset:54272
	ds_read_b128 v[220:223], v187 offset:55296
	ds_read_b128 v[224:227], v187 offset:56320
	global_load_lds_dwordx4 v[174:175], off
	s_add_i32 m0, s34, 0x2000
	s_add_u32 s30, s30, 0x80080
	v_lshl_add_u64 v[174:175], v[176:177], 0, s[4:5]
	s_addc_u32 s31, s31, 0
	s_add_i32 s34, s57, s9
	global_load_lds_dwordx4 v[174:175], off
	v_lshl_add_u64 v[174:175], s[30:31], 0, v[166:167]
	s_mov_b32 m0, s34
	s_nop 0
	global_load_lds_dwordx4 v[174:175], off
	v_lshl_add_u64 v[174:175], s[30:31], 0, v[162:163]
	s_add_i32 m0, s34, 0x2000
	s_nop 0
	global_load_lds_dwordx4 v[174:175], off
	v_lshl_add_u64 v[174:175], v[178:179], 0, s[4:5]
	s_mov_b32 m0, s39
	s_nop 0
	global_load_lds_dwordx4 v[174:175], off
	v_lshl_add_u64 v[174:175], v[180:181], 0, s[4:5]
	s_mov_b32 m0, s40
	s_nop 0
	global_load_lds_dwordx4 v[174:175], off
	s_waitcnt vmcnt(8)
	s_waitcnt lgkmcnt(0)
	s_barrier
	s_setprio 1
	s_waitcnt lgkmcnt(0)
	v_mfma_i32_16x16x64_i8 v[62:65], v[130:133], v[188:191], v[62:65]
	v_mfma_i32_16x16x64_i8 v[62:65], v[134:137], v[192:195], v[62:65]
	v_mfma_i32_16x16x64_i8 v[58:61], v[138:141], v[188:191], v[58:61]
	v_mfma_i32_16x16x64_i8 v[58:61], v[142:145], v[192:195], v[58:61]
	v_mfma_i32_16x16x64_i8 v[46:49], v[130:133], v[202:205], v[46:49]
	v_mfma_i32_16x16x64_i8 v[46:49], v[134:137], v[206:209], v[46:49]
	v_mfma_i32_16x16x64_i8 v[42:45], v[138:141], v[202:205], v[42:45]
	v_mfma_i32_16x16x64_i8 v[42:45], v[142:145], v[206:209], v[42:45]
	v_mfma_i32_16x16x64_i8 v[30:33], v[130:133], v[210:213], v[30:33]
	v_mfma_i32_16x16x64_i8 v[30:33], v[134:137], v[214:217], v[30:33]
	v_mfma_i32_16x16x64_i8 v[26:29], v[138:141], v[210:213], v[26:29]
	v_mfma_i32_16x16x64_i8 v[26:29], v[142:145], v[214:217], v[26:29]
	v_mfma_i32_16x16x64_i8 v[14:17], v[130:133], v[220:223], v[14:17]
	v_mfma_i32_16x16x64_i8 v[14:17], v[134:137], v[224:227], v[14:17]
	v_mfma_i32_16x16x64_i8 v[10:13], v[138:141], v[220:223], v[10:13]
	v_mfma_i32_16x16x64_i8 v[10:13], v[142:145], v[224:227], v[10:13]
	v_mfma_i32_16x16x64_i8 v[54:57], v[146:149], v[188:191], v[54:57]
	v_mfma_i32_16x16x64_i8 v[54:57], v[150:153], v[192:195], v[54:57]
	v_mfma_i32_16x16x64_i8 v[50:53], v[154:157], v[188:191], v[50:53]
	v_mfma_i32_16x16x64_i8 v[50:53], v[158:161], v[192:195], v[50:53]
	v_mfma_i32_16x16x64_i8 v[38:41], v[146:149], v[202:205], v[38:41]
	v_mfma_i32_16x16x64_i8 v[38:41], v[150:153], v[206:209], v[38:41]
	v_mfma_i32_16x16x64_i8 v[34:37], v[154:157], v[202:205], v[34:37]
	v_mfma_i32_16x16x64_i8 v[34:37], v[158:161], v[206:209], v[34:37]
	s_barrier
	s_setprio 2
	v_mfma_i32_16x16x64_i8 v[22:25], v[146:149], v[210:213], v[22:25]
	v_mfma_i32_16x16x64_i8 v[22:25], v[150:153], v[214:217], v[22:25]
	v_mfma_i32_16x16x64_i8 v[18:21], v[154:157], v[210:213], v[18:21]
	v_mfma_i32_16x16x64_i8 v[18:21], v[158:161], v[214:217], v[18:21]
	v_mfma_i32_16x16x64_i8 v[6:9], v[146:149], v[220:223], v[6:9]
	v_mfma_i32_16x16x64_i8 v[6:9], v[150:153], v[224:227], v[6:9]
	v_mfma_i32_16x16x64_i8 v[2:5], v[154:157], v[220:223], v[2:5]
	v_mfma_i32_16x16x64_i8 v[2:5], v[158:161], v[224:227], v[2:5]
	s_setprio 0
	s_add_i32 s45, s45, 2
	s_add_u32 s28, s28, 0x100
	s_addc_u32 s29, s29, 0
	s_add_u32 s43, s43, 0x100
	s_addc_u32 s44, s44, 0
	s_cmp_gt_u32 s45, 29
	s_cbranch_scc0 .LBB0_961
	s_nop 15
	s_nop 15
	s_and_b64 vcc, exec, s[6:7]
	s_cbranch_vccz .LBB0_964
	s_barrier

.LBB0_1058:
	ds_read_b128 v[128:131], v194
	ds_read_b128 v[132:135], v194 offset:1024
	ds_read_b128 v[136:139], v194 offset:2048
	ds_read_b128 v[140:143], v194 offset:3072
	ds_read_b128 v[144:147], v195
	ds_read_b128 v[148:151], v195 offset:1024
	ds_read_b128 v[152:155], v195 offset:2048
	ds_read_b128 v[156:159], v195 offset:3072
	s_add_u32 s2, s0, 0x100
	s_addc_u32 s3, s1, 0
	s_cmpk_eq_i32 s39, 0xa8
	s_cselect_b32 s37, s31, s3
	s_cselect_b32 s36, s30, s2
	s_cselect_b32 s5, s7, s38
	s_cselect_b32 s4, s6, s29
	v_lshl_add_u64 v[188:189], s[0:1], 0, v[168:169]
	s_add_i32 m0, s27, 0xc000
	ds_read_b128 v[172:175], v196
	ds_read_b128 v[176:179], v196 offset:1024
	ds_read_b128 v[180:183], v196 offset:2048
	ds_read_b128 v[184:187], v196 offset:3072
	ds_read_b128 v[200:203], v196 offset:4096
	ds_read_b128 v[204:207], v196 offset:5120
	ds_read_b128 v[208:211], v196 offset:6144
	ds_read_b128 v[212:215], v196 offset:7168
	global_load_lds_dwordx4 v[188:189], off
	v_lshl_add_u64 v[188:189], s[0:1], 0, v[170:171]
	s_add_i32 m0, s27, 0xe000
	s_nop 0
	global_load_lds_dwordx4 v[188:189], off
	s_waitcnt vmcnt(8)
	s_waitcnt lgkmcnt(0)
	s_barrier
	s_setprio 1
	s_waitcnt lgkmcnt(0)
	v_mfma_f32_16x16x32_bf16 v[12:15], v[128:131], v[172:175], v[12:15]
	v_mfma_f32_16x16x32_bf16 v[8:11], v[136:139], v[172:175], v[8:11]
	v_mfma_f32_16x16x32_bf16 v[36:39], v[128:131], v[180:183], v[36:39]
	v_mfma_f32_16x16x32_bf16 v[32:35], v[136:139], v[180:183], v[32:35]
	v_mfma_f32_16x16x32_bf16 v[44:47], v[128:131], v[200:203], v[44:47]
	v_mfma_f32_16x16x32_bf16 v[40:43], v[136:139], v[200:203], v[40:43]
	v_mfma_f32_16x16x32_bf16 v[64:67], v[128:131], v[208:211], v[64:67]
	v_mfma_f32_16x16x32_bf16 v[56:59], v[136:139], v[208:211], v[56:59]
	v_mfma_f32_16x16x32_bf16 v[12:15], v[132:135], v[176:179], v[12:15]
	v_mfma_f32_16x16x32_bf16 v[8:11], v[140:143], v[176:179], v[8:11]
	v_mfma_f32_16x16x32_bf16 v[36:39], v[132:135], v[184:187], v[36:39]
	v_mfma_f32_16x16x32_bf16 v[32:35], v[140:143], v[184:187], v[32:35]
	v_mfma_f32_16x16x32_bf16 v[44:47], v[132:135], v[204:207], v[44:47]
	v_mfma_f32_16x16x32_bf16 v[40:43], v[140:143], v[204:207], v[40:43]
	v_mfma_f32_16x16x32_bf16 v[64:67], v[132:135], v[212:215], v[64:67]
	v_mfma_f32_16x16x32_bf16 v[56:59], v[140:143], v[212:215], v[56:59]
	v_mfma_f32_16x16x32_bf16 v[4:7], v[144:147], v[172:175], v[4:7]
	v_mfma_f32_16x16x32_bf16 v[0:3], v[152:155], v[172:175], v[0:3]
	v_mfma_f32_16x16x32_bf16 v[24:27], v[144:147], v[180:183], v[24:27]
	v_mfma_f32_16x16x32_bf16 v[16:19], v[152:155], v[180:183], v[16:19]
	v_mfma_f32_16x16x32_bf16 v[28:31], v[144:147], v[200:203], v[28:31]
	v_mfma_f32_16x16x32_bf16 v[20:23], v[152:155], v[200:203], v[20:23]
	v_mfma_f32_16x16x32_bf16 v[52:55], v[144:147], v[208:211], v[52:55]
	v_mfma_f32_16x16x32_bf16 v[48:51], v[152:155], v[208:211], v[48:51]
	s_barrier
	s_setprio 2
	v_mfma_f32_16x16x32_bf16 v[4:7], v[148:151], v[176:179], v[4:7]
	v_mfma_f32_16x16x32_bf16 v[0:3], v[156:159], v[176:179], v[0:3]
	v_mfma_f32_16x16x32_bf16 v[24:27], v[148:151], v[184:187], v[24:27]
	v_mfma_f32_16x16x32_bf16 v[16:19], v[156:159], v[184:187], v[16:19]
	v_mfma_f32_16x16x32_bf16 v[28:31], v[148:151], v[204:207], v[28:31]
	v_mfma_f32_16x16x32_bf16 v[20:23], v[156:159], v[204:207], v[20:23]
	v_mfma_f32_16x16x32_bf16 v[52:55], v[148:151], v[212:215], v[52:55]
	v_mfma_f32_16x16x32_bf16 v[48:51], v[156:159], v[212:215], v[48:51]
	s_setprio 0
	s_add_i32 s0, s17, s25
	v_lshl_add_u64 v[188:189], s[4:5], 0, v[162:163]
	s_mov_b32 m0, s0
	ds_read_b128 v[172:175], v196 offset:16384
	ds_read_b128 v[176:179], v196 offset:17408
	ds_read_b128 v[180:183], v196 offset:18432
	ds_read_b128 v[184:187], v196 offset:19456
	ds_read_b128 v[200:203], v196 offset:20480
	ds_read_b128 v[204:207], v196 offset:21504
	ds_read_b128 v[208:211], v196 offset:22528
	ds_read_b128 v[212:215], v196 offset:23552
	global_load_lds_dwordx4 v[188:189], off
	s_add_i32 m0, s0, 0x2000
	s_add_u32 s0, s4, 0x2b0000
	v_lshl_add_u64 v[216:217], s[4:5], 0, v[166:167]
	s_addc_u32 s1, s5, 0
	s_add_i32 s40, s55, s25
	global_load_lds_dwordx4 v[216:217], off
	v_lshl_add_u64 v[220:221], s[0:1], 0, v[162:163]
	s_mov_b32 m0, s40
	v_lshl_add_u64 v[222:223], s[36:37], 0, v[164:165]
	global_load_lds_dwordx4 v[220:221], off
	v_lshl_add_u64 v[220:221], s[0:1], 0, v[166:167]
	s_add_i32 m0, s40, 0x2000
	s_nop 0
	global_load_lds_dwordx4 v[220:221], off
	v_lshl_add_u64 v[220:221], s[36:37], 0, v[160:161]
	s_mov_b32 m0, s27
	s_nop 0
	global_load_lds_dwordx4 v[220:221], off
	s_mov_b32 m0, s33
	s_nop 0
	global_load_lds_dwordx4 v[222:223], off
	s_waitcnt vmcnt(8)
	s_waitcnt lgkmcnt(0)
	s_barrier
	s_setprio 1
	s_waitcnt lgkmcnt(0)
	v_mfma_f32_16x16x32_bf16 v[76:79], v[128:131], v[172:175], v[76:79]
	v_mfma_f32_16x16x32_bf16 v[72:75], v[136:139], v[172:175], v[72:75]
	v_mfma_f32_16x16x32_bf16 v[92:95], v[128:131], v[180:183], v[92:95]
	v_mfma_f32_16x16x32_bf16 v[88:91], v[136:139], v[180:183], v[88:91]
	v_mfma_f32_16x16x32_bf16 v[108:111], v[128:131], v[200:203], v[108:111]
	v_mfma_f32_16x16x32_bf16 v[104:107], v[136:139], v[200:203], v[104:107]
	v_mfma_f32_16x16x32_bf16 v[124:127], v[128:131], v[208:211], v[124:127]
	v_mfma_f32_16x16x32_bf16 v[120:123], v[136:139], v[208:211], v[120:123]
	v_mfma_f32_16x16x32_bf16 v[76:79], v[132:135], v[176:179], v[76:79]
	v_mfma_f32_16x16x32_bf16 v[72:75], v[140:143], v[176:179], v[72:75]
	v_mfma_f32_16x16x32_bf16 v[92:95], v[132:135], v[184:187], v[92:95]
	v_mfma_f32_16x16x32_bf16 v[88:91], v[140:143], v[184:187], v[88:91]
	v_mfma_f32_16x16x32_bf16 v[108:111], v[132:135], v[204:207], v[108:111]
	v_mfma_f32_16x16x32_bf16 v[104:107], v[140:143], v[204:207], v[104:107]
	v_mfma_f32_16x16x32_bf16 v[124:127], v[132:135], v[212:215], v[124:127]
	v_mfma_f32_16x16x32_bf16 v[120:123], v[140:143], v[212:215], v[120:123]
	v_mfma_f32_16x16x32_bf16 v[68:71], v[144:147], v[172:175], v[68:71]
	v_mfma_f32_16x16x32_bf16 v[60:63], v[152:155], v[172:175], v[60:63]
	v_mfma_f32_16x16x32_bf16 v[84:87], v[144:147], v[180:183], v[84:87]
	v_mfma_f32_16x16x32_bf16 v[80:83], v[152:155], v[180:183], v[80:83]
	v_mfma_f32_16x16x32_bf16 v[100:103], v[144:147], v[200:203], v[100:103]
	v_mfma_f32_16x16x32_bf16 v[96:99], v[152:155], v[200:203], v[96:99]
	v_mfma_f32_16x16x32_bf16 v[116:119], v[144:147], v[208:211], v[116:119]
	v_mfma_f32_16x16x32_bf16 v[112:115], v[152:155], v[208:211], v[112:115]
	s_barrier
	s_setprio 2
	v_mfma_f32_16x16x32_bf16 v[68:71], v[148:151], v[176:179], v[68:71]
	v_mfma_f32_16x16x32_bf16 v[60:63], v[156:159], v[176:179], v[60:63]
	v_mfma_f32_16x16x32_bf16 v[84:87], v[148:151], v[184:187], v[84:87]
	v_mfma_f32_16x16x32_bf16 v[80:83], v[156:159], v[184:187], v[80:83]
	v_mfma_f32_16x16x32_bf16 v[100:103], v[148:151], v[204:207], v[100:103]
	v_mfma_f32_16x16x32_bf16 v[96:99], v[156:159], v[204:207], v[96:99]
	v_mfma_f32_16x16x32_bf16 v[116:119], v[148:151], v[212:215], v[116:119]
	v_mfma_f32_16x16x32_bf16 v[112:115], v[156:159], v[212:215], v[112:115]
	s_setprio 0
	v_add_u32_e32 v140, s56, v193
	v_add_u32_e32 v156, s57, v193
	ds_read_b128 v[128:131], v140
	ds_read_b128 v[132:135], v140 offset:1024
	ds_read_b128 v[136:139], v140 offset:2048
	ds_read_b128 v[140:143], v140 offset:3072
	ds_read_b128 v[144:147], v156
	ds_read_b128 v[148:151], v156 offset:1024
	ds_read_b128 v[152:155], v156 offset:2048
	ds_read_b128 v[156:159], v156 offset:3072
	s_add_u32 s0, s36, 0x2b0000
	s_addc_u32 s1, s37, 0
	s_mov_b32 m0, s46
	v_lshl_add_u64 v[224:225], s[0:1], 0, v[160:161]
	ds_read_b128 v[172:175], v196 offset:32768
	ds_read_b128 v[176:179], v196 offset:33792
	ds_read_b128 v[180:183], v196 offset:34816
	ds_read_b128 v[184:187], v196 offset:35840
	ds_read_b128 v[200:203], v196 offset:36864
	ds_read_b128 v[204:207], v196 offset:37888
	ds_read_b128 v[208:211], v196 offset:38912
	ds_read_b128 v[212:215], v196 offset:39936
	global_load_lds_dwordx4 v[224:225], off
	v_lshl_add_u64 v[224:225], s[0:1], 0, v[164:165]
	s_mov_b32 m0, s47
	s_nop 0
	global_load_lds_dwordx4 v[224:225], off
	s_waitcnt vmcnt(8)
	s_waitcnt lgkmcnt(0)
	s_barrier
	s_setprio 1
	s_waitcnt lgkmcnt(0)
	v_mfma_f32_16x16x32_bf16 v[12:15], v[128:131], v[172:175], v[12:15]
	v_mfma_f32_16x16x32_bf16 v[8:11], v[136:139], v[172:175], v[8:11]
	v_mfma_f32_16x16x32_bf16 v[36:39], v[128:131], v[180:183], v[36:39]
	v_mfma_f32_16x16x32_bf16 v[32:35], v[136:139], v[180:183], v[32:35]
	v_mfma_f32_16x16x32_bf16 v[44:47], v[128:131], v[200:203], v[44:47]
	v_mfma_f32_16x16x32_bf16 v[40:43], v[136:139], v[200:203], v[40:43]
	v_mfma_f32_16x16x32_bf16 v[64:67], v[128:131], v[208:211], v[64:67]
	v_mfma_f32_16x16x32_bf16 v[56:59], v[136:139], v[208:211], v[56:59]
	v_mfma_f32_16x16x32_bf16 v[12:15], v[132:135], v[176:179], v[12:15]
	v_mfma_f32_16x16x32_bf16 v[8:11], v[140:143], v[176:179], v[8:11]
	v_mfma_f32_16x16x32_bf16 v[36:39], v[132:135], v[184:187], v[36:39]
	v_mfma_f32_16x16x32_bf16 v[32:35], v[140:143], v[184:187], v[32:35]
	v_mfma_f32_16x16x32_bf16 v[44:47], v[132:135], v[204:207], v[44:47]
	v_mfma_f32_16x16x32_bf16 v[40:43], v[140:143], v[204:207], v[40:43]
	v_mfma_f32_16x16x32_bf16 v[64:67], v[132:135], v[212:215], v[64:67]
	v_mfma_f32_16x16x32_bf16 v[56:59], v[140:143], v[212:215], v[56:59]
	v_mfma_f32_16x16x32_bf16 v[4:7], v[144:147], v[172:175], v[4:7]
	v_mfma_f32_16x16x32_bf16 v[0:3], v[152:155], v[172:175], v[0:3]
	v_mfma_f32_16x16x32_bf16 v[24:27], v[144:147], v[180:183], v[24:27]
	v_mfma_f32_16x16x32_bf16 v[16:19], v[152:155], v[180:183], v[16:19]
	v_mfma_f32_16x16x32_bf16 v[28:31], v[144:147], v[200:203], v[28:31]
	v_mfma_f32_16x16x32_bf16 v[20:23], v[152:155], v[200:203], v[20:23]
	v_mfma_f32_16x16x32_bf16 v[52:55], v[144:147], v[208:211], v[52:55]
	v_mfma_f32_16x16x32_bf16 v[48:51], v[152:155], v[208:211], v[48:51]
	s_barrier
	s_setprio 2
	v_mfma_f32_16x16x32_bf16 v[4:7], v[148:151], v[176:179], v[4:7]
	v_mfma_f32_16x16x32_bf16 v[0:3], v[156:159], v[176:179], v[0:3]
	v_mfma_f32_16x16x32_bf16 v[24:27], v[148:151], v[184:187], v[24:27]
	v_mfma_f32_16x16x32_bf16 v[16:19], v[156:159], v[184:187], v[16:19]
	v_mfma_f32_16x16x32_bf16 v[28:31], v[148:151], v[204:207], v[28:31]
	v_mfma_f32_16x16x32_bf16 v[20:23], v[156:159], v[204:207], v[20:23]
	v_mfma_f32_16x16x32_bf16 v[52:55], v[148:151], v[212:215], v[52:55]
	v_mfma_f32_16x16x32_bf16 v[48:51], v[156:159], v[212:215], v[48:51]
	s_setprio 0
	s_add_i32 s0, s56, s25
	v_lshl_add_u64 v[188:189], v[188:189], 0, s[18:19]
	s_mov_b32 m0, s0
	ds_read_b128 v[172:175], v196 offset:49152
	ds_read_b128 v[176:179], v196 offset:50176
	ds_read_b128 v[180:183], v196 offset:51200
	ds_read_b128 v[184:187], v196 offset:52224
	ds_read_b128 v[200:203], v196 offset:53248
	ds_read_b128 v[204:207], v196 offset:54272
	ds_read_b128 v[208:211], v196 offset:55296
	ds_read_b128 v[212:215], v196 offset:56320
	global_load_lds_dwordx4 v[188:189], off
	s_add_i32 m0, s0, 0x2000
	s_add_u32 s0, s4, 0x2b0080
	v_lshl_add_u64 v[188:189], v[216:217], 0, s[18:19]
	s_addc_u32 s1, s5, 0
	s_add_i32 s4, s57, s25
	global_load_lds_dwordx4 v[188:189], off
	v_lshl_add_u64 v[188:189], s[0:1], 0, v[162:163]
	s_mov_b32 m0, s4
	s_nop 0
	global_load_lds_dwordx4 v[188:189], off
	v_lshl_add_u64 v[188:189], s[0:1], 0, v[166:167]
	s_add_i32 m0, s4, 0x2000
	s_nop 0
	global_load_lds_dwordx4 v[188:189], off
	v_lshl_add_u64 v[188:189], v[220:221], 0, s[18:19]
	s_mov_b32 m0, s52
	s_nop 0
	global_load_lds_dwordx4 v[188:189], off
	v_lshl_add_u64 v[188:189], v[222:223], 0, s[18:19]
	s_mov_b32 m0, s53
	s_nop 0
	global_load_lds_dwordx4 v[188:189], off
	s_waitcnt vmcnt(8)
	s_waitcnt lgkmcnt(0)
	s_barrier
	s_setprio 1
	s_waitcnt lgkmcnt(0)
	v_mfma_f32_16x16x32_bf16 v[76:79], v[128:131], v[172:175], v[76:79]
	v_mfma_f32_16x16x32_bf16 v[72:75], v[136:139], v[172:175], v[72:75]
	v_mfma_f32_16x16x32_bf16 v[92:95], v[128:131], v[180:183], v[92:95]
	v_mfma_f32_16x16x32_bf16 v[88:91], v[136:139], v[180:183], v[88:91]
	v_mfma_f32_16x16x32_bf16 v[108:111], v[128:131], v[200:203], v[108:111]
	v_mfma_f32_16x16x32_bf16 v[104:107], v[136:139], v[200:203], v[104:107]
	v_mfma_f32_16x16x32_bf16 v[124:127], v[128:131], v[208:211], v[124:127]
	v_mfma_f32_16x16x32_bf16 v[120:123], v[136:139], v[208:211], v[120:123]
	v_mfma_f32_16x16x32_bf16 v[76:79], v[132:135], v[176:179], v[76:79]
	v_mfma_f32_16x16x32_bf16 v[72:75], v[140:143], v[176:179], v[72:75]
	v_mfma_f32_16x16x32_bf16 v[92:95], v[132:135], v[184:187], v[92:95]
	v_mfma_f32_16x16x32_bf16 v[88:91], v[140:143], v[184:187], v[88:91]
	v_mfma_f32_16x16x32_bf16 v[108:111], v[132:135], v[204:207], v[108:111]
	v_mfma_f32_16x16x32_bf16 v[104:107], v[140:143], v[204:207], v[104:107]
	v_mfma_f32_16x16x32_bf16 v[124:127], v[132:135], v[212:215], v[124:127]
	v_mfma_f32_16x16x32_bf16 v[120:123], v[140:143], v[212:215], v[120:123]
	v_mfma_f32_16x16x32_bf16 v[68:71], v[144:147], v[172:175], v[68:71]
	v_mfma_f32_16x16x32_bf16 v[60:63], v[152:155], v[172:175], v[60:63]
	v_mfma_f32_16x16x32_bf16 v[84:87], v[144:147], v[180:183], v[84:87]
	v_mfma_f32_16x16x32_bf16 v[80:83], v[152:155], v[180:183], v[80:83]
	v_mfma_f32_16x16x32_bf16 v[100:103], v[144:147], v[200:203], v[100:103]
	v_mfma_f32_16x16x32_bf16 v[96:99], v[152:155], v[200:203], v[96:99]
	v_mfma_f32_16x16x32_bf16 v[116:119], v[144:147], v[208:211], v[116:119]
	v_mfma_f32_16x16x32_bf16 v[112:115], v[152:155], v[208:211], v[112:115]
	s_barrier
	s_setprio 2
	v_mfma_f32_16x16x32_bf16 v[68:71], v[148:151], v[176:179], v[68:71]
	v_mfma_f32_16x16x32_bf16 v[60:63], v[156:159], v[176:179], v[60:63]
	v_mfma_f32_16x16x32_bf16 v[84:87], v[148:151], v[184:187], v[84:87]
	v_mfma_f32_16x16x32_bf16 v[80:83], v[156:159], v[184:187], v[80:83]
	v_mfma_f32_16x16x32_bf16 v[100:103], v[148:151], v[204:207], v[100:103]
	v_mfma_f32_16x16x32_bf16 v[96:99], v[156:159], v[204:207], v[96:99]
	v_mfma_f32_16x16x32_bf16 v[116:119], v[148:151], v[212:215], v[116:119]
	v_mfma_f32_16x16x32_bf16 v[112:115], v[156:159], v[212:215], v[112:115]
	s_setprio 0
	s_add_i32 s39, s39, 2
	s_add_u32 s29, s29, 0x100
	s_addc_u32 s38, s38, 0
	s_cmpk_gt_u32 s39, 0xa9
	s_mov_b64 s[0:1], s[2:3]
	s_cbranch_scc0 .LBB0_1058
	s_and_b64 vcc, exec, s[20:21]
	s_cbranch_vccz .LBB0_1061
	s_barrier
